# attn prefetch waits counted; scan: decay loads hoisted + store-bound waits removed; GLA-prep phase rewritten (hoisted q/k loads, gate values kept in regs)
# speedup vs baseline: 1.0051x; 1.0051x over previous
; __device__ __forceinline__ int TID() { int t = threadIdx.x; asm volatile("" : "+v"(t)); return t; }
; DI void phase_gla_prep(const Params& p, int g, char* smem, int bid, int nb) {
;   float* lrs = (float*)smem;
;   float* tot = lrs + 1024;
;   const bf16_t* proj = (const bf16_t*)(p.ws + OFF_PROJ); const float* lrb = (const float*)(p.ws + OFF_LR);
;   bf16_t* gq = (bf16_t*)(p.ws + OFF_GQ); bf16_t* gk = (bf16_t*)(p.ws + OFF_GK); bf16_t* gkt = (bf16_t*)(p.ws + OFF_GKT); float* ge = (float*)(p.ws + OFF_GE);
;   const int tid = TID(), d = tid & 127, half = tid >> 7;
;   for (int item = bid; item < 2048; item += nb) {
;     const int c = item & 255, head = (item >> 8) & 3, dir = item >> 10, dd = head * 128 + d;
;     __syncthreads();
; #pragma unroll
;     for (int i = 0; i < 4; ++i) { const int idx = tid + 256 * i; lrs[idx] = lrb[(size_t)(c * 64 + (idx >> 4)) * 32 + dir * 16 + (idx & 15)]; }
.LBB0_241:
	s_andn2_b64 vcc, exec, s[0:1]
	s_cbranch_vccnz .LBB0_733
	s_cmp_gt_i32 s86, 2
	s_mov_b64 s[0:1], -1
	s_cbranch_scc0 .LBB0_342
	v_readlane_b32 s0, v233, 24
	v_readlane_b32 s1, v233, 25
	v_mov_b32_e32 v8, v195
	s_andn2_b64 vcc, exec, s[0:1]
	s_cbranch_vccnz .LBB0_341
	s_waitcnt vmcnt(0) lgkmcnt(0)
	v_and_b32_e32 v0, 0x7f, v195
	v_lshrrev_b32_e32 v12, 7, v195
	v_lshl_add_u32 v1, v195, 2, 32
	v_lshl_add_u32 v2, v12, 11, 32
	v_lshl_add_u32 v3, v0, 2, 32
	v_lshlrev_b32_e32 v4, 1, v0
	v_mul_u32_u24_e32 v13, 0x50000, v12
	v_add_u32_e32 v4, 0x800, v4
	v_add_u32_e32 v4, v4, v13
	v_lshlrev_b32_e32 v5, 1, v0
	v_lshl_add_u32 v5, v12, 13, v5
	v_add_u32_e32 v6, 0x1000, v5
	v_lshrrev_b32_e32 v7, 4, v195
	v_and_b32_e32 v13, 15, v195
	v_lshlrev_b32_e32 v13, 2, v13
	v_lshl_add_u32 v7, v7, 7, v13
	v_add_u32_e32 v8, 0x1000, v7
	v_lshlrev_b32_e32 v9, 2, v0
	v_lshlrev_b32_e32 v10, 7, v0
	v_lshl_add_u32 v10, v12, 6, v10
	v_readfirstlane_b32 s8, v12
	v_readlane_b32 s12, v235, 0
	s_branch .Lgp_loop

; DI void attn_item(const Params& p, int g, int seq, int hd, int qt, int m, char* smem, int split_j, int sub) {
;     ...
;   const bf16_t* vsrc = vaT + (size_t)(hd * 512 + (sb >> 5)) * 4096 + tid * 8;
;   const int npairs = (split_j < 0) ? (S >> 6) : (S >> 6) / SPLIT_SP;
;   const int tbase = (split_j < 0) ? 0 : split_j * npairs * 2;
;   const int qw0 = q0 + wave * 32;
;   bf16x8 qf[4];
; #pragma unroll
;   for (int s = 0; s < 4; ++s) qf[s] = *(const bf16x8*)(qrow + m * 64 + s * 16);
;   f32x16 O[4];
; #pragma unroll
;   for (int dt = 0; dt < 4; ++dt)
; #pragma unroll
;     for (int r = 0; r < 16; ++r) O[dt][r] = 0.f;
;   f32x2 ls2 = {0.f, 0.f};
;   int region = 0;
;   const bf16_t* ksrc = (const bf16_t*)(p.ws + OFF_KBLK) + (size_t)((hd * 2 + m) * 512 + (sb >> 5)) * 2048 + tid * 8;
;   u32x4 rkA, rvA0, rvA1, rkB, rvB0, rvB1;
;   auto load_tile = [&](int t, u32x4& k, u32x4& v0, u32x4& v1) __attribute__((always_inline)) {
;     k = *(const u32x4*)(ksrc + (size_t)(tbase + t) * 2048);
;     v0 = *(const u32x4*)(vsrc + (size_t)(tbase + t) * 4096); v1 = *(const u32x4*)(vsrc + (size_t)(tbase + t) * 4096 + 2048);
;   };
;     ...
;   load_tile(0, rkA, rvA0, rvA1);
;   load_tile(1, rkB, rvB0, rvB1);
;   __syncthreads();
;   store_tile(0, rkA, rvA0, rvA1);
;   store_tile(1, rkB, rvB0, rvB1);
;   __syncthreads();
.LBB0_264:
	s_or_b64 exec, exec, s[6:7]
	v_readlane_b32 s0, v231, 30
	s_sub_i32 s1, s12, s0
	s_lshr_b32 s0, s1, 2
	v_readlane_b32 s6, v231, 29
	s_add_i32 s0, s0, s6
	s_lshr_b32 s0, s0, 1
	v_readlane_b32 s6, v231, 32
	v_readlane_b32 s7, v231, 33
	s_lshr_b32 s6, s0, s6
	s_and_b32 s0, s0, s7
	v_readlane_b32 s7, v231, 37
	s_lshl_b32 s9, s6, s7
	v_readlane_b32 s6, v233, 14
	s_lshl_b32 s14, s0, 7
	v_readlane_b32 s7, v233, 15
	v_and_b32_e32 v168, 31, v0
	s_nop 3
	global_load_dword v1, v193, s[6:7] offset:480
	global_load_dword v10, v193, s[6:7] offset:992
	s_add_i32 s6, s14, s9
	s_ashr_i32 s0, s13, 1
	v_or_b32_e32 v2, s6, v168
	v_readlane_b32 s6, v233, 16
	s_andn2_b32 s0, s0, 31
	v_readlane_b32 s7, v233, 17
	v_add_u32_e32 v4, s0, v2
	s_bfe_u32 s8, s1, 0x10002
	v_mov_b64_e32 v[2:3], s[6:7]
	v_mad_i64_i32 v[2:3], s[6:7], v4, s2, v[2:3]
	s_lshl_b32 s7, s12, 1
	s_lshl_b32 s6, s9, 8
	v_readlane_b32 s11, v233, 13
	s_and_b32 s7, s7, 6
	v_readlane_b32 s10, v231, 38
	v_lshlrev_b32_e32 v4, 3, v0
	s_add_i32 s6, s6, s11
	s_lshl_b32 s10, s7, s10
	s_lshl_b32 s50, s8, 7
	v_ashrrev_i32_e32 v5, 31, v4
	s_add_u32 s6, s60, s6
	s_addc_u32 s7, s61, 0
	v_lshlrev_b64 v[6:7], 1, v[4:5]
	v_lshl_add_u64 v[176:177], s[6:7], 0, v[6:7]
	s_lshl_b32 s6, s8, 21
	s_lshl_b32 s7, s9, 7
	s_or_b32 s6, s6, s11
	v_bfe_u32 v188, v0, 5, 1
	s_add_i32 s6, s6, s7
	v_readlane_b32 s8, v233, 18
	v_lshlrev_b32_e32 v192, 4, v188
	v_readlane_b32 s9, v233, 19
	s_add_u32 s6, s8, s6
	v_lshl_add_u64 v[2:3], v[2:3], 0, v[192:193]
	s_addc_u32 s7, s9, 0
	v_lshl_add_u64 v[2:3], v[2:3], 0, s[50:51]
	v_lshl_add_u64 v[178:179], s[6:7], 0, v[6:7]
	s_lshl_b32 s50, s10, 12
	v_lshl_add_u64 v[6:7], v[178:179], 0, s[50:51]
	s_lshl_b32 s50, s10, 13
	v_lshl_add_u64 v[8:9], v[176:177], 0, s[50:51]
	global_load_dwordx4 v[96:99], v[6:7], off
	global_load_dwordx4 v[100:103], v[8:9], off
	v_add_co_u32_e32 v6, vcc, s81, v8
	s_or_b32 s6, s10, 1
	s_nop 0
	v_addc_co_u32_e32 v7, vcc, 0, v9, vcc
	s_lshl_b32 s50, s6, 12
	v_lshl_add_u64 v[8:9], v[178:179], 0, s[50:51]
	global_load_dwordx4 v[120:123], v[6:7], off
	global_load_dwordx4 v[124:127], v[8:9], off
	s_lshl_b32 s50, s6, 13
	v_lshl_add_u64 v[6:7], v[176:177], 0, s[50:51]
	v_add_co_u32_e32 v8, vcc, s81, v6
	v_and_b32_e32 v4, 24, v4
	s_nop 0
	v_addc_co_u32_e32 v9, vcc, 0, v7, vcc
	global_load_dwordx4 v[128:131], v[6:7], off
	global_load_dwordx4 v[132:135], v[8:9], off
	global_load_dwordx4 v[104:107], v[2:3], off
	global_load_dwordx4 v[108:111], v[2:3], off offset:32
	global_load_dwordx4 v[112:115], v[2:3], off offset:64
	global_load_dwordx4 v[116:119], v[2:3], off offset:96
	v_lshrrev_b32_e32 v2, 2, v0
	v_lshrrev_b32_e32 v3, 3, v0
	v_lshlrev_b32_e32 v0, 4, v0
	v_mul_lo_u32 v3, v3, s22
	v_and_b32_e32 v0, 0x70, v0
	v_mul_lo_u32 v2, v2, 40
	v_mul_u32_u24_e32 v5, 40, v168
	v_add3_u32 v189, 32, v3, v0
	v_lshlrev_b32_e32 v190, 1, v2
	v_lshlrev_b32_e32 v191, 1, v4
	v_add_u32_e32 v0, 32, v192
	s_add_i32 s14, s14, s0
	v_add3_u32 v2, 32, v190, v191
	v_mad_u32_u24 v196, v168, s22, v0
	v_lshl_add_u32 v197, v5, 1, v0
	v_or_b32_e32 v0, s14, v168
	v_mov_b32_e32 v14, v193
	v_mov_b32_e32 v15, v193
	s_waitcnt vmcnt(11) lgkmcnt(0)
	v_mul_f32_e32 v1, 0x3fb8aa3b, v1
	s_waitcnt vmcnt(10)
	v_mul_f32_e32 v169, 0x3fb8aa3b, v10
	v_exp_f32_e32 v170, v1
	v_exp_f32_e64 v180, -v169
	v_lshlrev_b32_e32 v1, 2, v188
	s_barrier
	v_sub_u32_e32 v198, v1, v0
	v_mov_b32_e32 v192, v193
	v_mov_b32_e32 v0, v193
	v_mov_b32_e32 v1, v193
	v_mov_b32_e32 v3, v193
	v_mov_b32_e32 v4, v193
	s_waitcnt vmcnt(9)
	ds_write_b128 v189, v[96:99]
	s_waitcnt vmcnt(8)
	ds_write_b128 v2, v[100:103] offset:18432
	s_waitcnt vmcnt(7)
	ds_write_b128 v2, v[120:123] offset:23552
	s_waitcnt vmcnt(6)
	ds_write_b128 v189, v[124:127] offset:4608
	s_waitcnt vmcnt(5)
	ds_write_b128 v2, v[128:131] offset:28672
	s_waitcnt vmcnt(4)
	ds_write_b128 v2, v[132:135] offset:33792
	v_mov_b32_e32 v2, v193
	v_mov_b32_e32 v5, v193
	v_mov_b32_e32 v6, v193
	v_mov_b32_e32 v7, v193
	v_mov_b32_e32 v8, v193
	v_mov_b32_e32 v9, v193
	v_mov_b32_e32 v10, v193
	v_mov_b32_e32 v11, v193
	v_mov_b32_e32 v12, v193
	v_mov_b32_e32 v13, v193
	v_mov_b64_e32 v[62:63], v[14:15]
	v_mov_b64_e32 v[46:47], v[14:15]
	v_mov_b64_e32 v[30:31], v[14:15]
	s_mov_b32 s11, 0
	v_mov_b32_e32 v172, v170
	v_mov_b32_e32 v173, v170
	v_mov_b32_e32 v182, v180
	v_mov_b32_e32 v183, v180
	v_mov_b32_e32 v174, v170
	v_mov_b32_e32 v175, v170
	v_mov_b32_e32 v184, v180
	v_mov_b32_e32 v185, v180
	s_lshl_b32 s13, s10, 5
	s_sub_i32 s14, 0, s14
	v_mov_b64_e32 v[60:61], v[12:13]
	v_mov_b64_e32 v[58:59], v[10:11]
	v_mov_b64_e32 v[56:57], v[8:9]
	v_mov_b64_e32 v[54:55], v[6:7]
	v_mov_b64_e32 v[52:53], v[4:5]
	v_mov_b64_e32 v[50:51], v[2:3]
	v_mov_b64_e32 v[48:49], v[0:1]
	v_mov_b64_e32 v[44:45], v[12:13]
	v_mov_b64_e32 v[42:43], v[10:11]
	v_mov_b64_e32 v[40:41], v[8:9]
	v_mov_b64_e32 v[38:39], v[6:7]
	v_mov_b64_e32 v[36:37], v[4:5]
	v_mov_b64_e32 v[34:35], v[2:3]
	v_mov_b64_e32 v[32:33], v[0:1]
	v_mov_b64_e32 v[28:29], v[12:13]
	v_mov_b64_e32 v[26:27], v[10:11]
	v_mov_b64_e32 v[24:25], v[8:9]
	v_mov_b64_e32 v[22:23], v[6:7]
	v_mov_b64_e32 v[20:21], v[4:5]
	v_mov_b64_e32 v[18:19], v[2:3]
	v_mov_b64_e32 v[16:17], v[0:1]
	s_mov_b32 s15, 0
	s_mov_b32 s16, 0
	v_mov_b64_e32 v[186:187], v[192:193]
	s_waitcnt vmcnt(0) lgkmcnt(0)
	s_barrier
	s_branch .LBB0_266

; #define MFMA32(a, b, c) __builtin_amdgcn_mfma_f32_32x32x16_bf16((a), (b), (c), 0, 0, 0)
; DI int crow(int r, int h) { return (r & 3) + 8 * (r >> 2) + 4 * h; }
; DI void attn_item(const Params& p, int g, int seq, int hd, int qt, int m, char* smem, int split_j, int sub) {
;     ...
;   auto compute = [&](int st, int buf) __attribute__((always_inline)) {
;     const int k0 = (tbase + st) * 32, h = h_, l31 = l31_;
;     const bf16_t* Kb = Ks + buf * 32 * 72; const bf16_t* Vb = Vs + buf * 128 * 40;
;     const int rmin = k0 - (qw0 + 31), rmax = k0 + 31 - qw0;
;     const bool farL = rmax <= -128, farR = rmin >= 128;
;     if (!farL && region == 0) { rescale(__builtin_amdgcn_exp2f(cneg)); region = 1; }
;     if (farR && region == 1) { rescale(__builtin_amdgcn_exp2f(-cpos)); region = 2; }
;     bf16x8 kf[4], vf[2][4];
; #pragma unroll
;     for (int s = 0; s < 4; ++s) kf[s] = *(const bf16x8*)(Kb + l31 * 72 + s * 16 + h * 8);
; #pragma unroll
;     for (int s2 = 0; s2 < 2; ++s2)
; #pragma unroll
;       for (int dt = 0; dt < 4; ++dt) vf[s2][dt] = *(const bf16x8*)(Vb + (dt * 32 + l31) * 40 + s2 * 16 + h * 8);
;     __builtin_amdgcn_sched_barrier(0);
;     f32x16 X;
; #pragma unroll
;     for (int r = 0; r < 16; ++r) X[r] = 0.f;
; #pragma unroll
;     for (int s = 0; s < 4; ++s) X = MFMA32(kf[s], qf[s], X);
;     if (farL || farR) {
; #pragma unroll
;       for (int r = 0; r < 16; ++r) X[r] = __builtin_amdgcn_exp2f(X[r]);
;     } else {
;       const int rel0 = k0 - (qw0 + l31) + 128;
; #pragma unroll
;       for (int r = 0; r < 16; ++r) { int idx = rel0 + crow(r, h); idx = idx < 0 ? 0 : (idx > 256 ? 256 : idx); X[r] = __builtin_amdgcn_exp2f(X[r] + tab[idx]); }
;     }
.LBB0_272:
	s_and_b32 s18, s11, 2
	s_mul_i32 s8, s18, 0x1200
	s_mul_i32 s19, s18, 0x2800
	v_add_u32_e32 v192, s8, v196
	v_add_u32_e32 v68, s19, v197
	ds_read_b128 v[64:67], v192
	ds_read_b128 v[80:83], v192 offset:32
	ds_read_b128 v[84:87], v192 offset:64
	ds_read_b128 v[88:91], v192 offset:96
	ds_read_b128 v[156:159], v68 offset:18432
	ds_read_b128 v[148:151], v68 offset:18464
	ds_read_b128 v[160:163], v68 offset:20992
	ds_read_b128 v[144:147], v68 offset:21024
	ds_read_b128 v[164:167], v68 offset:23552
	ds_read_b128 v[136:139], v68 offset:23584
	ds_read_b128 v[152:155], v68 offset:26112
	ds_read_b128 v[140:143], v68 offset:26144
	s_waitcnt lgkmcnt(11)
	v_mfma_f32_32x32x16_bf16 v[64:79], v[64:67], v[104:107], 0
	s_add_i32 s8, s17, 0xffffff61
	s_cmp_gt_u32 s8, 0xfffffec2
	s_waitcnt lgkmcnt(10)
	v_mfma_f32_32x32x16_bf16 v[64:79], v[80:83], v[108:111], v[64:79]
	s_waitcnt lgkmcnt(9)
	v_mfma_f32_32x32x16_bf16 v[64:79], v[84:87], v[112:115], v[64:79]
	s_waitcnt lgkmcnt(8)
	v_mfma_f32_32x32x16_bf16 v[64:79], v[88:91], v[116:119], v[64:79]
	s_cbranch_scc0 .LBB0_274
	v_add_u32_e32 v88, s13, v198
	v_add_u32_e32 v80, 0x80, v88
	v_add_u32_e32 v81, 0x81, v88
	v_add_u32_e32 v82, 0x82, v88
	v_add_u32_e32 v83, 0x83, v88
	v_add_u32_e32 v84, 0x88, v88
	v_add_u32_e32 v85, 0x89, v88
	v_add_u32_e32 v86, 0x8a, v88
	v_add_u32_e32 v87, 0x8b, v88
	v_med3_i32 v80, v80, 0, v215
	v_med3_i32 v81, v81, 0, v215
	v_med3_i32 v82, v82, 0, v215
	v_med3_i32 v83, v83, 0, v215
	v_med3_i32 v84, v84, 0, v215
	v_med3_i32 v85, v85, 0, v215
	v_med3_i32 v86, v86, 0, v215
	v_med3_i32 v87, v87, 0, v215
	v_add_u32_e32 v89, 0x90, v88
	v_add_u32_e32 v90, 0x91, v88
	v_add_u32_e32 v91, 0x92, v88
	v_add_u32_e32 v92, 0x93, v88
	v_add_u32_e32 v93, 0x98, v88
	v_add_u32_e32 v94, 0x99, v88
	v_add_u32_e32 v95, 0x9a, v88
	v_lshl_add_u32 v80, v80, 2, 32
	v_lshl_add_u32 v81, v81, 2, 32
	v_lshl_add_u32 v82, v82, 2, 32
	v_lshl_add_u32 v83, v83, 2, 32
	v_lshl_add_u32 v84, v84, 2, 32
	v_lshl_add_u32 v85, v85, 2, 32
	v_lshl_add_u32 v86, v86, 2, 32
	v_lshl_add_u32 v87, v87, 2, 32
	v_med3_i32 v89, v89, 0, v215
	v_med3_i32 v90, v90, 0, v215
	v_med3_i32 v91, v91, 0, v215
	v_med3_i32 v92, v92, 0, v215
	v_med3_i32 v93, v93, 0, v215
	v_med3_i32 v94, v94, 0, v215
	v_med3_i32 v95, v95, 0, v215
	v_add_u32_e32 v88, 0x9b, v88
	ds_read_b32 v80, v80 offset:59392
	ds_read_b32 v81, v81 offset:59392
	ds_read_b32 v82, v82 offset:59392
	ds_read_b32 v83, v83 offset:59392
	ds_read_b32 v84, v84 offset:59392
	ds_read_b32 v85, v85 offset:59392
	ds_read_b32 v86, v86 offset:59392
	ds_read_b32 v87, v87 offset:59392
	v_lshl_add_u32 v89, v89, 2, 32
	v_lshl_add_u32 v90, v90, 2, 32
	v_lshl_add_u32 v91, v91, 2, 32
	v_lshl_add_u32 v92, v92, 2, 32
	v_lshl_add_u32 v93, v93, 2, 32
	v_lshl_add_u32 v94, v94, 2, 32
	v_lshl_add_u32 v95, v95, 2, 32
	v_med3_i32 v88, v88, 0, v215
	v_lshl_add_u32 v88, v88, 2, 32
	ds_read_b32 v89, v89 offset:59392
	ds_read_b32 v90, v90 offset:59392
	ds_read_b32 v91, v91 offset:59392
	ds_read_b32 v92, v92 offset:59392
	ds_read_b32 v93, v93 offset:59392
	ds_read_b32 v94, v94 offset:59392
	ds_read_b32 v95, v95 offset:59392
	ds_read_b32 v171, v88 offset:59392
	s_waitcnt lgkmcnt(14)
	v_add_f32_e32 v80, v64, v80
	v_add_f32_e32 v81, v65, v81
	s_waitcnt lgkmcnt(13)
	v_add_f32_e32 v82, v66, v82
	s_waitcnt lgkmcnt(12)
	v_add_f32_e32 v83, v67, v83
	s_waitcnt lgkmcnt(11)
	v_add_f32_e32 v84, v68, v84
	s_waitcnt lgkmcnt(10)
	v_add_f32_e32 v85, v69, v85
	s_waitcnt lgkmcnt(9)
	v_add_f32_e32 v86, v70, v86
	s_waitcnt lgkmcnt(8)
	v_add_f32_e32 v87, v71, v87
	s_waitcnt lgkmcnt(7)
	v_add_f32_e32 v88, v72, v89
	s_waitcnt lgkmcnt(6)
	v_add_f32_e32 v89, v73, v90
	s_waitcnt lgkmcnt(5)
	v_add_f32_e32 v90, v74, v91
	s_waitcnt lgkmcnt(4)
	v_add_f32_e32 v91, v75, v92
	s_waitcnt lgkmcnt(3)
	v_add_f32_e32 v92, v76, v93
	s_waitcnt lgkmcnt(2)
	v_add_f32_e32 v93, v77, v94
	s_waitcnt lgkmcnt(1)
	v_add_f32_e32 v94, v78, v95
	v_exp_f32_e32 v80, v80
	v_exp_f32_e32 v81, v81
	v_exp_f32_e32 v82, v82
	v_exp_f32_e32 v83, v83
	v_exp_f32_e32 v84, v84
	v_exp_f32_e32 v85, v85
	v_exp_f32_e32 v86, v86
	v_exp_f32_e32 v87, v87
	v_exp_f32_e32 v88, v88
	v_exp_f32_e32 v89, v89
	v_exp_f32_e32 v90, v90
	v_exp_f32_e32 v91, v91
	v_exp_f32_e32 v92, v92
	v_exp_f32_e32 v93, v93
	v_exp_f32_e32 v94, v94
	s_waitcnt lgkmcnt(0)
	v_add_f32_e32 v79, v79, v171
	s_cbranch_execz .LBB0_275
	s_branch .LBB0_276

; #define MFMA32(a, b, c) __builtin_amdgcn_mfma_f32_32x32x16_bf16((a), (b), (c), 0, 0, 0)
; DI unsigned pk_bf16(float lo, float hi) { f32x2 v = {lo, hi}; bf16v2 b = __builtin_convertvector(v, bf16v2); return __builtin_bit_cast(unsigned, b); }
; DI void attn_item(const Params& p, int g, int seq, int hd, int qt, int m, char* smem, int split_j, int sub) {
;     ...
;     bf16x8 pf[2];
; #pragma unroll
;     for (int s2 = 0; s2 < 2; ++s2) {
;       u32x4 w; w.x = pk_bf16(X[8 * s2], X[8 * s2 + 1]); w.y = pk_bf16(X[8 * s2 + 2], X[8 * s2 + 3]); w.z = pk_bf16(X[8 * s2 + 4], X[8 * s2 + 5]); w.w = pk_bf16(X[8 * s2 + 6], X[8 * s2 + 7]);
;       ls2 += (f32x2){X[8 * s2], X[8 * s2 + 1]}; ls2 += (f32x2){X[8 * s2 + 2], X[8 * s2 + 3]};
;       ls2 += (f32x2){X[8 * s2 + 4], X[8 * s2 + 5]}; ls2 += (f32x2){X[8 * s2 + 6], X[8 * s2 + 7]};
;       pf[s2] = __builtin_bit_cast(bf16x8, w);
;     }
; #pragma unroll
;     for (int s2 = 0; s2 < 2; ++s2)
; #pragma unroll
;       for (int dt = 0; dt < 4; ++dt) O[dt] = MFMA32(pf[s2], vf[s2][dt], O[dt]);
;   };
;   load_tile(0, rkA, rvA0, rvA1);
;   load_tile(1, rkB, rvB0, rvB1);
;   __syncthreads();
;   store_tile(0, rkA, rvA0, rvA1);
;   store_tile(1, rkB, rvB0, rvB1);
;   __syncthreads();
;   for (int it = 0; it < npairs; ++it) {
;     const int set = it & 1;
;     if (it + 1 < npairs) { load_tile(2 * it + 2, rkA, rvA0, rvA1); load_tile(2 * it + 3, rkB, rvB0, rvB1); }
;     compute(2 * it, 2 * set);
;     compute(2 * it + 1, 2 * set + 1);
;     if (it + 1 < npairs) { store_tile(2 * (set ^ 1), rkA, rvA0, rvA1); store_tile(2 * (set ^ 1) + 1, rkB, rvB0, rvB1); }
.LBB0_284:
	v_cvt_pk_bf16_f32 v80, v64, v65
	v_cvt_pk_bf16_f32 v81, v66, v67
	v_cvt_pk_bf16_f32 v82, v68, v69
	v_cvt_pk_bf16_f32 v83, v70, v71
	v_exp_f32_e32 v79, v95
	v_cvt_pk_bf16_f32 v84, v72, v73
	s_waitcnt lgkmcnt(7)
	v_mfma_f32_32x32x16_bf16 v[16:31], v[80:83], v[156:159], v[16:31]
	v_cvt_pk_bf16_f32 v85, v74, v75
	v_cvt_pk_bf16_f32 v86, v76, v77
	v_cvt_pk_bf16_f32 v87, v78, v79
	s_andn2_b64 vcc, exec, s[6:7]
	s_waitcnt lgkmcnt(5)
	v_mfma_f32_32x32x16_bf16 v[32:47], v[80:83], v[160:163], v[32:47]
	s_waitcnt lgkmcnt(3)
	v_mfma_f32_32x32x16_bf16 v[48:63], v[80:83], v[164:167], v[48:63]
	s_waitcnt lgkmcnt(1)
	v_mfma_f32_32x32x16_bf16 v[0:15], v[80:83], v[152:155], v[0:15]
	v_mfma_f32_32x32x16_bf16 v[16:31], v[84:87], v[136:139], v[16:31]
	v_mfma_f32_32x32x16_bf16 v[32:47], v[84:87], v[140:143], v[32:47]
	v_mfma_f32_32x32x16_bf16 v[48:63], v[84:87], v[144:147], v[48:63]
	s_waitcnt lgkmcnt(0)
	v_mfma_f32_32x32x16_bf16 v[0:15], v[84:87], v[148:151], v[0:15]
	s_cbranch_vccnz .LBB0_265
	s_xor_b32 s6, s18, 2
	s_mul_i32 s7, s6, 0x2800
	s_add_i32 s7, s7, 32
	s_mulk_i32 s6, 0x1200
	v_add_u32_e32 v80, s6, v189
	v_add3_u32 v81, s7, v190, v191
	s_addk_i32 s7, 0x2800
	s_waitcnt vmcnt(5)
	ds_write_b128 v80, v[96:99]
	s_waitcnt vmcnt(4)
	ds_write_b128 v81, v[100:103] offset:18432
	s_waitcnt vmcnt(3)
	ds_write_b128 v81, v[120:123] offset:23552
	s_waitcnt vmcnt(2)
	ds_write_b128 v80, v[124:127] offset:4608
	v_add3_u32 v80, s7, v190, v191
	s_waitcnt vmcnt(1)
	ds_write_b128 v80, v[128:131] offset:18432
	s_waitcnt vmcnt(0)
	ds_write_b128 v80, v[132:135] offset:23552
	s_branch .LBB0_265

; __device__ __forceinline__ int TID() { int t = threadIdx.x; asm volatile("" : "+v"(t)); return t; }
; DI void gla_scan_unit(const Params& p, int g, int u, char* smem) {
;   const GroupInfo gi = group_info(p, g);
;   bf16_t* St = (bf16_t*)smem;
;   bf16_t* Am = St + 64 * 136;
;   const int slice = u & 3, dir = (u >> 2) & 1, head = (u >> 3) & 3, seq = u >> 5;
;   const int nchunk = gi.S >> 6, chunk0 = seq * nchunk;
;   const int tid = TID(), lane = tid & 63, wave = tid >> 6, wi = wave >> 1, wd = wave & 1, h = lane >> 5, l31 = lane & 31;
;   const bf16_t* gq = (const bf16_t*)(p.ws + OFF_GQ); const bf16_t* gk = (const bf16_t*)(p.ws + OFF_GK); const bf16_t* gkt = (const bf16_t*)(p.ws + OFF_GKT);
;   const float* ge = (const float*)(p.ws + OFF_GE); const bf16_t* vgT = (const bf16_t*)(p.ws + OFF_VGT);
;   bf16_t* od = (bf16_t*)gi.out + (size_t)dir * TOKG * 1024;
;   __syncthreads();
;   for (int i = tid; i < 64 * 136 / 2; i += 256) ((unsigned*)St)[i] = 0u;
;   f32x16 Sacc[2];
; #pragma unroll
;   for (int t = 0; t < 2; ++t)
; #pragma unroll
;     for (int r = 0; r < 16; ++r) Sacc[t][r] = 0.f;
;   __syncthreads();
;   auto blk_of = [&](int step) __attribute__((always_inline)) { return (size_t)((dir * 4 + head) * 256 + chunk0 + (dir ? nchunk - 1 - step : step)); };
;   bf16x8 qf[8], kf[8];
;   {
;     const size_t blk = blk_of(0);
; #pragma unroll
;     for (int s = 0; s < 8; ++s) { qf[s] = *(const bf16x8*)(gq + blk * 8192 + (wi * 32 + l31) * 128 + s * 16 + h * 8); kf[s] = *(const bf16x8*)(gk + blk * 8192 + (wd * 32 + l31) * 128 + s * 16 + h * 8); }
;   }
;     ...
;       const int gi_ = wi * 32 + l31;
; #pragma unroll
;       for (int q4 = 0; q4 < 4; ++q4) {
;         float v[4];
; #pragma unroll
;         for (int e = 0; e < 4; ++e) { const int gj = wd * 32 + 8 * q4 + 4 * h + e; const bool keep = dir ? (gj >= gi_) : (gj <= gi_); v[e] = keep ? X[4 * q4 + e] : 0.f; }
.LBB0_313:
	s_or_b64 exec, exec, s[0:1]
	v_readlane_b32 s0, v231, 34
	s_add_i32 s0, s12, s0
	s_bfe_u32 s6, s0, 0x10002
	s_ashr_i32 s7, s0, 5
	v_readlane_b32 s8, v231, 35
	v_ashrrev_i32_e32 v1, 7, v0
	v_bfe_u32 v10, v0, 6, 1
	v_bfe_u32 v4, v0, 5, 1
	s_bfe_i32 s1, s0, 0x10002
	s_lshl_b32 s84, s7, s8
	v_and_b32_e32 v12, 31, v0
	s_lshl_b32 s7, s6, 25
	v_readlane_b32 s8, v231, 23
	v_lshlrev_b32_e32 v196, 5, v1
	v_lshlrev_b32_e32 v11, 5, v10
	v_lshlrev_b32_e32 v198, 2, v4
	s_add_u32 s8, s8, s7
	v_readlane_b32 s7, v231, 24
	v_or_b32_e32 v13, v196, v12
	v_or_b32_e32 v14, v11, v198
	s_addc_u32 s9, s7, 0
	v_cmp_le_i32_e32 vcc, v14, v13
	s_cmp_eq_u32 s6, 0
	v_readlane_b32 s39, v231, 36
	v_cndmask_b32_e64 v15, 0, 1, vcc
	v_cmp_ge_i32_e32 vcc, v14, v13
	v_lshlrev_b32_e32 v5, 7, v12
	v_lshlrev_b32_e32 v17, 12, v1
	v_cndmask_b32_e64 v16, 0, 1, vcc
	s_cselect_b64 vcc, -1, 0
	s_lshl_b32 s0, s0, 5
	s_lshl_b32 s6, s6, 10
	s_and_b32 s78, s0, 0x300
	s_or_b32 s79, s6, s78
	s_and_b32 s1, s1, s39
	s_add_i32 s80, s79, s84
	s_add_i32 s0, s80, s1
	s_ashr_i32 s1, s0, 31
	s_lshl_b64 s[0:1], s[0:1], 14
	s_add_u32 s6, s4, s0
	s_addc_u32 s7, s5, s1
	v_lshlrev_b32_e32 v18, 3, v4
	v_lshlrev_b32_e32 v192, 4, v4
	s_add_u32 s0, s68, s0
	v_lshl_or_b32 v4, v10, 12, v5
	v_or_b32_e32 v2, v17, v5
	s_addc_u32 s1, s69, s1
	v_lshlrev_b32_e32 v6, 1, v4
	v_mov_b32_e32 v7, v193
	v_ashrrev_i32_e32 v3, 31, v2
	v_lshl_add_u64 v[8:9], s[0:1], 0, v[6:7]
	s_lshl_b32 s0, s12, 6
	v_lshl_add_u64 v[2:3], v[2:3], 1, s[6:7]
	s_and_b32 s6, s0, 0xc0
	s_lshl_b32 s0, s6, 7
	s_add_u32 s0, s64, s0
	v_lshl_add_u64 v[2:3], v[2:3], 0, v[192:193]
	v_mov_b32_e32 v5, v193
	s_addc_u32 s1, s65, 0
	s_waitcnt lgkmcnt(0)
	s_barrier
	v_lshl_add_u64 v[8:9], v[8:9], 0, v[192:193]
	global_load_dwordx4 v[76:79], v[2:3], off
	global_load_dwordx4 v[72:75], v[2:3], off offset:32
	global_load_dwordx4 v[100:103], v[8:9], off
	global_load_dwordx4 v[104:107], v[8:9], off offset:32
	global_load_dwordx4 v[68:71], v[2:3], off offset:64
	global_load_dwordx4 v[64:67], v[2:3], off offset:96
	global_load_dwordx4 v[108:111], v[8:9], off offset:64
	global_load_dwordx4 v[96:99], v[8:9], off offset:96
	global_load_dwordx4 v[60:63], v[2:3], off offset:128
	global_load_dwordx4 v[56:59], v[2:3], off offset:160
	global_load_dwordx4 v[92:95], v[8:9], off offset:128
	global_load_dwordx4 v[84:87], v[8:9], off offset:160
	global_load_dwordx4 v[52:55], v[2:3], off offset:192
	global_load_dwordx4 v[48:51], v[2:3], off offset:224
	global_load_dwordx4 v[88:91], v[8:9], off offset:192
	global_load_dwordx4 v[80:83], v[8:9], off offset:224
	v_lshl_add_u64 v[2:3], s[0:1], 0, v[4:5]
	v_readlane_b32 s0, v233, 20
	v_readlane_b32 s1, v233, 21
	v_lshl_add_u64 v[4:5], s[68:69], 0, v[6:7]
	v_lshl_add_u64 v[200:201], v[2:3], 0, v[192:193]
	v_lshl_add_u64 v[2:3], s[0:1], 0, v[192:193]
	v_lshl_add_u64 v[202:203], v[4:5], 0, v[192:193]
	v_or_b32_e32 v5, v11, v12
	s_movk_i32 s0, 0x110
	v_mad_u32_u24 v223, v5, s0, 32
	v_readlane_b32 s0, v233, 22
	v_readlane_b32 s1, v233, 23
	s_movk_i32 s10, 0x90
	v_mul_lo_u32 v4, v13, s10
	v_lshl_add_u64 v[8:9], s[0:1], 0, v[192:193]
	s_lshl_b32 s0, s78, 1
	s_add_u32 s0, s8, s0
	v_add_u32_e32 v221, 32, v4
	v_lshlrev_b32_e32 v4, 6, v10
	s_addc_u32 s1, s9, 0
	v_mov_b32_e32 v5, v193
	v_add_u32_e32 v19, v221, v4
	v_lshl_add_u64 v[4:5], s[0:1], 0, v[4:5]
	v_lshlrev_b32_e32 v10, 1, v12
	v_mov_b32_e32 v11, v193
	v_lshl_add_u64 v[4:5], v[4:5], 0, v[10:11]
	s_lshl_b32 s50, s6, 1
	v_lshlrev_b32_e32 v6, 7, v13
	v_lshl_add_u64 v[206:207], v[4:5], 0, s[50:51]
	v_cndmask_b32_e32 v5, v16, v15, vcc
	v_ashrrev_i32_e32 v7, 31, v6
	v_and_b32_e32 v5, 1, v5
	v_lshl_add_u64 v[6:7], v[6:7], 1, s[4:5]
	v_cmp_eq_u32_e64 s[0:1], 1, v5
	v_or_b32_e32 v5, 1, v14
	v_cmp_lt_i32_e64 s[6:7], v14, v13
	v_lshl_add_u64 v[204:205], v[6:7], 0, v[192:193]
	v_and_b32_e32 v0, 0xffffff80, v0
	v_cndmask_b32_e64 v7, 0, 1, s[6:7]
	v_cmp_ge_i32_e64 s[6:7], v5, v13
	v_add_u32_e32 v4, v223, v0
	v_lshl_or_b32 v0, v12, 6, v17
	v_cndmask_b32_e64 v5, 0, 1, s[6:7]
	v_cndmask_b32_e32 v5, v5, v7, vcc
	v_and_b32_e32 v5, 1, v5
	v_cmp_eq_u32_e64 s[36:37], 1, v5
	v_or_b32_e32 v5, 2, v14
	v_cmp_le_i32_e64 s[6:7], v5, v13
	v_lshlrev_b32_e32 v6, 6, v1
	v_ashrrev_i32_e32 v1, 31, v0
	v_cndmask_b32_e64 v7, 0, 1, s[6:7]
	v_cmp_ge_i32_e64 s[6:7], v5, v13
	v_lshl_add_u64 v[238:239], v[0:1], 1, v[2:3]
	v_mov_b32_e32 v0, 0
	v_cndmask_b32_e64 v5, 0, 1, s[6:7]
	v_cndmask_b32_e32 v5, v5, v7, vcc
	v_and_b32_e32 v5, 1, v5
	v_cmp_eq_u32_e64 s[6:7], 1, v5
	v_or_b32_e32 v5, 3, v14
	v_cmp_le_i32_e64 s[8:9], v5, v13
	s_mov_b32 s38, 0
	v_ashrrev_i32_e32 v197, 31, v196
	v_cndmask_b32_e64 v7, 0, 1, s[8:9]
	v_cmp_ge_i32_e64 s[8:9], v5, v13
	v_or_b32_e32 v208, 1, v198
	v_or_b32_e32 v210, 2, v198
	v_cndmask_b32_e64 v5, 0, 1, s[8:9]
	v_cndmask_b32_e32 v5, v5, v7, vcc
	v_and_b32_e32 v5, 1, v5
	v_cmp_eq_u32_e64 s[8:9], 1, v5
	v_or_b32_e32 v5, 8, v14
	v_cmp_le_i32_e64 s[10:11], v5, v13
	v_or_b32_e32 v212, 3, v198
	v_or_b32_e32 v214, 8, v198
	v_cndmask_b32_e64 v7, 0, 1, s[10:11]
	v_cmp_ge_i32_e64 s[10:11], v5, v13
	v_or_b32_e32 v216, 9, v198
	v_or_b32_e32 v218, 10, v198
	v_cndmask_b32_e64 v5, 0, 1, s[10:11]
	v_cndmask_b32_e32 v5, v5, v7, vcc
	v_and_b32_e32 v5, 1, v5
	v_cmp_eq_u32_e64 s[10:11], 1, v5
	v_or_b32_e32 v5, 9, v14
	v_cmp_le_i32_e64 s[12:13], v5, v13
	v_or_b32_e32 v220, 11, v198
	v_or_b32_e32 v222, 16, v198
	v_cndmask_b32_e64 v7, 0, 1, s[12:13]
	v_cmp_ge_i32_e64 s[12:13], v5, v13
	v_or_b32_e32 v224, 17, v198
	v_or_b32_e32 v226, 18, v198
	v_cndmask_b32_e64 v5, 0, 1, s[12:13]
	v_cndmask_b32_e32 v5, v5, v7, vcc
	v_and_b32_e32 v5, 1, v5
	v_cmp_eq_u32_e64 s[12:13], 1, v5
	v_or_b32_e32 v5, 10, v14
; #define MFMA32(a, b, c) __builtin_amdgcn_mfma_f32_32x32x16_bf16((a), (b), (c), 0, 0, 0)
; DI void gla_scan_unit(const Params& p, int g, int u, char* smem) {
;     ...
;   for (int step = 0; step < nchunk; ++step) {
;     const int cgk = chunk0 + (dir ? nchunk - 1 - step : step);
;     const size_t blk = (size_t)((dir * 4 + head) * 256 + cgk);
;     const size_t blkn = blk_of(step + 1 < nchunk ? step + 1 : step);
;     const bf16_t* gkt_c = gkt + blk * 8192;
;     const bf16_t* vt_c = vgT + ((size_t)(head * 256 + cgk) * 256 + slice * 64) * 64;
;     const float* e_c = ge + blk * 128;
;     bf16x8 vf[4], ktf[2][4]; f32x4 ev[2][4];
; #pragma unroll
;     for (int s = 0; s < 4; ++s) vf[s] = *(const bf16x8*)(vt_c + (wd * 32 + l31) * 64 + s * 16 + h * 8);
; #pragma unroll
;     for (int t = 0; t < 2; ++t)
; #pragma unroll
;       for (int s = 0; s < 4; ++s) ktf[t][s] = *(const bf16x8*)(gkt_c + ((2 * wi + t) * 32 + l31) * 64 + s * 16 + h * 8);
;     f32x16 X;
; #pragma unroll
;     for (int r = 0; r < 16; ++r) X[r] = 0.f;
; #pragma unroll
;     for (int s = 0; s < 8; ++s) X = MFMA32(kf[s], qf[s], X);
;     __builtin_amdgcn_sched_barrier(0);
; #pragma unroll
;     for (int s = 0; s < 8; ++s) kf[s] = *(const bf16x8*)(gk + blkn * 8192 + (wd * 32 + l31) * 128 + s * 16 + h * 8);
	v_cmp_le_i32_e64 s[14:15], v5, v13
	v_or_b32_e32 v228, 19, v198
	v_or_b32_e32 v230, 24, v198
	v_cndmask_b32_e64 v7, 0, 1, s[14:15]
	v_cmp_ge_i32_e64 s[14:15], v5, v13
	v_or_b32_e32 v232, 25, v198
	v_or_b32_e32 v234, 26, v198
	v_cndmask_b32_e64 v5, 0, 1, s[14:15]
	v_cndmask_b32_e32 v5, v5, v7, vcc
	v_and_b32_e32 v5, 1, v5
	v_cmp_eq_u32_e64 s[14:15], 1, v5
	v_or_b32_e32 v5, 11, v14
	v_cmp_le_i32_e64 s[16:17], v5, v13
	v_or_b32_e32 v236, 27, v198
	v_add_u32_e32 v225, v19, v18
	v_cndmask_b32_e64 v7, 0, 1, s[16:17]
	v_cmp_ge_i32_e64 s[16:17], v5, v13
	v_add_u32_e32 v227, v4, v18
	s_mov_b32 s50, s39
	v_cndmask_b32_e64 v5, 0, 1, s[16:17]
	v_cndmask_b32_e32 v5, v5, v7, vcc
	v_and_b32_e32 v5, 1, v5
	v_cmp_eq_u32_e64 s[16:17], 1, v5
	v_or_b32_e32 v5, 16, v14
	v_cmp_le_i32_e64 s[18:19], v5, v13
	v_mov_b32_e32 v1, v0
	v_mov_b32_e32 v2, v0
	v_cndmask_b32_e64 v7, 0, 1, s[18:19]
	v_cmp_ge_i32_e64 s[18:19], v5, v13
	v_mov_b32_e32 v3, v0
	v_mov_b32_e32 v4, v0
	v_cndmask_b32_e64 v5, 0, 1, s[18:19]
	v_cndmask_b32_e32 v5, v5, v7, vcc
	v_and_b32_e32 v5, 1, v5
	v_cmp_eq_u32_e64 s[18:19], 1, v5
	v_or_b32_e32 v5, 17, v14
	v_cmp_le_i32_e64 s[20:21], v5, v13
	v_mov_b32_e32 v10, v0
	v_mov_b32_e32 v11, v0
	v_cndmask_b32_e64 v7, 0, 1, s[20:21]
	v_cmp_ge_i32_e64 s[20:21], v5, v13
	v_mov_b32_e32 v12, v0
	v_mov_b32_e32 v15, v0
	v_cndmask_b32_e64 v5, 0, 1, s[20:21]
	v_cndmask_b32_e32 v5, v5, v7, vcc
	v_and_b32_e32 v5, 1, v5
	v_cmp_eq_u32_e64 s[20:21], 1, v5
	v_or_b32_e32 v5, 18, v14
	v_cmp_le_i32_e64 s[22:23], v5, v13
	v_mov_b32_e32 v16, v0
	v_mov_b32_e32 v17, v0
	v_cndmask_b32_e64 v7, 0, 1, s[22:23]
	v_cmp_ge_i32_e64 s[22:23], v5, v13
	v_mov_b32_e32 v18, v0
	v_mov_b32_e32 v19, v0
	v_cndmask_b32_e64 v5, 0, 1, s[22:23]
	v_cndmask_b32_e32 v5, v5, v7, vcc
	v_and_b32_e32 v5, 1, v5
	v_cmp_eq_u32_e64 s[22:23], 1, v5
	v_or_b32_e32 v5, 19, v14
	v_cmp_le_i32_e64 s[24:25], v5, v13
	v_mov_b32_e32 v20, v0
	v_mov_b32_e32 v21, v0
	v_cndmask_b32_e64 v7, 0, 1, s[24:25]
	v_cmp_ge_i32_e64 s[24:25], v5, v13
	v_mov_b32_e32 v22, v0
	v_mov_b32_e32 v23, v0
	v_cndmask_b32_e64 v5, 0, 1, s[24:25]
	v_cndmask_b32_e32 v5, v5, v7, vcc
	v_and_b32_e32 v5, 1, v5
	v_cmp_eq_u32_e64 s[24:25], 1, v5
	v_or_b32_e32 v5, 24, v14
	v_cmp_le_i32_e64 s[26:27], v5, v13
	v_mov_b32_e32 v24, v0
	v_mov_b32_e32 v25, v0
	v_cndmask_b32_e64 v7, 0, 1, s[26:27]
	v_cmp_ge_i32_e64 s[26:27], v5, v13
	v_mov_b32_e32 v26, v0
	v_mov_b32_e32 v27, v0
	v_cndmask_b32_e64 v5, 0, 1, s[26:27]
	v_cndmask_b32_e32 v5, v5, v7, vcc
	v_and_b32_e32 v5, 1, v5
	v_cmp_eq_u32_e64 s[26:27], 1, v5
	v_or_b32_e32 v5, 25, v14
	v_cmp_le_i32_e64 s[28:29], v5, v13
	v_mov_b32_e32 v28, v0
	v_mov_b32_e32 v29, v0
	v_cndmask_b32_e64 v7, 0, 1, s[28:29]
	v_cmp_ge_i32_e64 s[28:29], v5, v13
	v_mov_b32_e32 v30, v0
	v_mov_b32_e32 v31, v0
	v_cndmask_b32_e64 v5, 0, 1, s[28:29]
	v_cndmask_b32_e32 v5, v5, v7, vcc
	v_and_b32_e32 v5, 1, v5
	v_cmp_eq_u32_e64 s[28:29], 1, v5
	v_or_b32_e32 v5, 26, v14
	v_cmp_le_i32_e64 s[30:31], v5, v13
	s_nop 1
	v_cndmask_b32_e64 v7, 0, 1, s[30:31]
	v_cmp_ge_i32_e64 s[30:31], v5, v13
	s_nop 1
	v_cndmask_b32_e64 v5, 0, 1, s[30:31]
	v_cndmask_b32_e32 v5, v5, v7, vcc
	v_and_b32_e32 v5, 1, v5
	v_cmp_eq_u32_e64 s[30:31], 1, v5
	v_or_b32_e32 v5, 27, v14
	v_cmp_le_i32_e64 s[34:35], v5, v13
	v_mov_b32_e32 v14, v0
	s_nop 0
	v_cndmask_b32_e64 v7, 0, 1, s[34:35]
	v_cmp_ge_i32_e64 s[34:35], v5, v13
	v_mov_b32_e32 v13, v0
	s_nop 0
	v_cndmask_b32_e64 v5, 0, 1, s[34:35]
	v_cndmask_b32_e32 v5, v5, v7, vcc
	v_and_b32_e32 v5, 1, v5
	v_ashrrev_i32_e32 v7, 31, v6
	v_cmp_eq_u32_e64 s[34:35], 1, v5
	v_lshl_add_u64 v[240:241], v[6:7], 2, v[8:9]
	v_mov_b32_e32 v5, v0
	v_mov_b32_e32 v6, v0
	v_mov_b32_e32 v7, v0
	v_mov_b32_e32 v8, v0
	v_mov_b32_e32 v9, v0
	s_waitcnt vmcnt(0)
.LBB0_314:
	s_waitcnt vmcnt(23)
	v_mfma_f32_32x32x16_bf16 v[32:47], v[100:103], v[76:79], 0
	s_and_b64 s[62:63], vcc, exec
	s_cselect_b32 s39, s38, s50
	s_add_i32 s70, s39, s84
	s_add_i32 s62, s70, s79
	s_add_i32 s82, s38, 1
	s_cmp_lt_u32 s82, s73
	s_cselect_b32 s63, s82, s38
	s_waitcnt vmcnt(22)
	v_mfma_f32_32x32x16_bf16 v[32:47], v[104:107], v[72:75], v[32:47]
	s_not_b32 s38, s63
	s_add_i32 s71, s73, s38
	s_and_b64 s[38:39], vcc, exec
	s_cselect_b32 s71, s63, s71
	s_add_i32 s38, s70, s78
	s_ashr_i32 s39, s38, 31
	s_lshl_b64 s[38:39], s[38:39], 15
	s_waitcnt vmcnt(21)
	v_mfma_f32_32x32x16_bf16 v[32:47], v[108:111], v[68:71], v[32:47]
	s_ashr_i32 s63, s62, 31
	s_waitcnt vmcnt(20)
	v_mfma_f32_32x32x16_bf16 v[32:47], v[96:99], v[64:67], v[32:47]
	v_lshl_add_u64 v[96:97], v[200:201], 0, s[38:39]
	s_lshl_b64 s[38:39], s[62:63], 14
	global_load_dwordx4 v[136:139], v[96:97], off
	global_load_dwordx4 v[128:131], v[96:97], off offset:32
	s_waitcnt vmcnt(21)
	v_mfma_f32_32x32x16_bf16 v[32:47], v[92:95], v[60:63], v[32:47]
	v_lshl_add_u64 v[92:93], v[238:239], 0, s[38:39]
	s_lshl_b64 s[38:39], s[62:63], 9
	v_lshl_add_u64 v[144:145], v[240:241], 0, s[38:39]
	global_load_dwordx4 v[188:191], v[144:145], off
	global_load_dwordx4 v[184:187], v[144:145], off offset:32
	global_load_dwordx4 v[180:183], v[144:145], off offset:64
	global_load_dwordx4 v[176:179], v[144:145], off offset:96
	global_load_dwordx4 v[156:159], v[144:145], off offset:128
	global_load_dwordx4 v[152:155], v[144:145], off offset:160
	global_load_dwordx4 v[148:151], v[144:145], off offset:192
	s_nop 0
	global_load_dwordx4 v[144:147], v[144:145], off offset:224
	global_load_dwordx4 v[172:175], v[92:93], off
	global_load_dwordx4 v[168:171], v[92:93], off offset:32
	global_load_dwordx4 v[120:123], v[96:97], off offset:64
	global_load_dwordx4 v[112:115], v[96:97], off offset:96
	global_load_dwordx4 v[164:167], v[92:93], off offset:64
	global_load_dwordx4 v[160:163], v[92:93], off offset:96
	s_waitcnt vmcnt(34)
; #define MFMA32(a, b, c) __builtin_amdgcn_mfma_f32_32x32x16_bf16((a), (b), (c), 0, 0, 0)
; DI void lds_barrier() { asm volatile("s_waitcnt lgkmcnt(0)\n\ts_barrier" ::: "memory"); }
; DI unsigned pk_bf16(float lo, float hi) { f32x2 v = {lo, hi}; bf16v2 b = __builtin_convertvector(v, bf16v2); return __builtin_bit_cast(unsigned, b); }
; DI bf16_t f2bf(float x) { return (bf16_t)(pk_bf16(x, 0.f) & 0xffffu); }
; DI int crow(int r, int h) { return (r & 3) + 8 * (r >> 2) + 4 * h; }
; DI void gla_scan_unit(const Params& p, int g, int u, char* smem) {
;     ...
;     for (int s = 0; s < 8; ++s) X = MFMA32(kf[s], qf[s], X);
;     __builtin_amdgcn_sched_barrier(0);
; #pragma unroll
;     for (int s = 0; s < 8; ++s) kf[s] = *(const bf16x8*)(gk + blkn * 8192 + (wd * 32 + l31) * 128 + s * 16 + h * 8);
;     {
;       const int gi_ = wi * 32 + l31;
; #pragma unroll
;       for (int q4 = 0; q4 < 4; ++q4) {
;         float v[4];
; #pragma unroll
;         for (int e = 0; e < 4; ++e) { const int gj = wd * 32 + 8 * q4 + 4 * h + e; const bool keep = dir ? (gj >= gi_) : (gj <= gi_); v[e] = keep ? X[4 * q4 + e] : 0.f; }
;         u32x2 o; o.x = pk_bf16(v[0], v[1]); o.y = pk_bf16(v[2], v[3]);
;         *(u32x2*)(Am + gi_ * 72 + wd * 32 + 8 * q4 + 4 * h) = o;
;       }
;     }
;     f32x16 o;
; #pragma unroll
;     for (int r = 0; r < 16; ++r) o[r] = 0.f;
; #pragma unroll
;     for (int s = 0; s < 8; ++s) { const bf16x8 sf = *(const bf16x8*)(St + (wd * 32 + l31) * 136 + s * 16 + h * 8); o = MFMA32(qf[s], sf, o); }
;     __builtin_amdgcn_sched_barrier(0);
; #pragma unroll
;     for (int s = 0; s < 8; ++s) qf[s] = *(const bf16x8*)(gq + blkn * 8192 + (wi * 32 + l31) * 128 + s * 16 + h * 8);
;     lds_barrier();
; #pragma unroll
;     for (int t = 0; t < 2; ++t)
; #pragma unroll
;       for (int q4 = 0; q4 < 4; ++q4) ev[t][q4] = *(const f32x4*)(e_c + (2 * wi + t) * 32 + 8 * q4 + 4 * h);
; #pragma unroll
;     for (int s = 0; s < 4; ++s) { const bf16x8 af = *(const bf16x8*)(Am + (wi * 32 + l31) * 72 + s * 16 + h * 8); o = MFMA32(af, vf[s], o); }
;     {
;       const size_t tokb = (size_t)cgk * 64 + wi * 32;
; #pragma unroll
;       for (int r = 0; r < 16; ++r) od[(tokb + crow(r, h)) * 1024 + head * 256 + slice * 64 + wd * 32 + l31] = f2bf(o[r]);
	v_mfma_f32_32x32x16_bf16 v[32:47], v[84:87], v[56:59], v[32:47]
	v_add_co_u32_e64 v84, s[38:39], s81, v92
	s_nop 1
	v_addc_co_u32_e64 v85, s[38:39], 0, v93, s[38:39]
	global_load_dwordx4 v[140:143], v[84:85], off
	global_load_dwordx4 v[132:135], v[84:85], off offset:32
	global_load_dwordx4 v[124:127], v[84:85], off offset:64
	global_load_dwordx4 v[116:119], v[84:85], off offset:96
	s_waitcnt vmcnt(37)
	v_mfma_f32_32x32x16_bf16 v[32:47], v[88:91], v[52:55], v[32:47]
	s_add_i32 s38, s71, s80
	s_ashr_i32 s39, s38, 31
	s_waitcnt vmcnt(36)
	v_mfma_f32_32x32x16_bf16 v[32:47], v[80:83], v[48:51], v[32:47]
	s_nop 11
	v_cndmask_b32_e64 v32, 0, v32, s[0:1]
	v_cndmask_b32_e64 v33, 0, v33, s[36:37]
	v_cndmask_b32_e64 v34, 0, v34, s[6:7]
	v_cndmask_b32_e64 v35, 0, v35, s[8:9]
	v_cvt_pk_bf16_f32 v32, v32, v33
	v_cvt_pk_bf16_f32 v33, v34, v35
	v_cndmask_b32_e64 v34, 0, v36, s[10:11]
	v_cndmask_b32_e64 v35, 0, v37, s[12:13]
	v_cndmask_b32_e64 v36, 0, v38, s[14:15]
	v_cndmask_b32_e64 v37, 0, v39, s[16:17]
	v_cvt_pk_bf16_f32 v34, v34, v35
	v_cvt_pk_bf16_f32 v35, v36, v37
	v_add_u32_e32 v36, 0x4000, v225
	ds_write2_b64 v36, v[32:33], v[34:35] offset0:128 offset1:130
	v_cndmask_b32_e64 v32, 0, v40, s[18:19]
	v_cndmask_b32_e64 v33, 0, v41, s[20:21]
	v_cndmask_b32_e64 v34, 0, v42, s[22:23]
	v_cndmask_b32_e64 v35, 0, v43, s[24:25]
	v_cvt_pk_bf16_f32 v32, v32, v33
	v_cvt_pk_bf16_f32 v33, v34, v35
	v_cndmask_b32_e64 v34, 0, v44, s[26:27]
	v_cndmask_b32_e64 v35, 0, v45, s[28:29]
	v_cndmask_b32_e64 v37, 0, v46, s[30:31]
	v_cndmask_b32_e64 v38, 0, v47, s[34:35]
	v_cvt_pk_bf16_f32 v34, v34, v35
	v_cvt_pk_bf16_f32 v35, v37, v38
	ds_write2_b64 v36, v[32:33], v[34:35] offset0:132 offset1:134
	v_add_u32_e32 v88, v223, v192
	ds_read_b128 v[32:35], v88
	ds_read_b128 v[80:83], v88 offset:32
	s_waitcnt lgkmcnt(1)
	v_mfma_f32_32x32x16_bf16 v[32:47], v[76:79], v[32:35], 0
	s_lshl_b64 s[38:39], s[38:39], 14
	s_waitcnt lgkmcnt(0)
	v_mfma_f32_32x32x16_bf16 v[32:47], v[72:75], v[80:83], v[32:47]
	ds_read_b128 v[72:75], v88 offset:64
	ds_read_b128 v[76:79], v88 offset:96
	s_waitcnt lgkmcnt(1)
	v_mfma_f32_32x32x16_bf16 v[32:47], v[68:71], v[72:75], v[32:47]
	s_waitcnt lgkmcnt(0)
	v_mfma_f32_32x32x16_bf16 v[32:47], v[64:67], v[76:79], v[32:47]
	ds_read_b128 v[64:67], v88 offset:128
	ds_read_b128 v[68:71], v88 offset:160
	s_waitcnt lgkmcnt(1)
	v_mfma_f32_32x32x16_bf16 v[32:47], v[60:63], v[64:67], v[32:47]
	v_lshl_add_u64 v[64:65], v[202:203], 0, s[38:39]
	global_load_dwordx4 v[100:103], v[64:65], off
	global_load_dwordx4 v[104:107], v[64:65], off offset:32
	s_waitcnt lgkmcnt(0)
	v_mfma_f32_32x32x16_bf16 v[32:47], v[56:59], v[68:71], v[32:47]
	ds_read_b128 v[56:59], v88 offset:192
	global_load_dwordx4 v[108:111], v[64:65], off offset:64
	global_load_dwordx4 v[96:99], v[64:65], off offset:96
	global_load_dwordx4 v[92:95], v[64:65], off offset:128
	global_load_dwordx4 v[84:87], v[64:65], off offset:160
	ds_read_b128 v[60:63], v88 offset:224
	global_load_dwordx4 v[88:91], v[64:65], off offset:192
	global_load_dwordx4 v[80:83], v[64:65], off offset:224
	s_waitcnt lgkmcnt(1)
	v_mfma_f32_32x32x16_bf16 v[32:47], v[52:55], v[56:59], v[32:47]
	s_waitcnt lgkmcnt(0)
	v_mfma_f32_32x32x16_bf16 v[32:47], v[48:51], v[60:63], v[32:47]
	v_lshl_add_u64 v[48:49], v[204:205], 0, s[38:39]
	global_load_dwordx4 v[76:79], v[48:49], off
	global_load_dwordx4 v[72:75], v[48:49], off offset:32
	global_load_dwordx4 v[68:71], v[48:49], off offset:64
	global_load_dwordx4 v[64:67], v[48:49], off offset:96
	global_load_dwordx4 v[60:63], v[48:49], off offset:128
	global_load_dwordx4 v[56:59], v[48:49], off offset:160
	global_load_dwordx4 v[52:55], v[48:49], off offset:192
	s_nop 0
	global_load_dwordx4 v[48:51], v[48:49], off offset:224
	s_waitcnt lgkmcnt(0)
	s_barrier
	v_add_u32_e32 v229, v221, v192
	ds_read_b128 v[242:245], v229 offset:17408
	ds_read_b128 v[246:249], v229 offset:17440
	s_waitcnt vmcnt(35) lgkmcnt(1)
	v_mfma_f32_32x32x16_bf16 v[32:47], v[242:245], v[136:139], v[32:47]
	ds_read_b128 v[242:245], v229 offset:17472
	s_ashr_i32 s71, s70, 31
	s_lshl_b64 s[38:39], s[70:71], 6
	s_add_i32 s50, s50, -1
	s_cmp_eq_u32 s82, s73
	s_waitcnt vmcnt(34) lgkmcnt(1)
	v_mfma_f32_32x32x16_bf16 v[32:47], v[246:249], v[128:131], v[32:47]
	s_waitcnt vmcnt(23) lgkmcnt(0)
	v_mfma_f32_32x32x16_bf16 v[32:47], v[242:245], v[120:123], v[32:47]
	ds_read_b128 v[242:245], v229 offset:17504
	s_waitcnt vmcnt(22) lgkmcnt(0)
	v_mfma_f32_32x32x16_bf16 v[32:47], v[242:245], v[112:115], v[32:47]
	v_lshl_add_u64 v[242:243], s[38:39], 0, v[196:197]
	v_or_b32_e32 v244, v242, v198
	v_mov_b32_e32 v245, v243
	v_lshlrev_b64 v[244:245], 11, v[244:245]
	v_lshl_add_u64 v[244:245], v[206:207], 0, v[244:245]
	s_mov_b32 s38, s82
	s_nop 5
	v_cvt_pk_bf16_f32 v32, v32, s0
	global_store_short v[244:245], v32, off
	v_cvt_pk_bf16_f32 v229, v33, s0
	v_or_b32_e32 v32, v242, v208
	v_mov_b32_e32 v33, v243
	v_lshlrev_b64 v[32:33], 11, v[32:33]
	v_lshl_add_u64 v[32:33], v[206:207], 0, v[32:33]
	global_store_short v[32:33], v229, off
	v_or_b32_e32 v32, v242, v210
	v_mov_b32_e32 v33, v243
	v_lshlrev_b64 v[32:33], 11, v[32:33]
	v_cvt_pk_bf16_f32 v34, v34, s0
	v_lshl_add_u64 v[32:33], v[206:207], 0, v[32:33]
	global_store_short v[32:33], v34, off
	v_or_b32_e32 v32, v242, v212
	v_mov_b32_e32 v33, v243
	v_lshlrev_b64 v[32:33], 11, v[32:33]
	v_cvt_pk_bf16_f32 v34, v35, s0
	v_lshl_add_u64 v[32:33], v[206:207], 0, v[32:33]
	global_store_short v[32:33], v34, off
	v_or_b32_e32 v32, v242, v214
	v_mov_b32_e32 v33, v243
	v_lshlrev_b64 v[32:33], 11, v[32:33]
	v_cvt_pk_bf16_f32 v34, v36, s0
	v_lshl_add_u64 v[32:33], v[206:207], 0, v[32:33]
	v_mfma_f32_32x32x16_bf16 v[0:15], v[172:175], v[136:139], v[0:15]
	global_store_short v[32:33], v34, off
	v_or_b32_e32 v32, v242, v216
	v_mov_b32_e32 v33, v243
	v_lshlrev_b64 v[32:33], 11, v[32:33]
	v_cvt_pk_bf16_f32 v34, v37, s0
	v_lshl_add_u64 v[32:33], v[206:207], 0, v[32:33]
	global_store_short v[32:33], v34, off
	s_waitcnt vmcnt(25)
; #define MFMA32(a, b, c) __builtin_amdgcn_mfma_f32_32x32x16_bf16((a), (b), (c), 0, 0, 0)
; DI void lds_barrier() { asm volatile("s_waitcnt lgkmcnt(0)\n\ts_barrier" ::: "memory"); }
; DI unsigned pk_bf16(float lo, float hi) { f32x2 v = {lo, hi}; bf16v2 b = __builtin_convertvector(v, bf16v2); return __builtin_bit_cast(unsigned, b); }
; DI bf16_t f2bf(float x) { return (bf16_t)(pk_bf16(x, 0.f) & 0xffffu); }
; DI int crow(int r, int h) { return (r & 3) + 8 * (r >> 2) + 4 * h; }
; DI void gla_scan_unit(const Params& p, int g, int u, char* smem) {
;     ...
;       for (int r = 0; r < 16; ++r) od[(tokb + crow(r, h)) * 1024 + head * 256 + slice * 64 + wd * 32 + l31] = f2bf(o[r]);
;     }
; #pragma unroll
;     for (int t = 0; t < 2; ++t) {
; #pragma unroll
;       for (int s = 0; s < 4; ++s) Sacc[t] = MFMA32(ktf[t][s], vf[s], Sacc[t]);
; #pragma unroll
;       for (int q4 = 0; q4 < 4; ++q4)
; #pragma unroll
;         for (int e = 0; e < 4; ++e) Sacc[t][4 * q4 + e] *= ev[t][q4][e];
;     }
;     lds_barrier();
; #pragma unroll
;     for (int t = 0; t < 2; ++t) {
;       const int dkb = 2 * wi + t;
; #pragma unroll
;       for (int q4 = 0; q4 < 4; ++q4) {
;         u32x2 w; w.x = pk_bf16(Sacc[t][4 * q4], Sacc[t][4 * q4 + 1]); w.y = pk_bf16(Sacc[t][4 * q4 + 2], Sacc[t][4 * q4 + 3]);
;         *(u32x2*)(St + (wd * 32 + l31) * 136 + dkb * 32 + 8 * q4 + 4 * h) = w;
;       }
;     }
;     lds_barrier();
	v_mfma_f32_32x32x16_bf16 v[16:31], v[140:143], v[136:139], v[16:31]
	v_or_b32_e32 v32, v242, v218
	v_mov_b32_e32 v33, v243
	v_lshlrev_b64 v[32:33], 11, v[32:33]
	v_cvt_pk_bf16_f32 v34, v38, s0
	v_lshl_add_u64 v[32:33], v[206:207], 0, v[32:33]
	global_store_short v[32:33], v34, off
	v_or_b32_e32 v32, v242, v220
	v_mov_b32_e32 v33, v243
	v_lshlrev_b64 v[32:33], 11, v[32:33]
	v_mfma_f32_32x32x16_bf16 v[0:15], v[168:171], v[128:131], v[0:15]
	v_cvt_pk_bf16_f32 v34, v39, s0
	v_lshl_add_u64 v[32:33], v[206:207], 0, v[32:33]
	global_store_short v[32:33], v34, off
	v_or_b32_e32 v32, v242, v222
	v_mov_b32_e32 v33, v243
	v_lshlrev_b64 v[32:33], 11, v[32:33]
	v_cvt_pk_bf16_f32 v34, v40, s0
	s_waitcnt vmcnt(26)
	v_mfma_f32_32x32x16_bf16 v[16:31], v[132:135], v[128:131], v[16:31]
	v_lshl_add_u64 v[32:33], v[206:207], 0, v[32:33]
	global_store_short v[32:33], v34, off
	v_or_b32_e32 v32, v242, v224
	v_mov_b32_e32 v33, v243
	v_lshlrev_b64 v[32:33], 11, v[32:33]
	v_cvt_pk_bf16_f32 v34, v41, s0
	v_lshl_add_u64 v[32:33], v[206:207], 0, v[32:33]
	global_store_short v[32:33], v34, off
	v_or_b32_e32 v32, v242, v226
	v_mov_b32_e32 v33, v243
	v_mfma_f32_32x32x16_bf16 v[0:15], v[164:167], v[120:123], v[0:15]
	v_lshlrev_b64 v[32:33], 11, v[32:33]
	v_cvt_pk_bf16_f32 v34, v42, s0
	v_lshl_add_u64 v[32:33], v[206:207], 0, v[32:33]
	global_store_short v[32:33], v34, off
	v_or_b32_e32 v32, v242, v228
	v_mov_b32_e32 v33, v243
	v_lshlrev_b64 v[32:33], 11, v[32:33]
	s_waitcnt vmcnt(28)
	v_mfma_f32_32x32x16_bf16 v[16:31], v[124:127], v[120:123], v[16:31]
	v_cvt_pk_bf16_f32 v34, v43, s0
	v_lshl_add_u64 v[32:33], v[206:207], 0, v[32:33]
	global_store_short v[32:33], v34, off
	v_or_b32_e32 v32, v242, v230
	v_mov_b32_e32 v33, v243
	v_lshlrev_b64 v[32:33], 11, v[32:33]
	v_cvt_pk_bf16_f32 v34, v44, s0
	v_lshl_add_u64 v[32:33], v[206:207], 0, v[32:33]
	v_mfma_f32_32x32x16_bf16 v[0:15], v[160:163], v[112:115], v[0:15]
	global_store_short v[32:33], v34, off
	v_or_b32_e32 v32, v242, v232
	v_mov_b32_e32 v33, v243
	v_lshlrev_b64 v[32:33], 11, v[32:33]
	v_cvt_pk_bf16_f32 v34, v45, s0
	v_lshl_add_u64 v[32:33], v[206:207], 0, v[32:33]
	global_store_short v[32:33], v34, off
	s_waitcnt vmcnt(30)
	v_mfma_f32_32x32x16_bf16 v[16:31], v[116:119], v[112:115], v[16:31]
	v_or_b32_e32 v32, v242, v234
	v_mov_b32_e32 v33, v243
	v_lshlrev_b64 v[32:33], 11, v[32:33]
	v_cvt_pk_bf16_f32 v34, v46, s0
	v_lshl_add_u64 v[32:33], v[206:207], 0, v[32:33]
	v_or_b32_e32 v242, v242, v236
	global_store_short v[32:33], v34, off
	v_lshlrev_b64 v[32:33], 11, v[242:243]
	v_cvt_pk_bf16_f32 v34, v47, s0
	v_lshl_add_u64 v[32:33], v[206:207], 0, v[32:33]
	v_pk_mul_f32 v[0:1], v[188:189], v[0:1]
	v_pk_mul_f32 v[2:3], v[190:191], v[2:3]
	v_pk_mul_f32 v[4:5], v[184:185], v[4:5]
	v_pk_mul_f32 v[6:7], v[186:187], v[6:7]
	global_store_short v[32:33], v34, off
	v_pk_mul_f32 v[8:9], v[180:181], v[8:9]
	v_pk_mul_f32 v[10:11], v[182:183], v[10:11]
	v_pk_mul_f32 v[12:13], v[176:177], v[12:13]
	v_pk_mul_f32 v[14:15], v[178:179], v[14:15]
	v_cvt_pk_bf16_f32 v32, v0, v1
	v_cvt_pk_bf16_f32 v33, v2, v3
	v_cvt_pk_bf16_f32 v34, v4, v5
	v_cvt_pk_bf16_f32 v35, v6, v7
	v_pk_mul_f32 v[16:17], v[156:157], v[16:17]
	v_pk_mul_f32 v[18:19], v[158:159], v[18:19]
	v_pk_mul_f32 v[20:21], v[152:153], v[20:21]
	v_pk_mul_f32 v[22:23], v[154:155], v[22:23]
	s_waitcnt lgkmcnt(0)
	s_barrier
	ds_write2_b64 v227, v[32:33], v[34:35] offset1:2
	v_cvt_pk_bf16_f32 v32, v8, v9
	v_cvt_pk_bf16_f32 v33, v10, v11
	v_cvt_pk_bf16_f32 v34, v12, v13
	v_cvt_pk_bf16_f32 v35, v14, v15
	v_pk_mul_f32 v[24:25], v[148:149], v[24:25]
	v_pk_mul_f32 v[26:27], v[150:151], v[26:27]
	v_pk_mul_f32 v[28:29], v[144:145], v[28:29]
	v_pk_mul_f32 v[30:31], v[146:147], v[30:31]
	ds_write2_b64 v227, v[32:33], v[34:35] offset0:4 offset1:6
	v_cvt_pk_bf16_f32 v32, v16, v17
	v_cvt_pk_bf16_f32 v33, v18, v19
	v_cvt_pk_bf16_f32 v34, v20, v21
	v_cvt_pk_bf16_f32 v35, v22, v23
	ds_write2_b64 v227, v[32:33], v[34:35] offset0:8 offset1:10
	v_cvt_pk_bf16_f32 v32, v24, v25
	v_cvt_pk_bf16_f32 v33, v26, v27
	v_cvt_pk_bf16_f32 v34, v28, v29
	v_cvt_pk_bf16_f32 v35, v30, v31
	ds_write2_b64 v227, v[32:33], v[34:35] offset0:12 offset1:14
	s_waitcnt lgkmcnt(0)
	s_barrier
	s_cbranch_scc0 .LBB0_314
	s_branch .LBB0_245
; DI void attn_item(const Params& p, int g, int seq, int hd, int qt, int m, char* smem, int split_j, int sub) {
;     ...
;   const bf16_t* vsrc = vaT + (size_t)(hd * 512 + (sb >> 5)) * 4096 + tid * 8;
;   const int npairs = (split_j < 0) ? (S >> 6) : (S >> 6) / SPLIT_SP;
;   const int tbase = (split_j < 0) ? 0 : split_j * npairs * 2;
;   const int qw0 = q0 + wave * 32;
;   bf16x8 qf[4];
; #pragma unroll
;   for (int s = 0; s < 4; ++s) qf[s] = *(const bf16x8*)(qrow + m * 64 + s * 16);
;   f32x16 O[4];
; #pragma unroll
;   for (int dt = 0; dt < 4; ++dt)
; #pragma unroll
;     for (int r = 0; r < 16; ++r) O[dt][r] = 0.f;
;   f32x2 ls2 = {0.f, 0.f};
;   int region = 0;
;   const bf16_t* ksrc = (const bf16_t*)(p.ws + OFF_KBLK) + (size_t)((hd * 2 + m) * 512 + (sb >> 5)) * 2048 + tid * 8;
;   u32x4 rkA, rvA0, rvA1, rkB, rvB0, rvB1;
;   auto load_tile = [&](int t, u32x4& k, u32x4& v0, u32x4& v1) __attribute__((always_inline)) {
;     k = *(const u32x4*)(ksrc + (size_t)(tbase + t) * 2048);
;     v0 = *(const u32x4*)(vsrc + (size_t)(tbase + t) * 4096); v1 = *(const u32x4*)(vsrc + (size_t)(tbase + t) * 4096 + 2048);
;   };
;     ...
;   load_tile(0, rkA, rvA0, rvA1);
;   load_tile(1, rkB, rvB0, rvB1);
;   __syncthreads();
;   store_tile(0, rkA, rvA0, rvA1);
;   store_tile(1, rkB, rvB0, rvB1);
;   __syncthreads();
.LBB0_315:
	s_or_b64 exec, exec, s[6:7]
	v_readlane_b32 s0, v231, 28
	s_sub_i32 s0, s12, s0
	s_ashr_i32 s8, s0, 1
	s_abs_i32 s1, s8
	v_readlane_b32 s6, v231, 44
	s_mul_hi_u32 s6, s1, s6
	v_readlane_b32 s10, v231, 45
	s_mul_i32 s7, s6, s10
	s_sub_i32 s1, s1, s7
	s_ashr_i32 s0, s8, 31
	s_add_i32 s7, s6, 1
	s_sub_i32 s9, s1, s10
	s_cmp_ge_u32 s1, s10
	s_cselect_b32 s6, s7, s6
	s_cselect_b32 s1, s9, s1
	s_add_i32 s7, s6, 1
	s_cmp_ge_u32 s1, s10
	s_cselect_b32 s1, s7, s6
	s_xor_b32 s1, s1, s0
	s_sub_i32 s9, s1, s0
	v_readlane_b32 s6, v231, 37
	s_mul_i32 s0, s9, s10
	s_lshl_b32 s10, s9, s6
	v_readlane_b32 s6, v233, 14
	s_sub_i32 s0, s8, s0
	v_readlane_b32 s7, v233, 15
	s_lshl_b32 s0, s0, 7
	s_nop 3
	global_load_dword v1, v193, s[6:7] offset:480
	global_load_dword v8, v193, s[6:7] offset:992
	s_ashr_i32 s6, s13, 1
	s_and_b32 s1, s12, 1
	s_add_i32 s0, s0, s10
	s_and_b32 s11, s6, 0xffffffe0
	s_lshl_b32 s6, s10, 8
	v_readlane_b32 s13, v233, 13
	s_add_i32 s0, s0, s11
	v_lshlrev_b32_e32 v2, 3, v0
	s_add_i32 s6, s6, s13
	s_lshl_b32 s50, s1, 7
	v_ashrrev_i32_e32 v3, 31, v2
	s_add_u32 s6, s60, s6
	s_addc_u32 s7, s61, 0
	v_lshlrev_b64 v[4:5], 1, v[2:3]
	v_lshl_add_u64 v[170:171], s[6:7], 0, v[4:5]
	s_lshl_b32 s6, s1, 21
	s_lshl_b32 s7, s10, 7
	s_or_b32 s6, s6, s13
	s_add_i32 s6, s6, s7
	v_readlane_b32 s14, v233, 18
	v_readlane_b32 s15, v233, 19
	s_add_u32 s6, s14, s6
	s_addc_u32 s7, s15, 0
	v_lshl_add_u64 v[172:173], s[6:7], 0, v[4:5]
	v_add_co_u32_e32 v4, vcc, s75, v170
	s_movk_i32 s6, 0x3000
	s_nop 0
	v_addc_co_u32_e32 v5, vcc, 0, v171, vcc
	v_add_co_u32_e32 v6, vcc, s81, v172
	global_load_dwordx4 v[96:99], v[172:173], off
	global_load_dwordx4 v[100:103], v[170:171], off
	v_addc_co_u32_e32 v7, vcc, 0, v173, vcc
	global_load_dwordx4 v[124:127], v[6:7], off
	global_load_dwordx4 v[120:123], v[4:5], off offset:-4096
	global_load_dwordx4 v[128:131], v[4:5], off
	v_add_co_u32_e32 v4, vcc, s6, v170
	v_readlane_b32 s6, v233, 16
	s_nop 0
	v_addc_co_u32_e32 v5, vcc, 0, v171, vcc
	v_and_b32_e32 v168, 31, v0
	v_readlane_b32 s7, v233, 17
	global_load_dwordx4 v[132:135], v[4:5], off
	v_bfe_u32 v188, v0, 5, 1
	v_mov_b64_e32 v[4:5], s[6:7]
	v_or_b32_e32 v3, s0, v168
	v_lshlrev_b32_e32 v192, 4, v188
	v_mad_i64_i32 v[4:5], s[6:7], v3, s2, v[4:5]
	v_lshl_add_u64 v[4:5], v[4:5], 0, v[192:193]
	v_lshl_add_u64 v[4:5], v[4:5], 0, s[50:51]
	global_load_dwordx4 v[104:107], v[4:5], off
	global_load_dwordx4 v[108:111], v[4:5], off offset:32
	global_load_dwordx4 v[112:115], v[4:5], off offset:64
	global_load_dwordx4 v[116:119], v[4:5], off offset:96
	v_lshrrev_b32_e32 v3, 2, v0
	v_lshrrev_b32_e32 v4, 3, v0
	v_lshlrev_b32_e32 v0, 4, v0
	v_mul_lo_u32 v4, v4, s22
	v_and_b32_e32 v0, 0x70, v0
	s_lshl_b32 s7, s8, 7
	v_mul_u32_u24_e32 v5, 40, v168
	v_add3_u32 v169, 32, v4, v0
	v_add_u32_e32 v0, 32, v192
	s_add_i32 s8, s7, s11
	v_and_b32_e32 v2, 24, v2
	v_mul_lo_u32 v3, v3, 40
	v_mad_u32_u24 v191, v168, s22, v0
	v_lshl_add_u32 v196, v5, 1, v0
	v_or_b32_e32 v0, s8, v168
	v_readlane_b32 s8, v231, 46
	v_lshlrev_b32_e32 v189, 1, v3
	v_lshlrev_b32_e32 v190, 1, v2
	s_mul_i32 s8, s8, s9
	v_add3_u32 v2, 32, v189, v190
	v_sub_u32_e32 v0, s8, v0
	v_mov_b32_e32 v14, v193
	v_mov_b32_e32 v15, v193
	s_waitcnt lgkmcnt(0)
	s_barrier
	s_waitcnt vmcnt(11)
	v_mul_f32_e32 v1, 0x3fb8aa3b, v1
	v_exp_f32_e32 v174, v1
	s_waitcnt vmcnt(10)
	v_mul_f32_e32 v1, 0xbfb8aa3b, v8
	v_exp_f32_e32 v176, v1
	v_lshl_add_u32 v197, v188, 2, v0
	s_waitcnt vmcnt(9)
	ds_write_b128 v169, v[96:99]
	s_waitcnt vmcnt(8)
	ds_write_b128 v2, v[100:103] offset:18432
	s_waitcnt vmcnt(6)
	ds_write_b128 v2, v[120:123] offset:23552
	ds_write_b128 v169, v[124:127] offset:4608
	s_waitcnt vmcnt(5)
	ds_write_b128 v2, v[128:131] offset:28672
	s_waitcnt vmcnt(4)
	ds_write_b128 v2, v[132:135] offset:33792
	s_sub_i32 s8, s8, s11
	v_mov_b32_e32 v192, v193
	v_mov_b32_e32 v0, v193
	v_mov_b32_e32 v1, v193
	v_mov_b32_e32 v2, v193
	v_mov_b32_e32 v3, v193
	v_mov_b32_e32 v4, v193
	v_mov_b32_e32 v5, v193
	v_mov_b32_e32 v6, v193
	v_mov_b32_e32 v7, v193
	v_mov_b32_e32 v8, v193
	v_mov_b32_e32 v9, v193
	v_mov_b32_e32 v10, v193
	v_mov_b32_e32 v11, v193
	v_mov_b32_e32 v12, v193
	v_mov_b32_e32 v13, v193
	v_mov_b64_e32 v[30:31], v[14:15]
	v_mov_b64_e32 v[46:47], v[14:15]
	v_mov_b64_e32 v[62:63], v[14:15]
	s_mov_b32 s6, 3
	s_mov_b32 s13, 0
	v_mov_b32_e32 v178, v174
	v_mov_b32_e32 v179, v174
	v_mov_b32_e32 v180, v176
	v_mov_b32_e32 v181, v176
	v_mov_b32_e32 v182, v174
	v_mov_b32_e32 v183, v174
	v_mov_b32_e32 v184, v176
	v_mov_b32_e32 v185, v176
	s_sub_i32 s14, s8, s7
	v_mov_b64_e32 v[28:29], v[12:13]
	v_mov_b64_e32 v[26:27], v[10:11]
	v_mov_b64_e32 v[24:25], v[8:9]
	v_mov_b64_e32 v[22:23], v[6:7]
	v_mov_b64_e32 v[20:21], v[4:5]
	v_mov_b64_e32 v[18:19], v[2:3]
	v_mov_b64_e32 v[16:17], v[0:1]
	v_mov_b64_e32 v[44:45], v[12:13]
	v_mov_b64_e32 v[42:43], v[10:11]
	v_mov_b64_e32 v[40:41], v[8:9]
	v_mov_b64_e32 v[38:39], v[6:7]
	v_mov_b64_e32 v[36:37], v[4:5]
	v_mov_b64_e32 v[34:35], v[2:3]
	v_mov_b64_e32 v[32:33], v[0:1]
	v_mov_b64_e32 v[60:61], v[12:13]
	v_mov_b64_e32 v[58:59], v[10:11]
	v_mov_b64_e32 v[56:57], v[8:9]
	v_mov_b64_e32 v[54:55], v[6:7]
	v_mov_b64_e32 v[52:53], v[4:5]
	v_mov_b64_e32 v[50:51], v[2:3]
	v_mov_b64_e32 v[48:49], v[0:1]
	s_mov_b32 s15, 0
	s_mov_b32 s17, 0
	v_mov_b64_e32 v[186:187], v[192:193]
	s_waitcnt vmcnt(0) lgkmcnt(0)
	s_barrier
	s_branch .LBB0_317

; #define MFMA32(a, b, c) __builtin_amdgcn_mfma_f32_32x32x16_bf16((a), (b), (c), 0, 0, 0)
; DI int crow(int r, int h) { return (r & 3) + 8 * (r >> 2) + 4 * h; }
; DI void attn_item(const Params& p, int g, int seq, int hd, int qt, int m, char* smem, int split_j, int sub) {
;     ...
;   auto compute = [&](int st, int buf) __attribute__((always_inline)) {
;     const int k0 = (tbase + st) * 32, h = h_, l31 = l31_;
;     const bf16_t* Kb = Ks + buf * 32 * 72; const bf16_t* Vb = Vs + buf * 128 * 40;
;     const int rmin = k0 - (qw0 + 31), rmax = k0 + 31 - qw0;
;     const bool farL = rmax <= -128, farR = rmin >= 128;
;     if (!farL && region == 0) { rescale(__builtin_amdgcn_exp2f(cneg)); region = 1; }
;     if (farR && region == 1) { rescale(__builtin_amdgcn_exp2f(-cpos)); region = 2; }
;     bf16x8 kf[4], vf[2][4];
; #pragma unroll
;     for (int s = 0; s < 4; ++s) kf[s] = *(const bf16x8*)(Kb + l31 * 72 + s * 16 + h * 8);
; #pragma unroll
;     for (int s2 = 0; s2 < 2; ++s2)
; #pragma unroll
;       for (int dt = 0; dt < 4; ++dt) vf[s2][dt] = *(const bf16x8*)(Vb + (dt * 32 + l31) * 40 + s2 * 16 + h * 8);
;     __builtin_amdgcn_sched_barrier(0);
;     f32x16 X;
; #pragma unroll
;     for (int r = 0; r < 16; ++r) X[r] = 0.f;
; #pragma unroll
;     for (int s = 0; s < 4; ++s) X = MFMA32(kf[s], qf[s], X);
;     if (farL || farR) {
; #pragma unroll
;       for (int r = 0; r < 16; ++r) X[r] = __builtin_amdgcn_exp2f(X[r]);
;     } else {
;       const int rel0 = k0 - (qw0 + l31) + 128;
; #pragma unroll
;       for (int r = 0; r < 16; ++r) { int idx = rel0 + crow(r, h); idx = idx < 0 ? 0 : (idx > 256 ? 256 : idx); X[r] = __builtin_amdgcn_exp2f(X[r] + tab[idx]); }
;     }
.LBB0_323:
	s_add_i32 s10, s6, -3
	s_and_b32 s16, s10, 2
	s_mul_i32 s10, s16, 0x1200
	s_mul_i32 s18, s16, 0x2800
	v_add_u32_e32 v192, s10, v191
	v_add_u32_e32 v68, s18, v196
	ds_read_b128 v[64:67], v192
	ds_read_b128 v[80:83], v192 offset:32
	ds_read_b128 v[84:87], v192 offset:64
	ds_read_b128 v[88:91], v192 offset:96
	ds_read_b128 v[156:159], v68 offset:18432
	ds_read_b128 v[148:151], v68 offset:18464
	ds_read_b128 v[160:163], v68 offset:20992
	ds_read_b128 v[144:147], v68 offset:21024
	ds_read_b128 v[164:167], v68 offset:23552
	ds_read_b128 v[136:139], v68 offset:23584
	ds_read_b128 v[152:155], v68 offset:26112
	ds_read_b128 v[140:143], v68 offset:26144
	s_waitcnt lgkmcnt(11)
	v_mfma_f32_32x32x16_bf16 v[64:79], v[64:67], v[104:107], 0
	s_add_i32 s10, s7, 0xffffff61
	s_cmp_gt_u32 s10, 0xfffffec2
	s_waitcnt lgkmcnt(10)
	v_mfma_f32_32x32x16_bf16 v[64:79], v[80:83], v[108:111], v[64:79]
	s_waitcnt lgkmcnt(9)
	v_mfma_f32_32x32x16_bf16 v[64:79], v[84:87], v[112:115], v[64:79]
	s_waitcnt lgkmcnt(8)
	v_mfma_f32_32x32x16_bf16 v[64:79], v[88:91], v[116:119], v[64:79]
	s_cbranch_scc0 .LBB0_325
	v_add_u32_e32 v88, s13, v197
	v_add_u32_e32 v80, 0x80, v88
	v_add_u32_e32 v81, 0x81, v88
	v_add_u32_e32 v82, 0x82, v88
	v_add_u32_e32 v83, 0x83, v88
	v_add_u32_e32 v84, 0x88, v88
	v_add_u32_e32 v85, 0x89, v88
	v_add_u32_e32 v86, 0x8a, v88
	v_add_u32_e32 v87, 0x8b, v88
	v_med3_i32 v80, v80, 0, v215
	v_med3_i32 v81, v81, 0, v215
	v_med3_i32 v82, v82, 0, v215
	v_med3_i32 v83, v83, 0, v215
	v_med3_i32 v84, v84, 0, v215
	v_med3_i32 v85, v85, 0, v215
	v_med3_i32 v86, v86, 0, v215
	v_med3_i32 v87, v87, 0, v215
	v_add_u32_e32 v89, 0x90, v88
	v_add_u32_e32 v90, 0x91, v88
	v_add_u32_e32 v91, 0x92, v88
	v_add_u32_e32 v92, 0x93, v88
	v_add_u32_e32 v93, 0x98, v88
	v_add_u32_e32 v94, 0x99, v88
	v_add_u32_e32 v95, 0x9a, v88
	v_lshl_add_u32 v80, v80, 2, 32
	v_lshl_add_u32 v81, v81, 2, 32
	v_lshl_add_u32 v82, v82, 2, 32
	v_lshl_add_u32 v83, v83, 2, 32
	v_lshl_add_u32 v84, v84, 2, 32
	v_lshl_add_u32 v85, v85, 2, 32
	v_lshl_add_u32 v86, v86, 2, 32
	v_lshl_add_u32 v87, v87, 2, 32
	v_med3_i32 v89, v89, 0, v215
	v_med3_i32 v90, v90, 0, v215
	v_med3_i32 v91, v91, 0, v215
	v_med3_i32 v92, v92, 0, v215
	v_med3_i32 v93, v93, 0, v215
	v_med3_i32 v94, v94, 0, v215
	v_med3_i32 v95, v95, 0, v215
	v_add_u32_e32 v88, 0x9b, v88
	ds_read_b32 v80, v80 offset:59392
	ds_read_b32 v81, v81 offset:59392
	ds_read_b32 v82, v82 offset:59392
	ds_read_b32 v83, v83 offset:59392
	ds_read_b32 v84, v84 offset:59392
	ds_read_b32 v85, v85 offset:59392
	ds_read_b32 v86, v86 offset:59392
	ds_read_b32 v87, v87 offset:59392
	v_lshl_add_u32 v89, v89, 2, 32
	v_lshl_add_u32 v90, v90, 2, 32
	v_lshl_add_u32 v91, v91, 2, 32
	v_lshl_add_u32 v92, v92, 2, 32
	v_lshl_add_u32 v93, v93, 2, 32
	v_lshl_add_u32 v94, v94, 2, 32
	v_lshl_add_u32 v95, v95, 2, 32
	v_med3_i32 v88, v88, 0, v215
	v_lshl_add_u32 v88, v88, 2, 32
	ds_read_b32 v89, v89 offset:59392
	ds_read_b32 v90, v90 offset:59392
	ds_read_b32 v91, v91 offset:59392
	ds_read_b32 v92, v92 offset:59392
	ds_read_b32 v93, v93 offset:59392
	ds_read_b32 v94, v94 offset:59392
	ds_read_b32 v95, v95 offset:59392
	ds_read_b32 v175, v88 offset:59392
	s_waitcnt lgkmcnt(14)
	v_add_f32_e32 v80, v64, v80
	v_add_f32_e32 v81, v65, v81
	s_waitcnt lgkmcnt(13)
	v_add_f32_e32 v82, v66, v82
	s_waitcnt lgkmcnt(12)
	v_add_f32_e32 v83, v67, v83
	s_waitcnt lgkmcnt(11)
	v_add_f32_e32 v84, v68, v84
	s_waitcnt lgkmcnt(10)
	v_add_f32_e32 v85, v69, v85
	s_waitcnt lgkmcnt(9)
	v_add_f32_e32 v86, v70, v86
	s_waitcnt lgkmcnt(8)
	v_add_f32_e32 v87, v71, v87
	s_waitcnt lgkmcnt(7)
	v_add_f32_e32 v88, v72, v89
	s_waitcnt lgkmcnt(6)
	v_add_f32_e32 v89, v73, v90
	s_waitcnt lgkmcnt(5)
	v_add_f32_e32 v90, v74, v91
	s_waitcnt lgkmcnt(4)
	v_add_f32_e32 v91, v75, v92
	s_waitcnt lgkmcnt(3)
	v_add_f32_e32 v92, v76, v93
	s_waitcnt lgkmcnt(2)
	v_add_f32_e32 v93, v77, v94
	s_waitcnt lgkmcnt(1)
	v_add_f32_e32 v94, v78, v95
	v_exp_f32_e32 v80, v80
	v_exp_f32_e32 v81, v81
	v_exp_f32_e32 v82, v82
	v_exp_f32_e32 v83, v83
	v_exp_f32_e32 v84, v84
	v_exp_f32_e32 v85, v85
	v_exp_f32_e32 v86, v86
	v_exp_f32_e32 v87, v87
	v_exp_f32_e32 v88, v88
	v_exp_f32_e32 v89, v89
	v_exp_f32_e32 v90, v90
	v_exp_f32_e32 v91, v91
	v_exp_f32_e32 v92, v92
	v_exp_f32_e32 v93, v93
	v_exp_f32_e32 v94, v94
	s_waitcnt lgkmcnt(0)
	v_add_f32_e32 v79, v79, v175
	s_cbranch_execz .LBB0_326
	s_branch .LBB0_327

; #define MFMA32(a, b, c) __builtin_amdgcn_mfma_f32_32x32x16_bf16((a), (b), (c), 0, 0, 0)
; DI unsigned pk_bf16(float lo, float hi) { f32x2 v = {lo, hi}; bf16v2 b = __builtin_convertvector(v, bf16v2); return __builtin_bit_cast(unsigned, b); }
; DI void attn_item(const Params& p, int g, int seq, int hd, int qt, int m, char* smem, int split_j, int sub) {
;     ...
;     bf16x8 pf[2];
; #pragma unroll
;     for (int s2 = 0; s2 < 2; ++s2) {
;       u32x4 w; w.x = pk_bf16(X[8 * s2], X[8 * s2 + 1]); w.y = pk_bf16(X[8 * s2 + 2], X[8 * s2 + 3]); w.z = pk_bf16(X[8 * s2 + 4], X[8 * s2 + 5]); w.w = pk_bf16(X[8 * s2 + 6], X[8 * s2 + 7]);
;       ls2 += (f32x2){X[8 * s2], X[8 * s2 + 1]}; ls2 += (f32x2){X[8 * s2 + 2], X[8 * s2 + 3]};
;       ls2 += (f32x2){X[8 * s2 + 4], X[8 * s2 + 5]}; ls2 += (f32x2){X[8 * s2 + 6], X[8 * s2 + 7]};
;       pf[s2] = __builtin_bit_cast(bf16x8, w);
;     }
; #pragma unroll
;     for (int s2 = 0; s2 < 2; ++s2)
; #pragma unroll
;       for (int dt = 0; dt < 4; ++dt) O[dt] = MFMA32(pf[s2], vf[s2][dt], O[dt]);
;   };
;   load_tile(0, rkA, rvA0, rvA1);
;   load_tile(1, rkB, rvB0, rvB1);
;   __syncthreads();
;   store_tile(0, rkA, rvA0, rvA1);
;   store_tile(1, rkB, rvB0, rvB1);
;   __syncthreads();
;   for (int it = 0; it < npairs; ++it) {
;     const int set = it & 1;
;     if (it + 1 < npairs) { load_tile(2 * it + 2, rkA, rvA0, rvA1); load_tile(2 * it + 3, rkB, rvB0, rvB1); }
;     compute(2 * it, 2 * set);
;     compute(2 * it + 1, 2 * set + 1);
;     if (it + 1 < npairs) { store_tile(2 * (set ^ 1), rkA, rvA0, rvA1); store_tile(2 * (set ^ 1) + 1, rkB, rvB0, rvB1); }
.LBB0_335:
	v_cvt_pk_bf16_f32 v80, v64, v65
	v_cvt_pk_bf16_f32 v81, v66, v67
	v_cvt_pk_bf16_f32 v82, v68, v69
	v_cvt_pk_bf16_f32 v83, v70, v71
	v_exp_f32_e32 v79, v95
	v_cvt_pk_bf16_f32 v84, v72, v73
	s_waitcnt lgkmcnt(7)
	v_mfma_f32_32x32x16_bf16 v[48:63], v[80:83], v[156:159], v[48:63]
	v_cvt_pk_bf16_f32 v85, v74, v75
	v_cvt_pk_bf16_f32 v86, v76, v77
	v_cvt_pk_bf16_f32 v87, v78, v79
	s_andn2_b64 vcc, exec, s[8:9]
	s_waitcnt lgkmcnt(5)
	v_mfma_f32_32x32x16_bf16 v[32:47], v[80:83], v[160:163], v[32:47]
	s_waitcnt lgkmcnt(3)
	v_mfma_f32_32x32x16_bf16 v[16:31], v[80:83], v[164:167], v[16:31]
	s_waitcnt lgkmcnt(1)
	v_mfma_f32_32x32x16_bf16 v[0:15], v[80:83], v[152:155], v[0:15]
	v_mfma_f32_32x32x16_bf16 v[48:63], v[84:87], v[136:139], v[48:63]
	v_mfma_f32_32x32x16_bf16 v[32:47], v[84:87], v[140:143], v[32:47]
	v_mfma_f32_32x32x16_bf16 v[16:31], v[84:87], v[144:147], v[16:31]
	s_waitcnt lgkmcnt(0)
	v_mfma_f32_32x32x16_bf16 v[0:15], v[84:87], v[148:151], v[0:15]
	s_cbranch_vccnz .LBB0_316
	s_xor_b32 s7, s16, 2
	s_mul_i32 s8, s7, 0x2800
	s_add_i32 s8, s8, 32
	s_mulk_i32 s7, 0x1200
	v_add_u32_e32 v80, s7, v169
	v_add3_u32 v81, s8, v189, v190
	s_addk_i32 s8, 0x2800
	s_waitcnt vmcnt(5)
	ds_write_b128 v80, v[96:99]
	s_waitcnt vmcnt(4)
	ds_write_b128 v81, v[100:103] offset:18432
	s_waitcnt vmcnt(3)
	ds_write_b128 v81, v[120:123] offset:23552
	s_waitcnt vmcnt(2)
	ds_write_b128 v80, v[124:127] offset:4608
	v_add3_u32 v80, s8, v189, v190
	s_waitcnt vmcnt(1)
	ds_write_b128 v80, v[128:131] offset:18432
	s_waitcnt vmcnt(0)
	ds_write_b128 v80, v[132:135] offset:23552
	s_branch .LBB0_316

; DI float bf2f(bf16_t v) { return __uint_as_float(((unsigned)v) << 16); }
; DI void phase_gla_prep(const Params& p, int g, char* smem, int bid, int nb) {
;     ...
;   for (int item = bid; item < 2048; item += nb) {
;     const int c = item & 255, head = (item >> 8) & 3, dir = item >> 10, dd = head * 128 + d;
;     __syncthreads();
; #pragma unroll
;     for (int i = 0; i < 4; ++i) { const int idx = tid + 256 * i; lrs[idx] = lrb[(size_t)(c * 64 + (idx >> 4)) * 32 + dir * 16 + (idx & 15)]; }
;     const float* wgp = dir ? p.w_gate_b : p.w_gate_f;
;     float wg[16];
; #pragma unroll
;     for (int r = 0; r < 16; ++r) wg[r] = wgp[r * 512 + dd];
;     const float bg = (dir ? p.b_gate_b : p.b_gate_f)[dd];
;     __syncthreads();
;     ...
;       const size_t tg = (size_t)c * 64 + t;
;       const float qv = bf2f(proj[tg * NPROJ + PQG + dd]), kv = bf2f(proj[tg * NPROJ + PKG + dd]);
.Lgp_loop:
	s_and_b32 s10, s12, 0xff
	s_bfe_u32 s11, s12, 0x20008
	s_lshr_b32 s13, s12, 10
	s_lshl_b32 s0, s13, 2
	s_add_i32 s0, s0, s11
	s_lshl_b32 s0, s0, 8
	s_add_i32 s9, s0, s10
	v_readlane_b32 s16, v233, 26
	v_readlane_b32 s17, v233, 27
	s_lshl_b32 s0, s10, 13
	s_lshl_b32 s1, s13, 6
	s_add_i32 s0, s0, s1
	s_nop 1
	s_add_u32 s16, s16, s0
	s_addc_u32 s17, s17, 0
	v_readlane_b32 s18, v235, 29
	v_readlane_b32 s19, v235, 30
	v_readlane_b32 s0, v235, 33
	v_readlane_b32 s1, v235, 34
	v_readlane_b32 s20, v235, 31
	v_readlane_b32 s21, v235, 32
	v_readlane_b32 s22, v235, 35
	v_readlane_b32 s23, v235, 36
	s_nop 1
	s_cmp_eq_u32 s13, 0
	s_cselect_b32 s18, s18, s0
	s_cselect_b32 s19, s19, s1
	s_cselect_b32 s20, s20, s22
	s_cselect_b32 s21, s21, s23
	s_cselect_b64 s[6:7], -1, 0
	s_lshl_b32 s0, s11, 9
	s_add_u32 s18, s18, s0
	s_addc_u32 s19, s19, 0
	s_add_u32 s20, s20, s0
	s_addc_u32 s21, s21, 0
	s_mul_i32 s0, s10, 0xa0000
	s_lshl_b32 s1, s11, 8
	s_add_i32 s0, s0, s1
	s_add_u32 s22, s94, s0
	s_addc_u32 s23, s95, 0
	s_lshl_b32 s0, s9, 14
	s_add_u32 s24, s4, s0
	s_addc_u32 s25, s5, 0
	s_add_u32 s26, s68, s0
	s_addc_u32 s27, s69, 0
	v_readlane_b32 s28, v233, 20
	v_readlane_b32 s29, v233, 21
	v_readlane_b32 s30, v233, 22
	v_readlane_b32 s31, v233, 23
	s_nop 1
	s_add_u32 s28, s28, s0
	s_addc_u32 s29, s29, 0
	s_lshl_b32 s0, s9, 9
	s_add_u32 s30, s30, s0
	s_addc_u32 s31, s31, 0
	s_waitcnt lgkmcnt(0)
	s_barrier
	global_load_dword v33, v7, s[16:17]
	global_load_dword v34, v7, s[16:17] offset:2048
	global_load_dword v35, v8, s[16:17]
	global_load_dword v36, v8, s[16:17] offset:2048
	global_load_dword v16, v9, s[18:19]
	global_load_dword v17, v9, s[18:19] offset:2048
	s_add_u32 s18, s18, 0x1000
	s_addc_u32 s19, s19, 0
	global_load_dword v18, v9, s[18:19]
	global_load_dword v19, v9, s[18:19] offset:2048
	s_add_u32 s18, s18, 0x1000
	s_addc_u32 s19, s19, 0
	global_load_dword v20, v9, s[18:19]
	global_load_dword v21, v9, s[18:19] offset:2048
	s_add_u32 s18, s18, 0x1000
	s_addc_u32 s19, s19, 0
	global_load_dword v22, v9, s[18:19]
	global_load_dword v23, v9, s[18:19] offset:2048
	s_add_u32 s18, s18, 0x1000
	s_addc_u32 s19, s19, 0
	global_load_dword v24, v9, s[18:19]
	global_load_dword v25, v9, s[18:19] offset:2048
	s_add_u32 s18, s18, 0x1000
	s_addc_u32 s19, s19, 0
	global_load_dword v26, v9, s[18:19]
	global_load_dword v27, v9, s[18:19] offset:2048
	s_add_u32 s18, s18, 0x1000
	s_addc_u32 s19, s19, 0
	global_load_dword v28, v9, s[18:19]
	global_load_dword v29, v9, s[18:19] offset:2048
	s_add_u32 s18, s18, 0x1000
	s_addc_u32 s19, s19, 0
	global_load_dword v30, v9, s[18:19]
	global_load_dword v31, v9, s[18:19] offset:2048
	global_load_dword v32, v9, s[20:21]
	global_load_ushort v96, v4, s[22:23]
	global_load_ushort v144, v4, s[22:23] offset:1024
	s_add_u32 s22, s22, 0x2800
	s_addc_u32 s23, s23, 0
	global_load_ushort v97, v4, s[22:23]
	global_load_ushort v145, v4, s[22:23] offset:1024
	s_add_u32 s22, s22, 0x2800
	s_addc_u32 s23, s23, 0
	global_load_ushort v98, v4, s[22:23]
	global_load_ushort v146, v4, s[22:23] offset:1024
	s_add_u32 s22, s22, 0x2800
	s_addc_u32 s23, s23, 0
	global_load_ushort v99, v4, s[22:23]
	global_load_ushort v147, v4, s[22:23] offset:1024
	s_add_u32 s22, s22, 0x2800
	s_addc_u32 s23, s23, 0
	global_load_ushort v100, v4, s[22:23]
	global_load_ushort v148, v4, s[22:23] offset:1024
	s_add_u32 s22, s22, 0x2800
	s_addc_u32 s23, s23, 0
	global_load_ushort v101, v4, s[22:23]
	global_load_ushort v149, v4, s[22:23] offset:1024
	s_add_u32 s22, s22, 0x2800
	s_addc_u32 s23, s23, 0
	global_load_ushort v102, v4, s[22:23]
	global_load_ushort v150, v4, s[22:23] offset:1024
	s_add_u32 s22, s22, 0x2800
	s_addc_u32 s23, s23, 0
	global_load_ushort v103, v4, s[22:23]
	global_load_ushort v151, v4, s[22:23] offset:1024
	s_add_u32 s22, s22, 0x2800
	s_addc_u32 s23, s23, 0
	global_load_ushort v104, v4, s[22:23]
	global_load_ushort v152, v4, s[22:23] offset:1024
	s_add_u32 s22, s22, 0x2800
	s_addc_u32 s23, s23, 0
	global_load_ushort v105, v4, s[22:23]
	global_load_ushort v153, v4, s[22:23] offset:1024
	s_add_u32 s22, s22, 0x2800
	s_addc_u32 s23, s23, 0
	global_load_ushort v106, v4, s[22:23]
	global_load_ushort v154, v4, s[22:23] offset:1024
	s_add_u32 s22, s22, 0x2800
	s_addc_u32 s23, s23, 0
	global_load_ushort v107, v4, s[22:23]
	global_load_ushort v155, v4, s[22:23] offset:1024
	s_add_u32 s22, s22, 0x2800
	s_addc_u32 s23, s23, 0
	global_load_ushort v108, v4, s[22:23]
	global_load_ushort v156, v4, s[22:23] offset:1024
	s_add_u32 s22, s22, 0x2800
	s_addc_u32 s23, s23, 0
	global_load_ushort v109, v4, s[22:23]
	global_load_ushort v157, v4, s[22:23] offset:1024
	s_add_u32 s22, s22, 0x2800
	s_addc_u32 s23, s23, 0
	global_load_ushort v110, v4, s[22:23]
	global_load_ushort v158, v4, s[22:23] offset:1024
	s_add_u32 s22, s22, 0x2800
	s_addc_u32 s23, s23, 0
	global_load_ushort v111, v4, s[22:23]
	global_load_ushort v159, v4, s[22:23] offset:1024
	s_add_u32 s22, s22, 0x2800
	s_addc_u32 s23, s23, 0
	s_waitcnt vmcnt(49)
	ds_write_b32 v1, v33
	ds_write_b32 v1, v34 offset:1024
	ds_write_b32 v1, v35 offset:2048
	ds_write_b32 v1, v36 offset:3072
	s_waitcnt lgkmcnt(0)
	s_barrier
; DI float logsig16(float z) { return (fminf(z, 0.f) - __logf(1.f + __expf(-fabsf(z)))) * (1.f / 16.f); }
; DI void phase_gla_prep(const Params& p, int g, char* smem, int bid, int nb) {
;     ...
;     float tsum = 0.f;
;     for (int tt = 0; tt < 32; ++tt) {
;       const float* l = lrs + (half * 32 + tt) * 16; float z = bg;
; #pragma unroll
;       for (int r = 0; r < 16; ++r) z += l[r] * wg[r];
;       tsum += logsig16(z);
;     }
;     tot[half * 128 + d] = tsum;
;     ...
;     for (int tt = 0; tt < 32; ++tt) {
;       const int t = half * 32 + tt;
;       const float* l = lrs + t * 16; float z = bg;
; #pragma unroll
;       for (int r = 0; r < 16; ++r) z += l[r] * wg[r];
;       const float gv = logsig16(z);
	v_mov_b32_e32 v54, 0
	ds_read_b128 v[36:39], v2
	ds_read_b128 v[40:43], v2 offset:16
	ds_read_b128 v[44:47], v2 offset:32
	ds_read_b128 v[48:51], v2 offset:48
	ds_read_b128 v[176:179], v2 offset:64
	ds_read_b128 v[180:183], v2 offset:80
	ds_read_b128 v[184:187], v2 offset:96
	ds_read_b128 v[188:191], v2 offset:112
	s_waitcnt vmcnt(32)
	s_waitcnt lgkmcnt(4)
	v_fma_f32 v52, v16, v36, v32
	v_fmac_f32_e32 v52, v17, v37
	v_fmac_f32_e32 v52, v18, v38
	v_fmac_f32_e32 v52, v19, v39
	v_fmac_f32_e32 v52, v20, v40
	v_fmac_f32_e32 v52, v21, v41
	v_fmac_f32_e32 v52, v22, v42
	v_fmac_f32_e32 v52, v23, v43
	v_fmac_f32_e32 v52, v24, v44
	v_fmac_f32_e32 v52, v25, v45
	v_fmac_f32_e32 v52, v26, v46
	v_fmac_f32_e32 v52, v27, v47
	v_fmac_f32_e32 v52, v28, v48
	v_fmac_f32_e32 v52, v29, v49
	v_fmac_f32_e32 v52, v30, v50
	v_fmac_f32_e32 v52, v31, v51
	ds_read_b128 v[36:39], v2 offset:128
	ds_read_b128 v[40:43], v2 offset:144
	ds_read_b128 v[44:47], v2 offset:160
	ds_read_b128 v[48:51], v2 offset:176
	s_waitcnt lgkmcnt(4)
	v_fma_f32 v53, v16, v176, v32
	v_mul_f32_e64 v55, |v52|, s85
	v_fmac_f32_e32 v53, v17, v177
	v_exp_f32_e32 v55, v55
	v_fmac_f32_e32 v53, v18, v178
	v_min_f32_e32 v56, 0, v52
	v_fmac_f32_e32 v53, v19, v179
	v_add_f32_e32 v55, 1.0, v55
	v_fmac_f32_e32 v53, v20, v180
	v_log_f32_e32 v55, v55
	v_fmac_f32_e32 v53, v21, v181
	v_fmac_f32_e32 v53, v22, v182
	v_mul_f32_e32 v57, 0x3f317217, v55
	v_fmac_f32_e32 v53, v23, v183
	v_fma_f32 v58, v55, s74, -v57
	v_fmac_f32_e32 v53, v24, v184
	v_fmac_f32_e32 v58, 0x3377d1cf, v55
	v_fmac_f32_e32 v53, v25, v185
	v_fmac_f32_e32 v58, 0x3f317217, v55
	v_fmac_f32_e32 v53, v26, v186
	v_sub_f32_e32 v56, v56, v58
	v_fmac_f32_e32 v53, v27, v187
	v_mul_f32_e32 v64, 0x3d800000, v56
	v_fmac_f32_e32 v53, v28, v188
	v_add_f32_e32 v54, v54, v64
	v_fmac_f32_e32 v53, v29, v189
	v_fmac_f32_e32 v53, v30, v190
	v_fmac_f32_e32 v53, v31, v191
	ds_read_b128 v[176:179], v2 offset:192
	ds_read_b128 v[180:183], v2 offset:208
	ds_read_b128 v[184:187], v2 offset:224
	ds_read_b128 v[188:191], v2 offset:240
	s_waitcnt lgkmcnt(4)
	v_fma_f32 v52, v16, v36, v32
	v_mul_f32_e64 v55, |v53|, s85
	v_fmac_f32_e32 v52, v17, v37
	v_exp_f32_e32 v55, v55
	v_fmac_f32_e32 v52, v18, v38
	v_min_f32_e32 v56, 0, v53
	v_fmac_f32_e32 v52, v19, v39
	v_add_f32_e32 v55, 1.0, v55
	v_fmac_f32_e32 v52, v20, v40
	v_log_f32_e32 v55, v55
	v_fmac_f32_e32 v52, v21, v41
	v_fmac_f32_e32 v52, v22, v42
	v_mul_f32_e32 v57, 0x3f317217, v55
	v_fmac_f32_e32 v52, v23, v43
	v_fma_f32 v58, v55, s74, -v57
	v_fmac_f32_e32 v52, v24, v44
	v_fmac_f32_e32 v58, 0x3377d1cf, v55
	v_fmac_f32_e32 v52, v25, v45
	v_fmac_f32_e32 v58, 0x3f317217, v55
	v_fmac_f32_e32 v52, v26, v46
	v_sub_f32_e32 v56, v56, v58
	v_fmac_f32_e32 v52, v27, v47
	v_mul_f32_e32 v65, 0x3d800000, v56
	v_fmac_f32_e32 v52, v28, v48
	v_add_f32_e32 v54, v54, v65
	v_fmac_f32_e32 v52, v29, v49
	v_fmac_f32_e32 v52, v30, v50
	v_fmac_f32_e32 v52, v31, v51
	ds_read_b128 v[36:39], v2 offset:256
	ds_read_b128 v[40:43], v2 offset:272
	ds_read_b128 v[44:47], v2 offset:288
	ds_read_b128 v[48:51], v2 offset:304
	s_waitcnt lgkmcnt(4)
	v_fma_f32 v53, v16, v176, v32
	v_mul_f32_e64 v55, |v52|, s85
	v_fmac_f32_e32 v53, v17, v177
	v_exp_f32_e32 v55, v55
	v_fmac_f32_e32 v53, v18, v178
	v_min_f32_e32 v56, 0, v52
	v_fmac_f32_e32 v53, v19, v179
	v_add_f32_e32 v55, 1.0, v55
	v_fmac_f32_e32 v53, v20, v180
	v_log_f32_e32 v55, v55
	v_fmac_f32_e32 v53, v21, v181
	v_fmac_f32_e32 v53, v22, v182
	v_mul_f32_e32 v57, 0x3f317217, v55
	v_fmac_f32_e32 v53, v23, v183
	v_fma_f32 v58, v55, s74, -v57
	v_fmac_f32_e32 v53, v24, v184
	v_fmac_f32_e32 v58, 0x3377d1cf, v55
	v_fmac_f32_e32 v53, v25, v185
	v_fmac_f32_e32 v58, 0x3f317217, v55
	v_fmac_f32_e32 v53, v26, v186
	v_sub_f32_e32 v56, v56, v58
	v_fmac_f32_e32 v53, v27, v187
	v_mul_f32_e32 v66, 0x3d800000, v56
	v_fmac_f32_e32 v53, v28, v188
	v_add_f32_e32 v54, v54, v66
	v_fmac_f32_e32 v53, v29, v189
	v_fmac_f32_e32 v53, v30, v190
	v_fmac_f32_e32 v53, v31, v191
	ds_read_b128 v[176:179], v2 offset:320
	ds_read_b128 v[180:183], v2 offset:336
	ds_read_b128 v[184:187], v2 offset:352
	ds_read_b128 v[188:191], v2 offset:368
	s_waitcnt lgkmcnt(4)
	v_fma_f32 v52, v16, v36, v32
	v_mul_f32_e64 v55, |v53|, s85
	v_fmac_f32_e32 v52, v17, v37
	v_exp_f32_e32 v55, v55
	v_fmac_f32_e32 v52, v18, v38
	v_min_f32_e32 v56, 0, v53
	v_fmac_f32_e32 v52, v19, v39
	v_add_f32_e32 v55, 1.0, v55
	v_fmac_f32_e32 v52, v20, v40
	v_log_f32_e32 v55, v55
	v_fmac_f32_e32 v52, v21, v41
	v_fmac_f32_e32 v52, v22, v42
	v_mul_f32_e32 v57, 0x3f317217, v55
	v_fmac_f32_e32 v52, v23, v43
	v_fma_f32 v58, v55, s74, -v57
	v_fmac_f32_e32 v52, v24, v44
	v_fmac_f32_e32 v58, 0x3377d1cf, v55
	v_fmac_f32_e32 v52, v25, v45
	v_fmac_f32_e32 v58, 0x3f317217, v55
	v_fmac_f32_e32 v52, v26, v46
	v_sub_f32_e32 v56, v56, v58
	v_fmac_f32_e32 v52, v27, v47
	v_mul_f32_e32 v67, 0x3d800000, v56
	v_fmac_f32_e32 v52, v28, v48
	v_add_f32_e32 v54, v54, v67
	v_fmac_f32_e32 v52, v29, v49
	v_fmac_f32_e32 v52, v30, v50
	v_fmac_f32_e32 v52, v31, v51
	ds_read_b128 v[36:39], v2 offset:384
	ds_read_b128 v[40:43], v2 offset:400
	ds_read_b128 v[44:47], v2 offset:416
	ds_read_b128 v[48:51], v2 offset:432
	s_waitcnt lgkmcnt(4)
; DI float logsig16(float z) { return (fminf(z, 0.f) - __logf(1.f + __expf(-fabsf(z)))) * (1.f / 16.f); }
; DI void phase_gla_prep(const Params& p, int g, char* smem, int bid, int nb) {
;     ...
;     for (int tt = 0; tt < 32; ++tt) {
;       const int t = half * 32 + tt;
;       const float* l = lrs + t * 16; float z = bg;
; #pragma unroll
;       for (int r = 0; r < 16; ++r) z += l[r] * wg[r];
;       const float gv = logsig16(z);
;       const float b = dir ? (TOTAL - run) : (run + gv);
;       run += gv;
	v_fma_f32 v53, v16, v176, v32
	v_mul_f32_e64 v55, |v52|, s85
	v_fmac_f32_e32 v53, v17, v177
	v_exp_f32_e32 v55, v55
	v_fmac_f32_e32 v53, v18, v178
	v_min_f32_e32 v56, 0, v52
	v_fmac_f32_e32 v53, v19, v179
	v_add_f32_e32 v55, 1.0, v55
	v_fmac_f32_e32 v53, v20, v180
	v_log_f32_e32 v55, v55
	v_fmac_f32_e32 v53, v21, v181
	v_fmac_f32_e32 v53, v22, v182
	v_mul_f32_e32 v57, 0x3f317217, v55
	v_fmac_f32_e32 v53, v23, v183
	v_fma_f32 v58, v55, s74, -v57
	v_fmac_f32_e32 v53, v24, v184
	v_fmac_f32_e32 v58, 0x3377d1cf, v55
	v_fmac_f32_e32 v53, v25, v185
	v_fmac_f32_e32 v58, 0x3f317217, v55
	v_fmac_f32_e32 v53, v26, v186
	v_sub_f32_e32 v56, v56, v58
	v_fmac_f32_e32 v53, v27, v187
	v_mul_f32_e32 v68, 0x3d800000, v56
	v_fmac_f32_e32 v53, v28, v188
	v_add_f32_e32 v54, v54, v68
	v_fmac_f32_e32 v53, v29, v189
	v_fmac_f32_e32 v53, v30, v190
	v_fmac_f32_e32 v53, v31, v191
	ds_read_b128 v[176:179], v2 offset:448
	ds_read_b128 v[180:183], v2 offset:464
	ds_read_b128 v[184:187], v2 offset:480
	ds_read_b128 v[188:191], v2 offset:496
	s_waitcnt lgkmcnt(4)
	v_fma_f32 v52, v16, v36, v32
	v_mul_f32_e64 v55, |v53|, s85
	v_fmac_f32_e32 v52, v17, v37
	v_exp_f32_e32 v55, v55
	v_fmac_f32_e32 v52, v18, v38
	v_min_f32_e32 v56, 0, v53
	v_fmac_f32_e32 v52, v19, v39
	v_add_f32_e32 v55, 1.0, v55
	v_fmac_f32_e32 v52, v20, v40
	v_log_f32_e32 v55, v55
	v_fmac_f32_e32 v52, v21, v41
	v_fmac_f32_e32 v52, v22, v42
	v_mul_f32_e32 v57, 0x3f317217, v55
	v_fmac_f32_e32 v52, v23, v43
	v_fma_f32 v58, v55, s74, -v57
	v_fmac_f32_e32 v52, v24, v44
	v_fmac_f32_e32 v58, 0x3377d1cf, v55
	v_fmac_f32_e32 v52, v25, v45
	v_fmac_f32_e32 v58, 0x3f317217, v55
	v_fmac_f32_e32 v52, v26, v46
	v_sub_f32_e32 v56, v56, v58
	v_fmac_f32_e32 v52, v27, v47
	v_mul_f32_e32 v69, 0x3d800000, v56
	v_fmac_f32_e32 v52, v28, v48
	v_add_f32_e32 v54, v54, v69
	v_fmac_f32_e32 v52, v29, v49
	v_fmac_f32_e32 v52, v30, v50
	v_fmac_f32_e32 v52, v31, v51
	ds_read_b128 v[36:39], v2 offset:512
	ds_read_b128 v[40:43], v2 offset:528
	ds_read_b128 v[44:47], v2 offset:544
	ds_read_b128 v[48:51], v2 offset:560
	s_waitcnt lgkmcnt(4)
	v_fma_f32 v53, v16, v176, v32
	v_mul_f32_e64 v55, |v52|, s85
	v_fmac_f32_e32 v53, v17, v177
	v_exp_f32_e32 v55, v55
	v_fmac_f32_e32 v53, v18, v178
	v_min_f32_e32 v56, 0, v52
	v_fmac_f32_e32 v53, v19, v179
	v_add_f32_e32 v55, 1.0, v55
	v_fmac_f32_e32 v53, v20, v180
	v_log_f32_e32 v55, v55
	v_fmac_f32_e32 v53, v21, v181
	v_fmac_f32_e32 v53, v22, v182
	v_mul_f32_e32 v57, 0x3f317217, v55
	v_fmac_f32_e32 v53, v23, v183
	v_fma_f32 v58, v55, s74, -v57
	v_fmac_f32_e32 v53, v24, v184
	v_fmac_f32_e32 v58, 0x3377d1cf, v55
	v_fmac_f32_e32 v53, v25, v185
	v_fmac_f32_e32 v58, 0x3f317217, v55
	v_fmac_f32_e32 v53, v26, v186
	v_sub_f32_e32 v56, v56, v58
	v_fmac_f32_e32 v53, v27, v187
	v_mul_f32_e32 v70, 0x3d800000, v56
	v_fmac_f32_e32 v53, v28, v188
	v_add_f32_e32 v54, v54, v70
	v_fmac_f32_e32 v53, v29, v189
	v_fmac_f32_e32 v53, v30, v190
	v_fmac_f32_e32 v53, v31, v191
	ds_read_b128 v[176:179], v2 offset:576
	ds_read_b128 v[180:183], v2 offset:592
	ds_read_b128 v[184:187], v2 offset:608
	ds_read_b128 v[188:191], v2 offset:624
	s_waitcnt lgkmcnt(4)
	v_fma_f32 v52, v16, v36, v32
	v_mul_f32_e64 v55, |v53|, s85
	v_fmac_f32_e32 v52, v17, v37
	v_exp_f32_e32 v55, v55
	v_fmac_f32_e32 v52, v18, v38
	v_min_f32_e32 v56, 0, v53
	v_fmac_f32_e32 v52, v19, v39
	v_add_f32_e32 v55, 1.0, v55
	v_fmac_f32_e32 v52, v20, v40
	v_log_f32_e32 v55, v55
	v_fmac_f32_e32 v52, v21, v41
	v_fmac_f32_e32 v52, v22, v42
	v_mul_f32_e32 v57, 0x3f317217, v55
	v_fmac_f32_e32 v52, v23, v43
	v_fma_f32 v58, v55, s74, -v57
	v_fmac_f32_e32 v52, v24, v44
	v_fmac_f32_e32 v58, 0x3377d1cf, v55
	v_fmac_f32_e32 v52, v25, v45
	v_fmac_f32_e32 v58, 0x3f317217, v55
	v_fmac_f32_e32 v52, v26, v46
	v_sub_f32_e32 v56, v56, v58
	v_fmac_f32_e32 v52, v27, v47
	v_mul_f32_e32 v71, 0x3d800000, v56
	v_fmac_f32_e32 v52, v28, v48
	v_add_f32_e32 v54, v54, v71
	v_fmac_f32_e32 v52, v29, v49
	v_fmac_f32_e32 v52, v30, v50
	v_fmac_f32_e32 v52, v31, v51
	ds_read_b128 v[36:39], v2 offset:640
	ds_read_b128 v[40:43], v2 offset:656
	ds_read_b128 v[44:47], v2 offset:672
	ds_read_b128 v[48:51], v2 offset:688
	s_waitcnt lgkmcnt(4)
	v_fma_f32 v53, v16, v176, v32
	v_mul_f32_e64 v55, |v52|, s85
	v_fmac_f32_e32 v53, v17, v177
	v_exp_f32_e32 v55, v55
	v_fmac_f32_e32 v53, v18, v178
	v_min_f32_e32 v56, 0, v52
	v_fmac_f32_e32 v53, v19, v179
	v_add_f32_e32 v55, 1.0, v55
	v_fmac_f32_e32 v53, v20, v180
	v_log_f32_e32 v55, v55
	v_fmac_f32_e32 v53, v21, v181
	v_fmac_f32_e32 v53, v22, v182
	v_mul_f32_e32 v57, 0x3f317217, v55
	v_fmac_f32_e32 v53, v23, v183
	v_fma_f32 v58, v55, s74, -v57
	v_fmac_f32_e32 v53, v24, v184
	v_fmac_f32_e32 v58, 0x3377d1cf, v55
	v_fmac_f32_e32 v53, v25, v185
	v_fmac_f32_e32 v58, 0x3f317217, v55
	v_fmac_f32_e32 v53, v26, v186
	v_sub_f32_e32 v56, v56, v58
	v_fmac_f32_e32 v53, v27, v187
	v_mul_f32_e32 v72, 0x3d800000, v56
	v_fmac_f32_e32 v53, v28, v188
	v_add_f32_e32 v54, v54, v72
	v_fmac_f32_e32 v53, v29, v189
	v_fmac_f32_e32 v53, v30, v190
	v_fmac_f32_e32 v53, v31, v191
	ds_read_b128 v[176:179], v2 offset:704
	ds_read_b128 v[180:183], v2 offset:720
	ds_read_b128 v[184:187], v2 offset:736
	ds_read_b128 v[188:191], v2 offset:752
	s_waitcnt vmcnt(31)
; DI float bf2f(bf16_t v) { return __uint_as_float(((unsigned)v) << 16); }
; DI float logsig16(float z) { return (fminf(z, 0.f) - __logf(1.f + __expf(-fabsf(z)))) * (1.f / 16.f); }
; DI void phase_gla_prep(const Params& p, int g, char* smem, int bid, int nb) {
;     ...
;     for (int tt = 0; tt < 32; ++tt) {
;       const int t = half * 32 + tt;
;       const float* l = lrs + t * 16; float z = bg;
; #pragma unroll
;       for (int r = 0; r < 16; ++r) z += l[r] * wg[r];
;       const float gv = logsig16(z);
;       const float b = dir ? (TOTAL - run) : (run + gv);
;       run += gv;
;       const size_t tg = (size_t)c * 64 + t;
;       const float qv = bf2f(proj[tg * NPROJ + PQG + dd]), kv = bf2f(proj[tg * NPROJ + PKG + dd]);
	global_load_ushort v112, v4, s[22:23]
	global_load_ushort v160, v4, s[22:23] offset:1024
	s_add_u32 s22, s22, 0x2800
	s_addc_u32 s23, s23, 0
	global_load_ushort v113, v4, s[22:23]
	global_load_ushort v161, v4, s[22:23] offset:1024
	s_add_u32 s22, s22, 0x2800
	s_addc_u32 s23, s23, 0
	global_load_ushort v114, v4, s[22:23]
	global_load_ushort v162, v4, s[22:23] offset:1024
	s_add_u32 s22, s22, 0x2800
	s_addc_u32 s23, s23, 0
	global_load_ushort v115, v4, s[22:23]
	global_load_ushort v163, v4, s[22:23] offset:1024
	s_add_u32 s22, s22, 0x2800
	s_addc_u32 s23, s23, 0
	global_load_ushort v116, v4, s[22:23]
	global_load_ushort v164, v4, s[22:23] offset:1024
	s_add_u32 s22, s22, 0x2800
	s_addc_u32 s23, s23, 0
	global_load_ushort v117, v4, s[22:23]
	global_load_ushort v165, v4, s[22:23] offset:1024
	s_add_u32 s22, s22, 0x2800
	s_addc_u32 s23, s23, 0
	global_load_ushort v118, v4, s[22:23]
	global_load_ushort v166, v4, s[22:23] offset:1024
	s_add_u32 s22, s22, 0x2800
	s_addc_u32 s23, s23, 0
	global_load_ushort v119, v4, s[22:23]
	global_load_ushort v167, v4, s[22:23] offset:1024
	s_add_u32 s22, s22, 0x2800
	s_addc_u32 s23, s23, 0
	global_load_ushort v120, v4, s[22:23]
	global_load_ushort v168, v4, s[22:23] offset:1024
	s_add_u32 s22, s22, 0x2800
	s_addc_u32 s23, s23, 0
	global_load_ushort v121, v4, s[22:23]
	global_load_ushort v169, v4, s[22:23] offset:1024
	s_add_u32 s22, s22, 0x2800
	s_addc_u32 s23, s23, 0
	global_load_ushort v122, v4, s[22:23]
	global_load_ushort v170, v4, s[22:23] offset:1024
	s_add_u32 s22, s22, 0x2800
	s_addc_u32 s23, s23, 0
	global_load_ushort v123, v4, s[22:23]
	global_load_ushort v171, v4, s[22:23] offset:1024
	s_add_u32 s22, s22, 0x2800
	s_addc_u32 s23, s23, 0
	global_load_ushort v124, v4, s[22:23]
	global_load_ushort v172, v4, s[22:23] offset:1024
	s_add_u32 s22, s22, 0x2800
	s_addc_u32 s23, s23, 0
	global_load_ushort v125, v4, s[22:23]
	global_load_ushort v173, v4, s[22:23] offset:1024
	s_add_u32 s22, s22, 0x2800
	s_addc_u32 s23, s23, 0
	global_load_ushort v126, v4, s[22:23]
	global_load_ushort v174, v4, s[22:23] offset:1024
	s_add_u32 s22, s22, 0x2800
	s_addc_u32 s23, s23, 0
	global_load_ushort v127, v4, s[22:23]
	global_load_ushort v175, v4, s[22:23] offset:1024
	s_add_u32 s22, s22, 0x2800
	s_addc_u32 s23, s23, 0
	s_waitcnt lgkmcnt(4)
	v_fma_f32 v52, v16, v36, v32
	v_mul_f32_e64 v55, |v53|, s85
	v_fmac_f32_e32 v52, v17, v37
	v_exp_f32_e32 v55, v55
	v_fmac_f32_e32 v52, v18, v38
	v_min_f32_e32 v56, 0, v53
	v_fmac_f32_e32 v52, v19, v39
	v_add_f32_e32 v55, 1.0, v55
	v_fmac_f32_e32 v52, v20, v40
	v_log_f32_e32 v55, v55
	v_fmac_f32_e32 v52, v21, v41
	v_fmac_f32_e32 v52, v22, v42
	v_mul_f32_e32 v57, 0x3f317217, v55
	v_fmac_f32_e32 v52, v23, v43
	v_fma_f32 v58, v55, s74, -v57
	v_fmac_f32_e32 v52, v24, v44
	v_fmac_f32_e32 v58, 0x3377d1cf, v55
	v_fmac_f32_e32 v52, v25, v45
	v_fmac_f32_e32 v58, 0x3f317217, v55
	v_fmac_f32_e32 v52, v26, v46
	v_sub_f32_e32 v56, v56, v58
	v_fmac_f32_e32 v52, v27, v47
	v_mul_f32_e32 v73, 0x3d800000, v56
	v_fmac_f32_e32 v52, v28, v48
	v_add_f32_e32 v54, v54, v73
	v_fmac_f32_e32 v52, v29, v49
	v_fmac_f32_e32 v52, v30, v50
	v_fmac_f32_e32 v52, v31, v51
	ds_read_b128 v[36:39], v2 offset:768
	ds_read_b128 v[40:43], v2 offset:784
	ds_read_b128 v[44:47], v2 offset:800
	ds_read_b128 v[48:51], v2 offset:816
	s_waitcnt lgkmcnt(4)
	v_fma_f32 v53, v16, v176, v32
	v_mul_f32_e64 v55, |v52|, s85
	v_fmac_f32_e32 v53, v17, v177
	v_exp_f32_e32 v55, v55
	v_fmac_f32_e32 v53, v18, v178
	v_min_f32_e32 v56, 0, v52
	v_fmac_f32_e32 v53, v19, v179
	v_add_f32_e32 v55, 1.0, v55
	v_fmac_f32_e32 v53, v20, v180
	v_log_f32_e32 v55, v55
	v_fmac_f32_e32 v53, v21, v181
	v_fmac_f32_e32 v53, v22, v182
	v_mul_f32_e32 v57, 0x3f317217, v55
	v_fmac_f32_e32 v53, v23, v183
	v_fma_f32 v58, v55, s74, -v57
	v_fmac_f32_e32 v53, v24, v184
	v_fmac_f32_e32 v58, 0x3377d1cf, v55
	v_fmac_f32_e32 v53, v25, v185
	v_fmac_f32_e32 v58, 0x3f317217, v55
	v_fmac_f32_e32 v53, v26, v186
	v_sub_f32_e32 v56, v56, v58
	v_fmac_f32_e32 v53, v27, v187
	v_mul_f32_e32 v74, 0x3d800000, v56
	v_fmac_f32_e32 v53, v28, v188
	v_add_f32_e32 v54, v54, v74
	v_fmac_f32_e32 v53, v29, v189
	v_fmac_f32_e32 v53, v30, v190
	v_fmac_f32_e32 v53, v31, v191
	ds_read_b128 v[176:179], v2 offset:832
	ds_read_b128 v[180:183], v2 offset:848
	ds_read_b128 v[184:187], v2 offset:864
	ds_read_b128 v[188:191], v2 offset:880
	s_waitcnt lgkmcnt(4)
	v_fma_f32 v52, v16, v36, v32
	v_mul_f32_e64 v55, |v53|, s85
	v_fmac_f32_e32 v52, v17, v37
	v_exp_f32_e32 v55, v55
	v_fmac_f32_e32 v52, v18, v38
	v_min_f32_e32 v56, 0, v53
	v_fmac_f32_e32 v52, v19, v39
	v_add_f32_e32 v55, 1.0, v55
	v_fmac_f32_e32 v52, v20, v40
	v_log_f32_e32 v55, v55
	v_fmac_f32_e32 v52, v21, v41
	v_fmac_f32_e32 v52, v22, v42
	v_mul_f32_e32 v57, 0x3f317217, v55
	v_fmac_f32_e32 v52, v23, v43
	v_fma_f32 v58, v55, s74, -v57
	v_fmac_f32_e32 v52, v24, v44
	v_fmac_f32_e32 v58, 0x3377d1cf, v55
	v_fmac_f32_e32 v52, v25, v45
	v_fmac_f32_e32 v58, 0x3f317217, v55
	v_fmac_f32_e32 v52, v26, v46
	v_sub_f32_e32 v56, v56, v58
	v_fmac_f32_e32 v52, v27, v47
	v_mul_f32_e32 v75, 0x3d800000, v56
	v_fmac_f32_e32 v52, v28, v48
	v_add_f32_e32 v54, v54, v75
	v_fmac_f32_e32 v52, v29, v49
	v_fmac_f32_e32 v52, v30, v50
	v_fmac_f32_e32 v52, v31, v51
	ds_read_b128 v[36:39], v2 offset:896
	ds_read_b128 v[40:43], v2 offset:912
	ds_read_b128 v[44:47], v2 offset:928
	ds_read_b128 v[48:51], v2 offset:944
	s_waitcnt lgkmcnt(4)
; DI float logsig16(float z) { return (fminf(z, 0.f) - __logf(1.f + __expf(-fabsf(z)))) * (1.f / 16.f); }
; DI void phase_gla_prep(const Params& p, int g, char* smem, int bid, int nb) {
;     ...
;     for (int tt = 0; tt < 32; ++tt) {
;       const int t = half * 32 + tt;
;       const float* l = lrs + t * 16; float z = bg;
; #pragma unroll
;       for (int r = 0; r < 16; ++r) z += l[r] * wg[r];
;       const float gv = logsig16(z);
;       const float b = dir ? (TOTAL - run) : (run + gv);
;       run += gv;
	v_fma_f32 v53, v16, v176, v32
	v_mul_f32_e64 v55, |v52|, s85
	v_fmac_f32_e32 v53, v17, v177
	v_exp_f32_e32 v55, v55
	v_fmac_f32_e32 v53, v18, v178
	v_min_f32_e32 v56, 0, v52
	v_fmac_f32_e32 v53, v19, v179
	v_add_f32_e32 v55, 1.0, v55
	v_fmac_f32_e32 v53, v20, v180
	v_log_f32_e32 v55, v55
	v_fmac_f32_e32 v53, v21, v181
	v_fmac_f32_e32 v53, v22, v182
	v_mul_f32_e32 v57, 0x3f317217, v55
	v_fmac_f32_e32 v53, v23, v183
	v_fma_f32 v58, v55, s74, -v57
	v_fmac_f32_e32 v53, v24, v184
	v_fmac_f32_e32 v58, 0x3377d1cf, v55
	v_fmac_f32_e32 v53, v25, v185
	v_fmac_f32_e32 v58, 0x3f317217, v55
	v_fmac_f32_e32 v53, v26, v186
	v_sub_f32_e32 v56, v56, v58
	v_fmac_f32_e32 v53, v27, v187
	v_mul_f32_e32 v76, 0x3d800000, v56
	v_fmac_f32_e32 v53, v28, v188
	v_add_f32_e32 v54, v54, v76
	v_fmac_f32_e32 v53, v29, v189
	v_fmac_f32_e32 v53, v30, v190
	v_fmac_f32_e32 v53, v31, v191
	ds_read_b128 v[176:179], v2 offset:960
	ds_read_b128 v[180:183], v2 offset:976
	ds_read_b128 v[184:187], v2 offset:992
	ds_read_b128 v[188:191], v2 offset:1008
	s_waitcnt lgkmcnt(4)
	v_fma_f32 v52, v16, v36, v32
	v_mul_f32_e64 v55, |v53|, s85
	v_fmac_f32_e32 v52, v17, v37
	v_exp_f32_e32 v55, v55
	v_fmac_f32_e32 v52, v18, v38
	v_min_f32_e32 v56, 0, v53
	v_fmac_f32_e32 v52, v19, v39
	v_add_f32_e32 v55, 1.0, v55
	v_fmac_f32_e32 v52, v20, v40
	v_log_f32_e32 v55, v55
	v_fmac_f32_e32 v52, v21, v41
	v_fmac_f32_e32 v52, v22, v42
	v_mul_f32_e32 v57, 0x3f317217, v55
	v_fmac_f32_e32 v52, v23, v43
	v_fma_f32 v58, v55, s74, -v57
	v_fmac_f32_e32 v52, v24, v44
	v_fmac_f32_e32 v58, 0x3377d1cf, v55
	v_fmac_f32_e32 v52, v25, v45
	v_fmac_f32_e32 v58, 0x3f317217, v55
	v_fmac_f32_e32 v52, v26, v46
	v_sub_f32_e32 v56, v56, v58
	v_fmac_f32_e32 v52, v27, v47
	v_mul_f32_e32 v77, 0x3d800000, v56
	v_fmac_f32_e32 v52, v28, v48
	v_add_f32_e32 v54, v54, v77
	v_fmac_f32_e32 v52, v29, v49
	v_fmac_f32_e32 v52, v30, v50
	v_fmac_f32_e32 v52, v31, v51
	ds_read_b128 v[36:39], v2 offset:1024
	ds_read_b128 v[40:43], v2 offset:1040
	ds_read_b128 v[44:47], v2 offset:1056
	ds_read_b128 v[48:51], v2 offset:1072
	s_waitcnt lgkmcnt(4)
	v_fma_f32 v53, v16, v176, v32
	v_mul_f32_e64 v55, |v52|, s85
	v_fmac_f32_e32 v53, v17, v177
	v_exp_f32_e32 v55, v55
	v_fmac_f32_e32 v53, v18, v178
	v_min_f32_e32 v56, 0, v52
	v_fmac_f32_e32 v53, v19, v179
	v_add_f32_e32 v55, 1.0, v55
	v_fmac_f32_e32 v53, v20, v180
	v_log_f32_e32 v55, v55
	v_fmac_f32_e32 v53, v21, v181
	v_fmac_f32_e32 v53, v22, v182
	v_mul_f32_e32 v57, 0x3f317217, v55
	v_fmac_f32_e32 v53, v23, v183
	v_fma_f32 v58, v55, s74, -v57
	v_fmac_f32_e32 v53, v24, v184
	v_fmac_f32_e32 v58, 0x3377d1cf, v55
	v_fmac_f32_e32 v53, v25, v185
	v_fmac_f32_e32 v58, 0x3f317217, v55
	v_fmac_f32_e32 v53, v26, v186
	v_sub_f32_e32 v56, v56, v58
	v_fmac_f32_e32 v53, v27, v187
	v_mul_f32_e32 v78, 0x3d800000, v56
	v_fmac_f32_e32 v53, v28, v188
	v_add_f32_e32 v54, v54, v78
	v_fmac_f32_e32 v53, v29, v189
	v_fmac_f32_e32 v53, v30, v190
	v_fmac_f32_e32 v53, v31, v191
	ds_read_b128 v[176:179], v2 offset:1088
	ds_read_b128 v[180:183], v2 offset:1104
	ds_read_b128 v[184:187], v2 offset:1120
	ds_read_b128 v[188:191], v2 offset:1136
	s_waitcnt lgkmcnt(4)
	v_fma_f32 v52, v16, v36, v32
	v_mul_f32_e64 v55, |v53|, s85
	v_fmac_f32_e32 v52, v17, v37
	v_exp_f32_e32 v55, v55
	v_fmac_f32_e32 v52, v18, v38
	v_min_f32_e32 v56, 0, v53
	v_fmac_f32_e32 v52, v19, v39
	v_add_f32_e32 v55, 1.0, v55
	v_fmac_f32_e32 v52, v20, v40
	v_log_f32_e32 v55, v55
	v_fmac_f32_e32 v52, v21, v41
	v_fmac_f32_e32 v52, v22, v42
	v_mul_f32_e32 v57, 0x3f317217, v55
	v_fmac_f32_e32 v52, v23, v43
	v_fma_f32 v58, v55, s74, -v57
	v_fmac_f32_e32 v52, v24, v44
	v_fmac_f32_e32 v58, 0x3377d1cf, v55
	v_fmac_f32_e32 v52, v25, v45
	v_fmac_f32_e32 v58, 0x3f317217, v55
	v_fmac_f32_e32 v52, v26, v46
	v_sub_f32_e32 v56, v56, v58
	v_fmac_f32_e32 v52, v27, v47
	v_mul_f32_e32 v79, 0x3d800000, v56
	v_fmac_f32_e32 v52, v28, v48
	v_add_f32_e32 v54, v54, v79
	v_fmac_f32_e32 v52, v29, v49
	v_fmac_f32_e32 v52, v30, v50
	v_fmac_f32_e32 v52, v31, v51
	ds_read_b128 v[36:39], v2 offset:1152
	ds_read_b128 v[40:43], v2 offset:1168
	ds_read_b128 v[44:47], v2 offset:1184
	ds_read_b128 v[48:51], v2 offset:1200
	s_waitcnt lgkmcnt(4)
	v_fma_f32 v53, v16, v176, v32
	v_mul_f32_e64 v55, |v52|, s85
	v_fmac_f32_e32 v53, v17, v177
	v_exp_f32_e32 v55, v55
	v_fmac_f32_e32 v53, v18, v178
	v_min_f32_e32 v56, 0, v52
	v_fmac_f32_e32 v53, v19, v179
	v_add_f32_e32 v55, 1.0, v55
	v_fmac_f32_e32 v53, v20, v180
	v_log_f32_e32 v55, v55
	v_fmac_f32_e32 v53, v21, v181
	v_fmac_f32_e32 v53, v22, v182
	v_mul_f32_e32 v57, 0x3f317217, v55
	v_fmac_f32_e32 v53, v23, v183
	v_fma_f32 v58, v55, s74, -v57
	v_fmac_f32_e32 v53, v24, v184
	v_fmac_f32_e32 v58, 0x3377d1cf, v55
	v_fmac_f32_e32 v53, v25, v185
	v_fmac_f32_e32 v58, 0x3f317217, v55
	v_fmac_f32_e32 v53, v26, v186
	v_sub_f32_e32 v56, v56, v58
	v_fmac_f32_e32 v53, v27, v187
	v_mul_f32_e32 v80, 0x3d800000, v56
	v_fmac_f32_e32 v53, v28, v188
	v_add_f32_e32 v54, v54, v80
	v_fmac_f32_e32 v53, v29, v189
	v_fmac_f32_e32 v53, v30, v190
	v_fmac_f32_e32 v53, v31, v191
	ds_read_b128 v[176:179], v2 offset:1216
	ds_read_b128 v[180:183], v2 offset:1232
	ds_read_b128 v[184:187], v2 offset:1248
	ds_read_b128 v[188:191], v2 offset:1264
	s_waitcnt lgkmcnt(4)
; DI float logsig16(float z) { return (fminf(z, 0.f) - __logf(1.f + __expf(-fabsf(z)))) * (1.f / 16.f); }
; DI void phase_gla_prep(const Params& p, int g, char* smem, int bid, int nb) {
;     ...
;     for (int tt = 0; tt < 32; ++tt) {
;       const int t = half * 32 + tt;
;       const float* l = lrs + t * 16; float z = bg;
; #pragma unroll
;       for (int r = 0; r < 16; ++r) z += l[r] * wg[r];
;       const float gv = logsig16(z);
;       const float b = dir ? (TOTAL - run) : (run + gv);
;       run += gv;
	v_fma_f32 v52, v16, v36, v32
	v_mul_f32_e64 v55, |v53|, s85
	v_fmac_f32_e32 v52, v17, v37
	v_exp_f32_e32 v55, v55
	v_fmac_f32_e32 v52, v18, v38
	v_min_f32_e32 v56, 0, v53
	v_fmac_f32_e32 v52, v19, v39
	v_add_f32_e32 v55, 1.0, v55
	v_fmac_f32_e32 v52, v20, v40
	v_log_f32_e32 v55, v55
	v_fmac_f32_e32 v52, v21, v41
	v_fmac_f32_e32 v52, v22, v42
	v_mul_f32_e32 v57, 0x3f317217, v55
	v_fmac_f32_e32 v52, v23, v43
	v_fma_f32 v58, v55, s74, -v57
	v_fmac_f32_e32 v52, v24, v44
	v_fmac_f32_e32 v58, 0x3377d1cf, v55
	v_fmac_f32_e32 v52, v25, v45
	v_fmac_f32_e32 v58, 0x3f317217, v55
	v_fmac_f32_e32 v52, v26, v46
	v_sub_f32_e32 v56, v56, v58
	v_fmac_f32_e32 v52, v27, v47
	v_mul_f32_e32 v81, 0x3d800000, v56
	v_fmac_f32_e32 v52, v28, v48
	v_add_f32_e32 v54, v54, v81
	v_fmac_f32_e32 v52, v29, v49
	v_fmac_f32_e32 v52, v30, v50
	v_fmac_f32_e32 v52, v31, v51
	ds_read_b128 v[36:39], v2 offset:1280
	ds_read_b128 v[40:43], v2 offset:1296
	ds_read_b128 v[44:47], v2 offset:1312
	ds_read_b128 v[48:51], v2 offset:1328
	s_waitcnt lgkmcnt(4)
	v_fma_f32 v53, v16, v176, v32
	v_mul_f32_e64 v55, |v52|, s85
	v_fmac_f32_e32 v53, v17, v177
	v_exp_f32_e32 v55, v55
	v_fmac_f32_e32 v53, v18, v178
	v_min_f32_e32 v56, 0, v52
	v_fmac_f32_e32 v53, v19, v179
	v_add_f32_e32 v55, 1.0, v55
	v_fmac_f32_e32 v53, v20, v180
	v_log_f32_e32 v55, v55
	v_fmac_f32_e32 v53, v21, v181
	v_fmac_f32_e32 v53, v22, v182
	v_mul_f32_e32 v57, 0x3f317217, v55
	v_fmac_f32_e32 v53, v23, v183
	v_fma_f32 v58, v55, s74, -v57
	v_fmac_f32_e32 v53, v24, v184
	v_fmac_f32_e32 v58, 0x3377d1cf, v55
	v_fmac_f32_e32 v53, v25, v185
	v_fmac_f32_e32 v58, 0x3f317217, v55
	v_fmac_f32_e32 v53, v26, v186
	v_sub_f32_e32 v56, v56, v58
	v_fmac_f32_e32 v53, v27, v187
	v_mul_f32_e32 v82, 0x3d800000, v56
	v_fmac_f32_e32 v53, v28, v188
	v_add_f32_e32 v54, v54, v82
	v_fmac_f32_e32 v53, v29, v189
	v_fmac_f32_e32 v53, v30, v190
	v_fmac_f32_e32 v53, v31, v191
	ds_read_b128 v[176:179], v2 offset:1344
	ds_read_b128 v[180:183], v2 offset:1360
	ds_read_b128 v[184:187], v2 offset:1376
	ds_read_b128 v[188:191], v2 offset:1392
	s_waitcnt lgkmcnt(4)
	v_fma_f32 v52, v16, v36, v32
	v_mul_f32_e64 v55, |v53|, s85
	v_fmac_f32_e32 v52, v17, v37
	v_exp_f32_e32 v55, v55
	v_fmac_f32_e32 v52, v18, v38
	v_min_f32_e32 v56, 0, v53
	v_fmac_f32_e32 v52, v19, v39
	v_add_f32_e32 v55, 1.0, v55
	v_fmac_f32_e32 v52, v20, v40
	v_log_f32_e32 v55, v55
	v_fmac_f32_e32 v52, v21, v41
	v_fmac_f32_e32 v52, v22, v42
	v_mul_f32_e32 v57, 0x3f317217, v55
	v_fmac_f32_e32 v52, v23, v43
	v_fma_f32 v58, v55, s74, -v57
	v_fmac_f32_e32 v52, v24, v44
	v_fmac_f32_e32 v58, 0x3377d1cf, v55
	v_fmac_f32_e32 v52, v25, v45
	v_fmac_f32_e32 v58, 0x3f317217, v55
	v_fmac_f32_e32 v52, v26, v46
	v_sub_f32_e32 v56, v56, v58
	v_fmac_f32_e32 v52, v27, v47
	v_mul_f32_e32 v83, 0x3d800000, v56
	v_fmac_f32_e32 v52, v28, v48
	v_add_f32_e32 v54, v54, v83
	v_fmac_f32_e32 v52, v29, v49
	v_fmac_f32_e32 v52, v30, v50
	v_fmac_f32_e32 v52, v31, v51
	ds_read_b128 v[36:39], v2 offset:1408
	ds_read_b128 v[40:43], v2 offset:1424
	ds_read_b128 v[44:47], v2 offset:1440
	ds_read_b128 v[48:51], v2 offset:1456
	s_waitcnt lgkmcnt(4)
	v_fma_f32 v53, v16, v176, v32
	v_mul_f32_e64 v55, |v52|, s85
	v_fmac_f32_e32 v53, v17, v177
	v_exp_f32_e32 v55, v55
	v_fmac_f32_e32 v53, v18, v178
	v_min_f32_e32 v56, 0, v52
	v_fmac_f32_e32 v53, v19, v179
	v_add_f32_e32 v55, 1.0, v55
	v_fmac_f32_e32 v53, v20, v180
	v_log_f32_e32 v55, v55
	v_fmac_f32_e32 v53, v21, v181
	v_fmac_f32_e32 v53, v22, v182
	v_mul_f32_e32 v57, 0x3f317217, v55
	v_fmac_f32_e32 v53, v23, v183
	v_fma_f32 v58, v55, s74, -v57
	v_fmac_f32_e32 v53, v24, v184
	v_fmac_f32_e32 v58, 0x3377d1cf, v55
	v_fmac_f32_e32 v53, v25, v185
	v_fmac_f32_e32 v58, 0x3f317217, v55
	v_fmac_f32_e32 v53, v26, v186
	v_sub_f32_e32 v56, v56, v58
	v_fmac_f32_e32 v53, v27, v187
	v_mul_f32_e32 v84, 0x3d800000, v56
	v_fmac_f32_e32 v53, v28, v188
	v_add_f32_e32 v54, v54, v84
	v_fmac_f32_e32 v53, v29, v189
	v_fmac_f32_e32 v53, v30, v190
	v_fmac_f32_e32 v53, v31, v191
	ds_read_b128 v[176:179], v2 offset:1472
	ds_read_b128 v[180:183], v2 offset:1488
	ds_read_b128 v[184:187], v2 offset:1504
	ds_read_b128 v[188:191], v2 offset:1520
	s_waitcnt lgkmcnt(4)
	v_fma_f32 v52, v16, v36, v32
	v_mul_f32_e64 v55, |v53|, s85
	v_fmac_f32_e32 v52, v17, v37
	v_exp_f32_e32 v55, v55
	v_fmac_f32_e32 v52, v18, v38
	v_min_f32_e32 v56, 0, v53
	v_fmac_f32_e32 v52, v19, v39
	v_add_f32_e32 v55, 1.0, v55
	v_fmac_f32_e32 v52, v20, v40
	v_log_f32_e32 v55, v55
	v_fmac_f32_e32 v52, v21, v41
	v_fmac_f32_e32 v52, v22, v42
	v_mul_f32_e32 v57, 0x3f317217, v55
	v_fmac_f32_e32 v52, v23, v43
	v_fma_f32 v58, v55, s74, -v57
	v_fmac_f32_e32 v52, v24, v44
	v_fmac_f32_e32 v58, 0x3377d1cf, v55
	v_fmac_f32_e32 v52, v25, v45
	v_fmac_f32_e32 v58, 0x3f317217, v55
	v_fmac_f32_e32 v52, v26, v46
	v_sub_f32_e32 v56, v56, v58
	v_fmac_f32_e32 v52, v27, v47
	v_mul_f32_e32 v85, 0x3d800000, v56
	v_fmac_f32_e32 v52, v28, v48
	v_add_f32_e32 v54, v54, v85
	v_fmac_f32_e32 v52, v29, v49
	v_fmac_f32_e32 v52, v30, v50
	v_fmac_f32_e32 v52, v31, v51
	ds_read_b128 v[36:39], v2 offset:1536
	ds_read_b128 v[40:43], v2 offset:1552
	ds_read_b128 v[44:47], v2 offset:1568
	ds_read_b128 v[48:51], v2 offset:1584
	s_waitcnt lgkmcnt(4)
; DI float logsig16(float z) { return (fminf(z, 0.f) - __logf(1.f + __expf(-fabsf(z)))) * (1.f / 16.f); }
; DI void phase_gla_prep(const Params& p, int g, char* smem, int bid, int nb) {
;     ...
;     for (int tt = 0; tt < 32; ++tt) {
;       const int t = half * 32 + tt;
;       const float* l = lrs + t * 16; float z = bg;
; #pragma unroll
;       for (int r = 0; r < 16; ++r) z += l[r] * wg[r];
;       const float gv = logsig16(z);
;       const float b = dir ? (TOTAL - run) : (run + gv);
;       run += gv;
	v_fma_f32 v53, v16, v176, v32
	v_mul_f32_e64 v55, |v52|, s85
	v_fmac_f32_e32 v53, v17, v177
	v_exp_f32_e32 v55, v55
	v_fmac_f32_e32 v53, v18, v178
	v_min_f32_e32 v56, 0, v52
	v_fmac_f32_e32 v53, v19, v179
	v_add_f32_e32 v55, 1.0, v55
	v_fmac_f32_e32 v53, v20, v180
	v_log_f32_e32 v55, v55
	v_fmac_f32_e32 v53, v21, v181
	v_fmac_f32_e32 v53, v22, v182
	v_mul_f32_e32 v57, 0x3f317217, v55
	v_fmac_f32_e32 v53, v23, v183
	v_fma_f32 v58, v55, s74, -v57
	v_fmac_f32_e32 v53, v24, v184
	v_fmac_f32_e32 v58, 0x3377d1cf, v55
	v_fmac_f32_e32 v53, v25, v185
	v_fmac_f32_e32 v58, 0x3f317217, v55
	v_fmac_f32_e32 v53, v26, v186
	v_sub_f32_e32 v56, v56, v58
	v_fmac_f32_e32 v53, v27, v187
	v_mul_f32_e32 v86, 0x3d800000, v56
	v_fmac_f32_e32 v53, v28, v188
	v_add_f32_e32 v54, v54, v86
	v_fmac_f32_e32 v53, v29, v189
	v_fmac_f32_e32 v53, v30, v190
	v_fmac_f32_e32 v53, v31, v191
	ds_read_b128 v[176:179], v2 offset:1600
	ds_read_b128 v[180:183], v2 offset:1616
	ds_read_b128 v[184:187], v2 offset:1632
	ds_read_b128 v[188:191], v2 offset:1648
	s_waitcnt lgkmcnt(4)
	v_fma_f32 v52, v16, v36, v32
	v_mul_f32_e64 v55, |v53|, s85
	v_fmac_f32_e32 v52, v17, v37
	v_exp_f32_e32 v55, v55
	v_fmac_f32_e32 v52, v18, v38
	v_min_f32_e32 v56, 0, v53
	v_fmac_f32_e32 v52, v19, v39
	v_add_f32_e32 v55, 1.0, v55
	v_fmac_f32_e32 v52, v20, v40
	v_log_f32_e32 v55, v55
	v_fmac_f32_e32 v52, v21, v41
	v_fmac_f32_e32 v52, v22, v42
	v_mul_f32_e32 v57, 0x3f317217, v55
	v_fmac_f32_e32 v52, v23, v43
	v_fma_f32 v58, v55, s74, -v57
	v_fmac_f32_e32 v52, v24, v44
	v_fmac_f32_e32 v58, 0x3377d1cf, v55
	v_fmac_f32_e32 v52, v25, v45
	v_fmac_f32_e32 v58, 0x3f317217, v55
	v_fmac_f32_e32 v52, v26, v46
	v_sub_f32_e32 v56, v56, v58
	v_fmac_f32_e32 v52, v27, v47
	v_mul_f32_e32 v87, 0x3d800000, v56
	v_fmac_f32_e32 v52, v28, v48
	v_add_f32_e32 v54, v54, v87
	v_fmac_f32_e32 v52, v29, v49
	v_fmac_f32_e32 v52, v30, v50
	v_fmac_f32_e32 v52, v31, v51
	ds_read_b128 v[36:39], v2 offset:1664
	ds_read_b128 v[40:43], v2 offset:1680
	ds_read_b128 v[44:47], v2 offset:1696
	ds_read_b128 v[48:51], v2 offset:1712
	s_waitcnt lgkmcnt(4)
	v_fma_f32 v53, v16, v176, v32
	v_mul_f32_e64 v55, |v52|, s85
	v_fmac_f32_e32 v53, v17, v177
	v_exp_f32_e32 v55, v55
	v_fmac_f32_e32 v53, v18, v178
	v_min_f32_e32 v56, 0, v52
	v_fmac_f32_e32 v53, v19, v179
	v_add_f32_e32 v55, 1.0, v55
	v_fmac_f32_e32 v53, v20, v180
	v_log_f32_e32 v55, v55
	v_fmac_f32_e32 v53, v21, v181
	v_fmac_f32_e32 v53, v22, v182
	v_mul_f32_e32 v57, 0x3f317217, v55
	v_fmac_f32_e32 v53, v23, v183
	v_fma_f32 v58, v55, s74, -v57
	v_fmac_f32_e32 v53, v24, v184
	v_fmac_f32_e32 v58, 0x3377d1cf, v55
	v_fmac_f32_e32 v53, v25, v185
	v_fmac_f32_e32 v58, 0x3f317217, v55
	v_fmac_f32_e32 v53, v26, v186
	v_sub_f32_e32 v56, v56, v58
	v_fmac_f32_e32 v53, v27, v187
	v_mul_f32_e32 v88, 0x3d800000, v56
	v_fmac_f32_e32 v53, v28, v188
	v_add_f32_e32 v54, v54, v88
	v_fmac_f32_e32 v53, v29, v189
	v_fmac_f32_e32 v53, v30, v190
	v_fmac_f32_e32 v53, v31, v191
	ds_read_b128 v[176:179], v2 offset:1728
	ds_read_b128 v[180:183], v2 offset:1744
	ds_read_b128 v[184:187], v2 offset:1760
	ds_read_b128 v[188:191], v2 offset:1776
	s_waitcnt lgkmcnt(4)
	v_fma_f32 v52, v16, v36, v32
	v_mul_f32_e64 v55, |v53|, s85
	v_fmac_f32_e32 v52, v17, v37
	v_exp_f32_e32 v55, v55
	v_fmac_f32_e32 v52, v18, v38
	v_min_f32_e32 v56, 0, v53
	v_fmac_f32_e32 v52, v19, v39
	v_add_f32_e32 v55, 1.0, v55
	v_fmac_f32_e32 v52, v20, v40
	v_log_f32_e32 v55, v55
	v_fmac_f32_e32 v52, v21, v41
	v_fmac_f32_e32 v52, v22, v42
	v_mul_f32_e32 v57, 0x3f317217, v55
	v_fmac_f32_e32 v52, v23, v43
	v_fma_f32 v58, v55, s74, -v57
	v_fmac_f32_e32 v52, v24, v44
	v_fmac_f32_e32 v58, 0x3377d1cf, v55
	v_fmac_f32_e32 v52, v25, v45
	v_fmac_f32_e32 v58, 0x3f317217, v55
	v_fmac_f32_e32 v52, v26, v46
	v_sub_f32_e32 v56, v56, v58
	v_fmac_f32_e32 v52, v27, v47
	v_mul_f32_e32 v89, 0x3d800000, v56
	v_fmac_f32_e32 v52, v28, v48
	v_add_f32_e32 v54, v54, v89
	v_fmac_f32_e32 v52, v29, v49
	v_fmac_f32_e32 v52, v30, v50
	v_fmac_f32_e32 v52, v31, v51
	ds_read_b128 v[36:39], v2 offset:1792
	ds_read_b128 v[40:43], v2 offset:1808
	ds_read_b128 v[44:47], v2 offset:1824
	ds_read_b128 v[48:51], v2 offset:1840
	s_waitcnt lgkmcnt(4)
	v_fma_f32 v53, v16, v176, v32
	v_mul_f32_e64 v55, |v52|, s85
	v_fmac_f32_e32 v53, v17, v177
	v_exp_f32_e32 v55, v55
	v_fmac_f32_e32 v53, v18, v178
	v_min_f32_e32 v56, 0, v52
	v_fmac_f32_e32 v53, v19, v179
	v_add_f32_e32 v55, 1.0, v55
	v_fmac_f32_e32 v53, v20, v180
	v_log_f32_e32 v55, v55
	v_fmac_f32_e32 v53, v21, v181
	v_fmac_f32_e32 v53, v22, v182
	v_mul_f32_e32 v57, 0x3f317217, v55
	v_fmac_f32_e32 v53, v23, v183
	v_fma_f32 v58, v55, s74, -v57
	v_fmac_f32_e32 v53, v24, v184
	v_fmac_f32_e32 v58, 0x3377d1cf, v55
	v_fmac_f32_e32 v53, v25, v185
	v_fmac_f32_e32 v58, 0x3f317217, v55
	v_fmac_f32_e32 v53, v26, v186
	v_sub_f32_e32 v56, v56, v58
	v_fmac_f32_e32 v53, v27, v187
	v_mul_f32_e32 v90, 0x3d800000, v56
	v_fmac_f32_e32 v53, v28, v188
	v_add_f32_e32 v54, v54, v90
	v_fmac_f32_e32 v53, v29, v189
	v_fmac_f32_e32 v53, v30, v190
	v_fmac_f32_e32 v53, v31, v191
	ds_read_b128 v[176:179], v2 offset:1856
	ds_read_b128 v[180:183], v2 offset:1872
	ds_read_b128 v[184:187], v2 offset:1888
	ds_read_b128 v[188:191], v2 offset:1904
	s_waitcnt lgkmcnt(4)
; DI float logsig16(float z) { return (fminf(z, 0.f) - __logf(1.f + __expf(-fabsf(z)))) * (1.f / 16.f); }
; DI void phase_gla_prep(const Params& p, int g, char* smem, int bid, int nb) {
;     ...
;     for (int tt = 0; tt < 32; ++tt) {
;       const float* l = lrs + (half * 32 + tt) * 16; float z = bg;
; #pragma unroll
;       for (int r = 0; r < 16; ++r) z += l[r] * wg[r];
;       tsum += logsig16(z);
;     }
;     tot[half * 128 + d] = tsum;
;     __syncthreads();
	v_fma_f32 v52, v16, v36, v32
	v_mul_f32_e64 v55, |v53|, s85
	v_fmac_f32_e32 v52, v17, v37
	v_exp_f32_e32 v55, v55
	v_fmac_f32_e32 v52, v18, v38
	v_min_f32_e32 v56, 0, v53
	v_fmac_f32_e32 v52, v19, v39
	v_add_f32_e32 v55, 1.0, v55
	v_fmac_f32_e32 v52, v20, v40
	v_log_f32_e32 v55, v55
	v_fmac_f32_e32 v52, v21, v41
	v_fmac_f32_e32 v52, v22, v42
	v_mul_f32_e32 v57, 0x3f317217, v55
	v_fmac_f32_e32 v52, v23, v43
	v_fma_f32 v58, v55, s74, -v57
	v_fmac_f32_e32 v52, v24, v44
	v_fmac_f32_e32 v58, 0x3377d1cf, v55
	v_fmac_f32_e32 v52, v25, v45
	v_fmac_f32_e32 v58, 0x3f317217, v55
	v_fmac_f32_e32 v52, v26, v46
	v_sub_f32_e32 v56, v56, v58
	v_fmac_f32_e32 v52, v27, v47
	v_mul_f32_e32 v91, 0x3d800000, v56
	v_fmac_f32_e32 v52, v28, v48
	v_add_f32_e32 v54, v54, v91
	v_fmac_f32_e32 v52, v29, v49
	v_fmac_f32_e32 v52, v30, v50
	v_fmac_f32_e32 v52, v31, v51
	ds_read_b128 v[36:39], v2 offset:1920
	ds_read_b128 v[40:43], v2 offset:1936
	ds_read_b128 v[44:47], v2 offset:1952
	ds_read_b128 v[48:51], v2 offset:1968
	s_waitcnt lgkmcnt(4)
	v_fma_f32 v53, v16, v176, v32
	v_mul_f32_e64 v55, |v52|, s85
	v_fmac_f32_e32 v53, v17, v177
	v_exp_f32_e32 v55, v55
	v_fmac_f32_e32 v53, v18, v178
	v_min_f32_e32 v56, 0, v52
	v_fmac_f32_e32 v53, v19, v179
	v_add_f32_e32 v55, 1.0, v55
	v_fmac_f32_e32 v53, v20, v180
	v_log_f32_e32 v55, v55
	v_fmac_f32_e32 v53, v21, v181
	v_fmac_f32_e32 v53, v22, v182
	v_mul_f32_e32 v57, 0x3f317217, v55
	v_fmac_f32_e32 v53, v23, v183
	v_fma_f32 v58, v55, s74, -v57
	v_fmac_f32_e32 v53, v24, v184
	v_fmac_f32_e32 v58, 0x3377d1cf, v55
	v_fmac_f32_e32 v53, v25, v185
	v_fmac_f32_e32 v58, 0x3f317217, v55
	v_fmac_f32_e32 v53, v26, v186
	v_sub_f32_e32 v56, v56, v58
	v_fmac_f32_e32 v53, v27, v187
	v_mul_f32_e32 v92, 0x3d800000, v56
	v_fmac_f32_e32 v53, v28, v188
	v_add_f32_e32 v54, v54, v92
	v_fmac_f32_e32 v53, v29, v189
	v_fmac_f32_e32 v53, v30, v190
	v_fmac_f32_e32 v53, v31, v191
	ds_read_b128 v[176:179], v2 offset:1984
	ds_read_b128 v[180:183], v2 offset:2000
	ds_read_b128 v[184:187], v2 offset:2016
	ds_read_b128 v[188:191], v2 offset:2032
	s_waitcnt lgkmcnt(4)
	v_fma_f32 v52, v16, v36, v32
	v_mul_f32_e64 v55, |v53|, s85
	v_fmac_f32_e32 v52, v17, v37
	v_exp_f32_e32 v55, v55
	v_fmac_f32_e32 v52, v18, v38
	v_min_f32_e32 v56, 0, v53
	v_fmac_f32_e32 v52, v19, v39
	v_add_f32_e32 v55, 1.0, v55
	v_fmac_f32_e32 v52, v20, v40
	v_log_f32_e32 v55, v55
	v_fmac_f32_e32 v52, v21, v41
	v_fmac_f32_e32 v52, v22, v42
	v_mul_f32_e32 v57, 0x3f317217, v55
	v_fmac_f32_e32 v52, v23, v43
	v_fma_f32 v58, v55, s74, -v57
	v_fmac_f32_e32 v52, v24, v44
	v_fmac_f32_e32 v58, 0x3377d1cf, v55
	v_fmac_f32_e32 v52, v25, v45
	v_fmac_f32_e32 v58, 0x3f317217, v55
	v_fmac_f32_e32 v52, v26, v46
	v_sub_f32_e32 v56, v56, v58
	v_fmac_f32_e32 v52, v27, v47
	v_mul_f32_e32 v93, 0x3d800000, v56
	v_fmac_f32_e32 v52, v28, v48
	v_add_f32_e32 v54, v54, v93
	v_fmac_f32_e32 v52, v29, v49
	v_fmac_f32_e32 v52, v30, v50
	v_fmac_f32_e32 v52, v31, v51
	s_waitcnt lgkmcnt(0)
	v_fma_f32 v53, v16, v176, v32
	v_mul_f32_e64 v55, |v52|, s85
	v_fmac_f32_e32 v53, v17, v177
	v_exp_f32_e32 v55, v55
	v_fmac_f32_e32 v53, v18, v178
	v_min_f32_e32 v56, 0, v52
	v_fmac_f32_e32 v53, v19, v179
	v_add_f32_e32 v55, 1.0, v55
	v_fmac_f32_e32 v53, v20, v180
	v_log_f32_e32 v55, v55
	v_fmac_f32_e32 v53, v21, v181
	v_fmac_f32_e32 v53, v22, v182
	v_mul_f32_e32 v57, 0x3f317217, v55
	v_fmac_f32_e32 v53, v23, v183
	v_fma_f32 v58, v55, s74, -v57
	v_fmac_f32_e32 v53, v24, v184
	v_fmac_f32_e32 v58, 0x3377d1cf, v55
	v_fmac_f32_e32 v53, v25, v185
	v_fmac_f32_e32 v58, 0x3f317217, v55
	v_fmac_f32_e32 v53, v26, v186
	v_sub_f32_e32 v56, v56, v58
	v_fmac_f32_e32 v53, v27, v187
	v_mul_f32_e32 v94, 0x3d800000, v56
	v_fmac_f32_e32 v53, v28, v188
	v_add_f32_e32 v54, v54, v94
	v_fmac_f32_e32 v53, v29, v189
	v_fmac_f32_e32 v53, v30, v190
	v_fmac_f32_e32 v53, v31, v191
	v_mul_f32_e64 v55, |v53|, s85
	v_exp_f32_e32 v55, v55
	v_min_f32_e32 v56, 0, v53
	v_add_f32_e32 v55, 1.0, v55
	v_log_f32_e32 v55, v55
	s_nop 0
	v_mul_f32_e32 v57, 0x3f317217, v55
	v_fma_f32 v58, v55, s74, -v57
	v_fmac_f32_e32 v58, 0x3377d1cf, v55
	v_fmac_f32_e32 v58, 0x3f317217, v55
	v_sub_f32_e32 v56, v56, v58
	v_mul_f32_e32 v95, 0x3d800000, v56
	v_add_f32_e32 v54, v54, v95
	ds_write_b32 v1, v54 offset:4096
	s_waitcnt lgkmcnt(0)
	s_barrier
; DI float bf2f(bf16_t v) { return __uint_as_float(((unsigned)v) << 16); }
; DI bf16_t f2bf(float x) { return (bf16_t)(pk_bf16(x, 0.f) & 0xffffu); }
; DI float logsig16(float z) { return (fminf(z, 0.f) - __logf(1.f + __expf(-fabsf(z)))) * (1.f / 16.f); }
; DI void phase_gla_prep(const Params& p, int g, char* smem, int bid, int nb) {
;     ...
;     const float t0 = tot[d], t1 = tot[128 + d], TOTAL = t0 + t1;
;     float run = half ? t0 : 0.f;
;     const size_t blk = (size_t)((dir * 4 + head) * 256 + c);
;     unsigned ktp[16];
; #pragma unroll
;     for (int tt = 0; tt < 32; ++tt) {
;       const int t = half * 32 + tt;
;       const float* l = lrs + t * 16; float z = bg;
; #pragma unroll
;       for (int r = 0; r < 16; ++r) z += l[r] * wg[r];
;       const float gv = logsig16(z);
;       const float b = dir ? (TOTAL - run) : (run + gv);
;       run += gv;
;       const size_t tg = (size_t)c * 64 + t;
;       const float qv = bf2f(proj[tg * NPROJ + PQG + dd]), kv = bf2f(proj[tg * NPROJ + PKG + dd]);
;       const float qt = qv * __expf(b) * 0.08838834764831845f, kt = kv * __expf(-b);
;       gq[(blk * 64 + t) * 128 + d] = f2bf(qt);
;       const bf16_t kb = f2bf(kt);
;       gk[(blk * 64 + t) * 128 + d] = kb;
;       if (tt & 1) ktp[tt >> 1] |= ((unsigned)kb) << 16; else ktp[tt >> 1] = kb;
	ds_read_b32 v59, v3 offset:4096
	ds_read_b32 v60, v3 offset:4608
	s_cmp_lg_u32 s8, 0
	s_cselect_b64 s[0:1], -1, 0
	s_waitcnt lgkmcnt(0)
	v_add_f32_e32 v61, v59, v60
	v_cndmask_b32_e64 v62, 0, v59, s[0:1]
	s_waitcnt vmcnt(0)
	v_add_f32_e32 v63, v62, v64
	v_sub_f32_e32 v34, v61, v62
	v_add_f32_e32 v33, v63, v65
	v_sub_f32_e32 v35, v61, v63
	v_cndmask_b32_e64 v34, v34, v63, s[6:7]
	v_cndmask_b32_e64 v35, v35, v33, s[6:7]
	v_mul_f32_e32 v176, 0x3fb8aa3b, v34
	v_mul_f32_e32 v177, 0xbfb8aa3b, v34
	v_mul_f32_e32 v178, 0x3fb8aa3b, v35
	v_mul_f32_e32 v179, 0xbfb8aa3b, v35
	v_exp_f32_e32 v176, v176
	v_exp_f32_e32 v177, v177
	v_exp_f32_e32 v178, v178
	v_exp_f32_e32 v179, v179
	v_lshlrev_b32_e32 v180, 16, v96
	v_lshlrev_b32_e32 v181, 16, v144
	v_lshlrev_b32_e32 v182, 16, v97
	v_lshlrev_b32_e32 v183, 16, v145
	v_mul_f32_e32 v176, v176, v180
	v_mul_f32_e32 v177, v177, v181
	v_mul_f32_e32 v178, v178, v182
	v_mul_f32_e32 v179, v179, v183
	v_mul_f32_e32 v176, 0x3db504f3, v176
	v_mul_f32_e32 v178, 0x3db504f3, v178
	v_cvt_pk_bf16_f32 v180, v176, v178
	v_cvt_pk_bf16_f32 v128, v177, v179
	v_lshrrev_b32_e32 v182, 16, v180
	v_lshrrev_b32_e32 v183, 16, v128
	global_store_short v5, v180, s[24:25]
	global_store_short v5, v128, s[26:27]
	global_store_short v5, v182, s[24:25] offset:256
	global_store_short v5, v183, s[26:27] offset:256
	v_add_f32_e32 v63, v33, v66
	v_sub_f32_e32 v37, v61, v33
	v_add_f32_e32 v36, v63, v67
	v_sub_f32_e32 v38, v61, v63
	v_cndmask_b32_e64 v37, v37, v63, s[6:7]
	v_cndmask_b32_e64 v38, v38, v36, s[6:7]
	v_mul_f32_e32 v184, 0x3fb8aa3b, v37
	v_mul_f32_e32 v185, 0xbfb8aa3b, v37
	v_mul_f32_e32 v186, 0x3fb8aa3b, v38
	v_mul_f32_e32 v187, 0xbfb8aa3b, v38
	v_exp_f32_e32 v184, v184
	v_exp_f32_e32 v185, v185
	v_exp_f32_e32 v186, v186
	v_exp_f32_e32 v187, v187
	v_lshlrev_b32_e32 v188, 16, v98
	v_lshlrev_b32_e32 v189, 16, v146
	v_lshlrev_b32_e32 v190, 16, v99
	v_lshlrev_b32_e32 v191, 16, v147
	v_mul_f32_e32 v184, v184, v188
	v_mul_f32_e32 v185, v185, v189
	v_mul_f32_e32 v186, v186, v190
	v_mul_f32_e32 v187, v187, v191
	v_mul_f32_e32 v184, 0x3db504f3, v184
	v_mul_f32_e32 v186, 0x3db504f3, v186
	v_cvt_pk_bf16_f32 v188, v184, v186
	v_cvt_pk_bf16_f32 v129, v185, v187
	v_lshrrev_b32_e32 v190, 16, v188
	v_lshrrev_b32_e32 v191, 16, v129
	global_store_short v5, v188, s[24:25] offset:512
	global_store_short v5, v129, s[26:27] offset:512
	global_store_short v5, v190, s[24:25] offset:768
	global_store_short v5, v191, s[26:27] offset:768
	v_add_f32_e32 v63, v36, v68
	v_sub_f32_e32 v40, v61, v36
	v_add_f32_e32 v39, v63, v69
	v_sub_f32_e32 v41, v61, v63
	v_cndmask_b32_e64 v40, v40, v63, s[6:7]
	v_cndmask_b32_e64 v41, v41, v39, s[6:7]
	v_mul_f32_e32 v42, 0x3fb8aa3b, v40
	v_mul_f32_e32 v43, 0xbfb8aa3b, v40
	v_mul_f32_e32 v44, 0x3fb8aa3b, v41
	v_mul_f32_e32 v45, 0xbfb8aa3b, v41
	v_exp_f32_e32 v42, v42
	v_exp_f32_e32 v43, v43
	v_exp_f32_e32 v44, v44
	v_exp_f32_e32 v45, v45
	v_lshlrev_b32_e32 v46, 16, v100
	v_lshlrev_b32_e32 v47, 16, v148
	v_lshlrev_b32_e32 v48, 16, v101
	v_lshlrev_b32_e32 v49, 16, v149
	v_mul_f32_e32 v42, v42, v46
	v_mul_f32_e32 v43, v43, v47
	v_mul_f32_e32 v44, v44, v48
	v_mul_f32_e32 v45, v45, v49
	v_mul_f32_e32 v42, 0x3db504f3, v42
	v_mul_f32_e32 v44, 0x3db504f3, v44
	v_cvt_pk_bf16_f32 v46, v42, v44
	v_cvt_pk_bf16_f32 v130, v43, v45
	v_lshrrev_b32_e32 v48, 16, v46
	v_lshrrev_b32_e32 v49, 16, v130
	global_store_short v5, v46, s[24:25] offset:1024
	global_store_short v5, v130, s[26:27] offset:1024
	global_store_short v5, v48, s[24:25] offset:1280
	global_store_short v5, v49, s[26:27] offset:1280
	v_add_f32_e32 v63, v39, v70
	v_sub_f32_e32 v51, v61, v39
	v_add_f32_e32 v50, v63, v71
	v_sub_f32_e32 v52, v61, v63
	v_cndmask_b32_e64 v51, v51, v63, s[6:7]
	v_cndmask_b32_e64 v52, v52, v50, s[6:7]
	v_mul_f32_e32 v53, 0x3fb8aa3b, v51
	v_mul_f32_e32 v54, 0xbfb8aa3b, v51
	v_mul_f32_e32 v55, 0x3fb8aa3b, v52
	v_mul_f32_e32 v56, 0xbfb8aa3b, v52
	v_exp_f32_e32 v53, v53
	v_exp_f32_e32 v54, v54
	v_exp_f32_e32 v55, v55
	v_exp_f32_e32 v56, v56
	v_lshlrev_b32_e32 v57, 16, v102
	v_lshlrev_b32_e32 v58, 16, v150
	v_lshlrev_b32_e32 v59, 16, v103
	v_lshlrev_b32_e32 v60, 16, v151
	v_mul_f32_e32 v53, v53, v57
	v_mul_f32_e32 v54, v54, v58
	v_mul_f32_e32 v55, v55, v59
	v_mul_f32_e32 v56, v56, v60
	v_mul_f32_e32 v53, 0x3db504f3, v53
	v_mul_f32_e32 v55, 0x3db504f3, v55
	v_cvt_pk_bf16_f32 v57, v53, v55
	v_cvt_pk_bf16_f32 v131, v54, v56
	v_lshrrev_b32_e32 v59, 16, v57
	v_lshrrev_b32_e32 v60, 16, v131
	global_store_short v5, v57, s[24:25] offset:1536
	global_store_short v5, v131, s[26:27] offset:1536
	global_store_short v5, v59, s[24:25] offset:1792
	global_store_short v5, v60, s[26:27] offset:1792
	v_add_f32_e32 v63, v50, v72
	v_sub_f32_e32 v34, v61, v50
	v_add_f32_e32 v33, v63, v73
	v_sub_f32_e32 v35, v61, v63
	v_cndmask_b32_e64 v34, v34, v63, s[6:7]
	v_cndmask_b32_e64 v35, v35, v33, s[6:7]
	v_mul_f32_e32 v176, 0x3fb8aa3b, v34
	v_mul_f32_e32 v177, 0xbfb8aa3b, v34
	v_mul_f32_e32 v178, 0x3fb8aa3b, v35
	v_mul_f32_e32 v179, 0xbfb8aa3b, v35
	v_exp_f32_e32 v176, v176
	v_exp_f32_e32 v177, v177
	v_exp_f32_e32 v178, v178
	v_exp_f32_e32 v179, v179
	v_lshlrev_b32_e32 v180, 16, v104
	v_lshlrev_b32_e32 v181, 16, v152
	v_lshlrev_b32_e32 v182, 16, v105
	v_lshlrev_b32_e32 v183, 16, v153
	v_mul_f32_e32 v176, v176, v180
	v_mul_f32_e32 v177, v177, v181
	v_mul_f32_e32 v178, v178, v182
	v_mul_f32_e32 v179, v179, v183
	v_mul_f32_e32 v176, 0x3db504f3, v176
	v_mul_f32_e32 v178, 0x3db504f3, v178
	v_cvt_pk_bf16_f32 v180, v176, v178
	v_cvt_pk_bf16_f32 v132, v177, v179
	v_lshrrev_b32_e32 v182, 16, v180
	v_lshrrev_b32_e32 v183, 16, v132
	global_store_short v5, v180, s[24:25] offset:2048
; DI float bf2f(bf16_t v) { return __uint_as_float(((unsigned)v) << 16); }
; DI bf16_t f2bf(float x) { return (bf16_t)(pk_bf16(x, 0.f) & 0xffffu); }
; DI float logsig16(float z) { return (fminf(z, 0.f) - __logf(1.f + __expf(-fabsf(z)))) * (1.f / 16.f); }
; DI void phase_gla_prep(const Params& p, int g, char* smem, int bid, int nb) {
;     ...
;     for (int tt = 0; tt < 32; ++tt) {
;       const int t = half * 32 + tt;
;       const float* l = lrs + t * 16; float z = bg;
; #pragma unroll
;       for (int r = 0; r < 16; ++r) z += l[r] * wg[r];
;       const float gv = logsig16(z);
;       const float b = dir ? (TOTAL - run) : (run + gv);
;       run += gv;
;       const size_t tg = (size_t)c * 64 + t;
;       const float qv = bf2f(proj[tg * NPROJ + PQG + dd]), kv = bf2f(proj[tg * NPROJ + PKG + dd]);
;       const float qt = qv * __expf(b) * 0.08838834764831845f, kt = kv * __expf(-b);
;       gq[(blk * 64 + t) * 128 + d] = f2bf(qt);
;       const bf16_t kb = f2bf(kt);
;       gk[(blk * 64 + t) * 128 + d] = kb;
;       if (tt & 1) ktp[tt >> 1] |= ((unsigned)kb) << 16; else ktp[tt >> 1] = kb;
	global_store_short v5, v132, s[26:27] offset:2048
	global_store_short v5, v182, s[24:25] offset:2304
	global_store_short v5, v183, s[26:27] offset:2304
	v_add_f32_e32 v63, v33, v74
	v_sub_f32_e32 v37, v61, v33
	v_add_f32_e32 v36, v63, v75
	v_sub_f32_e32 v38, v61, v63
	v_cndmask_b32_e64 v37, v37, v63, s[6:7]
	v_cndmask_b32_e64 v38, v38, v36, s[6:7]
	v_mul_f32_e32 v184, 0x3fb8aa3b, v37
	v_mul_f32_e32 v185, 0xbfb8aa3b, v37
	v_mul_f32_e32 v186, 0x3fb8aa3b, v38
	v_mul_f32_e32 v187, 0xbfb8aa3b, v38
	v_exp_f32_e32 v184, v184
	v_exp_f32_e32 v185, v185
	v_exp_f32_e32 v186, v186
	v_exp_f32_e32 v187, v187
	v_lshlrev_b32_e32 v188, 16, v106
	v_lshlrev_b32_e32 v189, 16, v154
	v_lshlrev_b32_e32 v190, 16, v107
	v_lshlrev_b32_e32 v191, 16, v155
	v_mul_f32_e32 v184, v184, v188
	v_mul_f32_e32 v185, v185, v189
	v_mul_f32_e32 v186, v186, v190
	v_mul_f32_e32 v187, v187, v191
	v_mul_f32_e32 v184, 0x3db504f3, v184
	v_mul_f32_e32 v186, 0x3db504f3, v186
	v_cvt_pk_bf16_f32 v188, v184, v186
	v_cvt_pk_bf16_f32 v133, v185, v187
	v_lshrrev_b32_e32 v190, 16, v188
	v_lshrrev_b32_e32 v191, 16, v133
	global_store_short v5, v188, s[24:25] offset:2560
	global_store_short v5, v133, s[26:27] offset:2560
	global_store_short v5, v190, s[24:25] offset:2816
	global_store_short v5, v191, s[26:27] offset:2816
	v_add_f32_e32 v63, v36, v76
	v_sub_f32_e32 v40, v61, v36
	v_add_f32_e32 v39, v63, v77
	v_sub_f32_e32 v41, v61, v63
	v_cndmask_b32_e64 v40, v40, v63, s[6:7]
	v_cndmask_b32_e64 v41, v41, v39, s[6:7]
	v_mul_f32_e32 v42, 0x3fb8aa3b, v40
	v_mul_f32_e32 v43, 0xbfb8aa3b, v40
	v_mul_f32_e32 v44, 0x3fb8aa3b, v41
	v_mul_f32_e32 v45, 0xbfb8aa3b, v41
	v_exp_f32_e32 v42, v42
	v_exp_f32_e32 v43, v43
	v_exp_f32_e32 v44, v44
	v_exp_f32_e32 v45, v45
	v_lshlrev_b32_e32 v46, 16, v108
	v_lshlrev_b32_e32 v47, 16, v156
	v_lshlrev_b32_e32 v48, 16, v109
	v_lshlrev_b32_e32 v49, 16, v157
	v_mul_f32_e32 v42, v42, v46
	v_mul_f32_e32 v43, v43, v47
	v_mul_f32_e32 v44, v44, v48
	v_mul_f32_e32 v45, v45, v49
	v_mul_f32_e32 v42, 0x3db504f3, v42
	v_mul_f32_e32 v44, 0x3db504f3, v44
	v_cvt_pk_bf16_f32 v46, v42, v44
	v_cvt_pk_bf16_f32 v134, v43, v45
	v_lshrrev_b32_e32 v48, 16, v46
	v_lshrrev_b32_e32 v49, 16, v134
	global_store_short v5, v46, s[24:25] offset:3072
	global_store_short v5, v134, s[26:27] offset:3072
	global_store_short v5, v48, s[24:25] offset:3328
	global_store_short v5, v49, s[26:27] offset:3328
	v_add_f32_e32 v63, v39, v78
	v_sub_f32_e32 v51, v61, v39
	v_add_f32_e32 v50, v63, v79
	v_sub_f32_e32 v52, v61, v63
	v_cndmask_b32_e64 v51, v51, v63, s[6:7]
	v_cndmask_b32_e64 v52, v52, v50, s[6:7]
	v_mul_f32_e32 v53, 0x3fb8aa3b, v51
	v_mul_f32_e32 v54, 0xbfb8aa3b, v51
	v_mul_f32_e32 v55, 0x3fb8aa3b, v52
	v_mul_f32_e32 v56, 0xbfb8aa3b, v52
	v_exp_f32_e32 v53, v53
	v_exp_f32_e32 v54, v54
	v_exp_f32_e32 v55, v55
	v_exp_f32_e32 v56, v56
	v_lshlrev_b32_e32 v57, 16, v110
	v_lshlrev_b32_e32 v58, 16, v158
	v_lshlrev_b32_e32 v59, 16, v111
	v_lshlrev_b32_e32 v60, 16, v159
	v_mul_f32_e32 v53, v53, v57
	v_mul_f32_e32 v54, v54, v58
	v_mul_f32_e32 v55, v55, v59
	v_mul_f32_e32 v56, v56, v60
	v_mul_f32_e32 v53, 0x3db504f3, v53
	v_mul_f32_e32 v55, 0x3db504f3, v55
	v_cvt_pk_bf16_f32 v57, v53, v55
	v_cvt_pk_bf16_f32 v135, v54, v56
	v_lshrrev_b32_e32 v59, 16, v57
	v_lshrrev_b32_e32 v60, 16, v135
	global_store_short v5, v57, s[24:25] offset:3584
	global_store_short v5, v135, s[26:27] offset:3584
	global_store_short v5, v59, s[24:25] offset:3840
	global_store_short v5, v60, s[26:27] offset:3840
	v_add_f32_e32 v63, v50, v80
	v_sub_f32_e32 v34, v61, v50
	v_add_f32_e32 v33, v63, v81
	v_sub_f32_e32 v35, v61, v63
	v_cndmask_b32_e64 v34, v34, v63, s[6:7]
	v_cndmask_b32_e64 v35, v35, v33, s[6:7]
	v_mul_f32_e32 v176, 0x3fb8aa3b, v34
	v_mul_f32_e32 v177, 0xbfb8aa3b, v34
	v_mul_f32_e32 v178, 0x3fb8aa3b, v35
	v_mul_f32_e32 v179, 0xbfb8aa3b, v35
	v_exp_f32_e32 v176, v176
	v_exp_f32_e32 v177, v177
	v_exp_f32_e32 v178, v178
	v_exp_f32_e32 v179, v179
	v_lshlrev_b32_e32 v180, 16, v112
	v_lshlrev_b32_e32 v181, 16, v160
	v_lshlrev_b32_e32 v182, 16, v113
	v_lshlrev_b32_e32 v183, 16, v161
	v_mul_f32_e32 v176, v176, v180
	v_mul_f32_e32 v177, v177, v181
	v_mul_f32_e32 v178, v178, v182
	v_mul_f32_e32 v179, v179, v183
	v_mul_f32_e32 v176, 0x3db504f3, v176
	v_mul_f32_e32 v178, 0x3db504f3, v178
	v_cvt_pk_bf16_f32 v180, v176, v178
	v_cvt_pk_bf16_f32 v136, v177, v179
	v_lshrrev_b32_e32 v182, 16, v180
	v_lshrrev_b32_e32 v183, 16, v136
	global_store_short v6, v180, s[24:25]
	global_store_short v6, v136, s[26:27]
	global_store_short v6, v182, s[24:25] offset:256
	global_store_short v6, v183, s[26:27] offset:256
	v_add_f32_e32 v63, v33, v82
	v_sub_f32_e32 v37, v61, v33
	v_add_f32_e32 v36, v63, v83
	v_sub_f32_e32 v38, v61, v63
	v_cndmask_b32_e64 v37, v37, v63, s[6:7]
	v_cndmask_b32_e64 v38, v38, v36, s[6:7]
	v_mul_f32_e32 v184, 0x3fb8aa3b, v37
	v_mul_f32_e32 v185, 0xbfb8aa3b, v37
	v_mul_f32_e32 v186, 0x3fb8aa3b, v38
	v_mul_f32_e32 v187, 0xbfb8aa3b, v38
	v_exp_f32_e32 v184, v184
	v_exp_f32_e32 v185, v185
	v_exp_f32_e32 v186, v186
	v_exp_f32_e32 v187, v187
	v_lshlrev_b32_e32 v188, 16, v114
	v_lshlrev_b32_e32 v189, 16, v162
	v_lshlrev_b32_e32 v190, 16, v115
	v_lshlrev_b32_e32 v191, 16, v163
	v_mul_f32_e32 v184, v184, v188
	v_mul_f32_e32 v185, v185, v189
	v_mul_f32_e32 v186, v186, v190
	v_mul_f32_e32 v187, v187, v191
	v_mul_f32_e32 v184, 0x3db504f3, v184
	v_mul_f32_e32 v186, 0x3db504f3, v186
	v_cvt_pk_bf16_f32 v188, v184, v186
	v_cvt_pk_bf16_f32 v137, v185, v187
	v_lshrrev_b32_e32 v190, 16, v188
	v_lshrrev_b32_e32 v191, 16, v137
	global_store_short v6, v188, s[24:25] offset:512
	global_store_short v6, v137, s[26:27] offset:512
	global_store_short v6, v190, s[24:25] offset:768
; DI float bf2f(bf16_t v) { return __uint_as_float(((unsigned)v) << 16); }
; DI bf16_t f2bf(float x) { return (bf16_t)(pk_bf16(x, 0.f) & 0xffffu); }
; DI void phase_gla_prep(const Params& p, int g, char* smem, int bid, int nb) {
;     ...
;       const float b = dir ? (TOTAL - run) : (run + gv);
;       run += gv;
;       const size_t tg = (size_t)c * 64 + t;
;       const float qv = bf2f(proj[tg * NPROJ + PQG + dd]), kv = bf2f(proj[tg * NPROJ + PKG + dd]);
;       const float qt = qv * __expf(b) * 0.08838834764831845f, kt = kv * __expf(-b);
;       gq[(blk * 64 + t) * 128 + d] = f2bf(qt);
;       const bf16_t kb = f2bf(kt);
;       gk[(blk * 64 + t) * 128 + d] = kb;
;       if (tt & 1) ktp[tt >> 1] |= ((unsigned)kb) << 16; else ktp[tt >> 1] = kb;
;     }
;     bf16_t* kd = gkt + (blk * 128 + d) * 64 + half * 32;
; #pragma unroll
;     for (int q = 0; q < 4; ++q) { u32x4 v = {ktp[4 * q], ktp[4 * q + 1], ktp[4 * q + 2], ktp[4 * q + 3]}; *(u32x4*)(kd + 8 * q) = v; }
	global_store_short v6, v191, s[26:27] offset:768
	v_add_f32_e32 v63, v36, v84
	v_sub_f32_e32 v40, v61, v36
	v_add_f32_e32 v39, v63, v85
	v_sub_f32_e32 v41, v61, v63
	v_cndmask_b32_e64 v40, v40, v63, s[6:7]
	v_cndmask_b32_e64 v41, v41, v39, s[6:7]
	v_mul_f32_e32 v42, 0x3fb8aa3b, v40
	v_mul_f32_e32 v43, 0xbfb8aa3b, v40
	v_mul_f32_e32 v44, 0x3fb8aa3b, v41
	v_mul_f32_e32 v45, 0xbfb8aa3b, v41
	v_exp_f32_e32 v42, v42
	v_exp_f32_e32 v43, v43
	v_exp_f32_e32 v44, v44
	v_exp_f32_e32 v45, v45
	v_lshlrev_b32_e32 v46, 16, v116
	v_lshlrev_b32_e32 v47, 16, v164
	v_lshlrev_b32_e32 v48, 16, v117
	v_lshlrev_b32_e32 v49, 16, v165
	v_mul_f32_e32 v42, v42, v46
	v_mul_f32_e32 v43, v43, v47
	v_mul_f32_e32 v44, v44, v48
	v_mul_f32_e32 v45, v45, v49
	v_mul_f32_e32 v42, 0x3db504f3, v42
	v_mul_f32_e32 v44, 0x3db504f3, v44
	v_cvt_pk_bf16_f32 v46, v42, v44
	v_cvt_pk_bf16_f32 v138, v43, v45
	v_lshrrev_b32_e32 v48, 16, v46
	v_lshrrev_b32_e32 v49, 16, v138
	global_store_short v6, v46, s[24:25] offset:1024
	global_store_short v6, v138, s[26:27] offset:1024
	global_store_short v6, v48, s[24:25] offset:1280
	global_store_short v6, v49, s[26:27] offset:1280
	v_add_f32_e32 v63, v39, v86
	v_sub_f32_e32 v51, v61, v39
	v_add_f32_e32 v50, v63, v87
	v_sub_f32_e32 v52, v61, v63
	v_cndmask_b32_e64 v51, v51, v63, s[6:7]
	v_cndmask_b32_e64 v52, v52, v50, s[6:7]
	v_mul_f32_e32 v53, 0x3fb8aa3b, v51
	v_mul_f32_e32 v54, 0xbfb8aa3b, v51
	v_mul_f32_e32 v55, 0x3fb8aa3b, v52
	v_mul_f32_e32 v56, 0xbfb8aa3b, v52
	v_exp_f32_e32 v53, v53
	v_exp_f32_e32 v54, v54
	v_exp_f32_e32 v55, v55
	v_exp_f32_e32 v56, v56
	v_lshlrev_b32_e32 v57, 16, v118
	v_lshlrev_b32_e32 v58, 16, v166
	v_lshlrev_b32_e32 v59, 16, v119
	v_lshlrev_b32_e32 v60, 16, v167
	v_mul_f32_e32 v53, v53, v57
	v_mul_f32_e32 v54, v54, v58
	v_mul_f32_e32 v55, v55, v59
	v_mul_f32_e32 v56, v56, v60
	v_mul_f32_e32 v53, 0x3db504f3, v53
	v_mul_f32_e32 v55, 0x3db504f3, v55
	v_cvt_pk_bf16_f32 v57, v53, v55
	v_cvt_pk_bf16_f32 v139, v54, v56
	v_lshrrev_b32_e32 v59, 16, v57
	v_lshrrev_b32_e32 v60, 16, v139
	global_store_short v6, v57, s[24:25] offset:1536
	global_store_short v6, v139, s[26:27] offset:1536
	global_store_short v6, v59, s[24:25] offset:1792
	global_store_short v6, v60, s[26:27] offset:1792
	v_add_f32_e32 v63, v50, v88
	v_sub_f32_e32 v34, v61, v50
	v_add_f32_e32 v33, v63, v89
	v_sub_f32_e32 v35, v61, v63
	v_cndmask_b32_e64 v34, v34, v63, s[6:7]
	v_cndmask_b32_e64 v35, v35, v33, s[6:7]
	v_mul_f32_e32 v176, 0x3fb8aa3b, v34
	v_mul_f32_e32 v177, 0xbfb8aa3b, v34
	v_mul_f32_e32 v178, 0x3fb8aa3b, v35
	v_mul_f32_e32 v179, 0xbfb8aa3b, v35
	v_exp_f32_e32 v176, v176
	v_exp_f32_e32 v177, v177
	v_exp_f32_e32 v178, v178
	v_exp_f32_e32 v179, v179
	v_lshlrev_b32_e32 v180, 16, v120
	v_lshlrev_b32_e32 v181, 16, v168
	v_lshlrev_b32_e32 v182, 16, v121
	v_lshlrev_b32_e32 v183, 16, v169
	v_mul_f32_e32 v176, v176, v180
	v_mul_f32_e32 v177, v177, v181
	v_mul_f32_e32 v178, v178, v182
	v_mul_f32_e32 v179, v179, v183
	v_mul_f32_e32 v176, 0x3db504f3, v176
	v_mul_f32_e32 v178, 0x3db504f3, v178
	v_cvt_pk_bf16_f32 v180, v176, v178
	v_cvt_pk_bf16_f32 v140, v177, v179
	v_lshrrev_b32_e32 v182, 16, v180
	v_lshrrev_b32_e32 v183, 16, v140
	global_store_short v6, v180, s[24:25] offset:2048
	global_store_short v6, v140, s[26:27] offset:2048
	global_store_short v6, v182, s[24:25] offset:2304
	global_store_short v6, v183, s[26:27] offset:2304
	v_add_f32_e32 v63, v33, v90
	v_sub_f32_e32 v37, v61, v33
	v_add_f32_e32 v36, v63, v91
	v_sub_f32_e32 v38, v61, v63
	v_cndmask_b32_e64 v37, v37, v63, s[6:7]
	v_cndmask_b32_e64 v38, v38, v36, s[6:7]
	v_mul_f32_e32 v184, 0x3fb8aa3b, v37
	v_mul_f32_e32 v185, 0xbfb8aa3b, v37
	v_mul_f32_e32 v186, 0x3fb8aa3b, v38
	v_mul_f32_e32 v187, 0xbfb8aa3b, v38
	v_exp_f32_e32 v184, v184
	v_exp_f32_e32 v185, v185
	v_exp_f32_e32 v186, v186
	v_exp_f32_e32 v187, v187
	v_lshlrev_b32_e32 v188, 16, v122
	v_lshlrev_b32_e32 v189, 16, v170
	v_lshlrev_b32_e32 v190, 16, v123
	v_lshlrev_b32_e32 v191, 16, v171
	v_mul_f32_e32 v184, v184, v188
	v_mul_f32_e32 v185, v185, v189
	v_mul_f32_e32 v186, v186, v190
	v_mul_f32_e32 v187, v187, v191
	v_mul_f32_e32 v184, 0x3db504f3, v184
	v_mul_f32_e32 v186, 0x3db504f3, v186
	v_cvt_pk_bf16_f32 v188, v184, v186
	v_cvt_pk_bf16_f32 v141, v185, v187
	v_lshrrev_b32_e32 v190, 16, v188
	v_lshrrev_b32_e32 v191, 16, v141
	global_store_short v6, v188, s[24:25] offset:2560
	global_store_short v6, v141, s[26:27] offset:2560
	global_store_short v6, v190, s[24:25] offset:2816
	global_store_short v6, v191, s[26:27] offset:2816
	v_add_f32_e32 v63, v36, v92
	v_sub_f32_e32 v40, v61, v36
	v_add_f32_e32 v39, v63, v93
	v_sub_f32_e32 v41, v61, v63
	v_cndmask_b32_e64 v40, v40, v63, s[6:7]
	v_cndmask_b32_e64 v41, v41, v39, s[6:7]
	v_mul_f32_e32 v42, 0x3fb8aa3b, v40
	v_mul_f32_e32 v43, 0xbfb8aa3b, v40
	v_mul_f32_e32 v44, 0x3fb8aa3b, v41
	v_mul_f32_e32 v45, 0xbfb8aa3b, v41
	v_exp_f32_e32 v42, v42
	v_exp_f32_e32 v43, v43
	v_exp_f32_e32 v44, v44
	v_exp_f32_e32 v45, v45
	v_lshlrev_b32_e32 v46, 16, v124
	v_lshlrev_b32_e32 v47, 16, v172
	v_lshlrev_b32_e32 v48, 16, v125
	v_lshlrev_b32_e32 v49, 16, v173
	v_mul_f32_e32 v42, v42, v46
	v_mul_f32_e32 v43, v43, v47
	v_mul_f32_e32 v44, v44, v48
	v_mul_f32_e32 v45, v45, v49
	v_mul_f32_e32 v42, 0x3db504f3, v42
	v_mul_f32_e32 v44, 0x3db504f3, v44
	v_cvt_pk_bf16_f32 v46, v42, v44
	v_cvt_pk_bf16_f32 v142, v43, v45
	v_lshrrev_b32_e32 v48, 16, v46
	v_lshrrev_b32_e32 v49, 16, v142
	global_store_short v6, v46, s[24:25] offset:3072
	global_store_short v6, v142, s[26:27] offset:3072
	global_store_short v6, v48, s[24:25] offset:3328
	global_store_short v6, v49, s[26:27] offset:3328
	v_add_f32_e32 v63, v39, v94
	v_sub_f32_e32 v51, v61, v39
	v_add_f32_e32 v50, v63, v95
	v_sub_f32_e32 v52, v61, v63
	v_cndmask_b32_e64 v51, v51, v63, s[6:7]
	v_cndmask_b32_e64 v52, v52, v50, s[6:7]
	v_mul_f32_e32 v53, 0x3fb8aa3b, v51
	v_mul_f32_e32 v54, 0xbfb8aa3b, v51
	v_mul_f32_e32 v55, 0x3fb8aa3b, v52
	v_mul_f32_e32 v56, 0xbfb8aa3b, v52
	v_exp_f32_e32 v53, v53
	v_exp_f32_e32 v54, v54
	v_exp_f32_e32 v55, v55
	v_exp_f32_e32 v56, v56
	v_lshlrev_b32_e32 v57, 16, v126
	v_lshlrev_b32_e32 v58, 16, v174
	v_lshlrev_b32_e32 v59, 16, v127
	v_lshlrev_b32_e32 v60, 16, v175
	v_mul_f32_e32 v53, v53, v57
	v_mul_f32_e32 v54, v54, v58
	v_mul_f32_e32 v55, v55, v59
	v_mul_f32_e32 v56, v56, v60
	v_mul_f32_e32 v53, 0x3db504f3, v53
	v_mul_f32_e32 v55, 0x3db504f3, v55
	v_cvt_pk_bf16_f32 v57, v53, v55
	v_cvt_pk_bf16_f32 v143, v54, v56
	v_lshrrev_b32_e32 v59, 16, v57
	v_lshrrev_b32_e32 v60, 16, v143
	global_store_short v6, v57, s[24:25] offset:3584
	global_store_short v6, v143, s[26:27] offset:3584
	global_store_short v6, v59, s[24:25] offset:3840
	global_store_short v6, v60, s[26:27] offset:3840
	global_store_dwordx4 v10, v[128:131], s[28:29]
	global_store_dwordx4 v10, v[132:135], s[28:29] offset:16
	global_store_dwordx4 v10, v[136:139], s[28:29] offset:32
	global_store_dwordx4 v10, v[140:143], s[28:29] offset:48
	s_cmp_lg_u32 s8, 0
	s_cbranch_scc1 .Lgp_noge
; DI void phase_gla_prep(const Params& p, int g, char* smem, int bid, int nb) {
;     ...
;     bf16_t* kd = gkt + (blk * 128 + d) * 64 + half * 32;
; #pragma unroll
;     for (int q = 0; q < 4; ++q) { u32x4 v = {ktp[4 * q], ktp[4 * q + 1], ktp[4 * q + 2], ktp[4 * q + 3]}; *(u32x4*)(kd + 8 * q) = v; }
;     if (half == 0) ge[blk * 128 + d] = __expf(TOTAL);
;   }
	v_mul_f32_e32 v33, 0x3fb8aa3b, v61
	v_exp_f32_e32 v33, v33
	s_nop 0
	global_store_dword v9, v33, s[30:31]
.Lgp_noge:
	v_readlane_b32 s0, v235, 9
	s_nop 1
	s_add_i32 s12, s12, s0
	s_cmpk_lt_i32 s12, 0x800
	s_cbranch_scc1 .Lgp_loop
